# v72 (phase-5 epilogue 9 steps hoisted) + EpiRes1/2 epilogues (x-attn out-proj L0/L1, mLSTM... W2 L1): all residual loads issued up front
# speedup vs baseline: 1.0188x; 1.0024x over previous
.LBB0_404:
	ds_read_b128 v[128:131], v181
	ds_read_b128 v[132:135], v181 offset:1024
	ds_read_b128 v[136:139], v181 offset:2048
	ds_read_b128 v[140:143], v181 offset:3072
	s_add_u32 s30, s28, 0xfffc0080
	s_addc_u32 s31, s29, -1
	s_cmp_eq_u32 s66, 12
	s_cselect_b32 s35, s25, s31
	s_cselect_b32 s34, s24, s30
	s_cselect_b32 s31, s27, s65
	s_cselect_b32 s30, s26, s64
	v_lshl_add_u64 v[166:167], s[28:29], 0, v[152:153]
	s_add_i32 m0, s41, 0xc000
	ds_read_b128 v[158:161], v182
	ds_read_b128 v[162:165], v182 offset:1024
	ds_read_b128 v[184:187], v182 offset:2048
	ds_read_b128 v[188:191], v182 offset:3072
	ds_read_b128 v[192:195], v182 offset:4096
	ds_read_b128 v[196:199], v182 offset:5120
	ds_read_b128 v[200:203], v182 offset:6144
	ds_read_b128 v[204:207], v182 offset:7168
	global_load_lds_dwordx4 v[166:167], off
	v_lshl_add_u64 v[166:167], s[28:29], 0, v[154:155]
	s_add_i32 m0, s41, 0xe000
	s_nop 0
	global_load_lds_dwordx4 v[166:167], off
	s_waitcnt lgkmcnt(8)
	s_barrier
	s_waitcnt lgkmcnt(0)
	s_setprio 1
	s_waitcnt lgkmcnt(0)
	v_mfma_f32_16x16x32_bf16 v[124:127], v[128:131], v[158:161], v[124:127]
	v_mfma_f32_16x16x32_bf16 v[120:123], v[136:139], v[158:161], v[120:123]
	v_mfma_f32_16x16x32_bf16 v[116:119], v[128:131], v[184:187], v[116:119]
	v_mfma_f32_16x16x32_bf16 v[108:111], v[136:139], v[184:187], v[108:111]
	v_mfma_f32_16x16x32_bf16 v[92:95], v[128:131], v[192:195], v[92:95]
	v_mfma_f32_16x16x32_bf16 v[88:91], v[136:139], v[192:195], v[88:91]
	v_mfma_f32_16x16x32_bf16 v[76:79], v[128:131], v[200:203], v[76:79]
	v_mfma_f32_16x16x32_bf16 v[72:75], v[136:139], v[200:203], v[72:75]
	v_mfma_f32_16x16x32_bf16 v[124:127], v[132:135], v[162:165], v[124:127]
	v_mfma_f32_16x16x32_bf16 v[120:123], v[140:143], v[162:165], v[120:123]
	v_mfma_f32_16x16x32_bf16 v[116:119], v[132:135], v[188:191], v[116:119]
	v_mfma_f32_16x16x32_bf16 v[108:111], v[140:143], v[188:191], v[108:111]
	v_mfma_f32_16x16x32_bf16 v[92:95], v[132:135], v[196:199], v[92:95]
	v_mfma_f32_16x16x32_bf16 v[88:91], v[140:143], v[196:199], v[88:91]
	v_mfma_f32_16x16x32_bf16 v[76:79], v[132:135], v[204:207], v[76:79]
	v_mfma_f32_16x16x32_bf16 v[72:75], v[140:143], v[204:207], v[72:75]
	s_setprio 0
	s_barrier
	s_add_i32 s67, s56, s40
	v_lshl_add_u64 v[166:167], s[30:31], 0, v[146:147]
	s_mov_b32 m0, s67
	ds_read_b128 v[208:211], v183
	ds_read_b128 v[212:215], v183 offset:1024
	ds_read_b128 v[216:219], v183 offset:2048
	ds_read_b128 v[220:223], v183 offset:3072
	global_load_lds_dwordx4 v[166:167], off
	v_lshl_add_u64 v[224:225], s[30:31], 0, v[150:151]
	s_add_i32 m0, s67, 0x2000
	s_nop 0
	global_load_lds_dwordx4 v[224:225], off
	s_barrier
	s_waitcnt lgkmcnt(0)
	s_setprio 1
	s_waitcnt lgkmcnt(0)
	v_mfma_f32_16x16x32_bf16 v[112:115], v[208:211], v[158:161], v[112:115]
	v_mfma_f32_16x16x32_bf16 v[104:107], v[216:219], v[158:161], v[104:107]
	v_mfma_f32_16x16x32_bf16 v[100:103], v[208:211], v[184:187], v[100:103]
	v_mfma_f32_16x16x32_bf16 v[96:99], v[216:219], v[184:187], v[96:99]
	v_mfma_f32_16x16x32_bf16 v[84:87], v[208:211], v[192:195], v[84:87]
	v_mfma_f32_16x16x32_bf16 v[80:83], v[216:219], v[192:195], v[80:83]
	v_mfma_f32_16x16x32_bf16 v[68:71], v[208:211], v[200:203], v[68:71]
	v_mfma_f32_16x16x32_bf16 v[64:67], v[216:219], v[200:203], v[64:67]
	v_mfma_f32_16x16x32_bf16 v[112:115], v[212:215], v[162:165], v[112:115]
	v_mfma_f32_16x16x32_bf16 v[104:107], v[220:223], v[162:165], v[104:107]
	v_mfma_f32_16x16x32_bf16 v[100:103], v[212:215], v[188:191], v[100:103]
	v_mfma_f32_16x16x32_bf16 v[96:99], v[220:223], v[188:191], v[96:99]
	v_mfma_f32_16x16x32_bf16 v[84:87], v[212:215], v[196:199], v[84:87]
	v_mfma_f32_16x16x32_bf16 v[80:83], v[220:223], v[196:199], v[80:83]
	v_mfma_f32_16x16x32_bf16 v[68:71], v[212:215], v[204:207], v[68:71]
	v_mfma_f32_16x16x32_bf16 v[64:67], v[220:223], v[204:207], v[64:67]
	s_setprio 0
	s_mov_b32 m0, s41
	v_lshl_add_u64 v[226:227], s[34:35], 0, v[144:145]
	s_barrier
	ds_read_b128 v[158:161], v182 offset:16384
	ds_read_b128 v[162:165], v182 offset:17408
	ds_read_b128 v[184:187], v182 offset:18432
	ds_read_b128 v[188:191], v182 offset:19456
	ds_read_b128 v[192:195], v182 offset:20480
	ds_read_b128 v[196:199], v182 offset:21504
	ds_read_b128 v[200:203], v182 offset:22528
	ds_read_b128 v[204:207], v182 offset:23552
	global_load_lds_dwordx4 v[226:227], off
	v_lshl_add_u64 v[228:229], s[34:35], 0, v[148:149]
	s_mov_b32 m0, s42
	s_nop 0
	global_load_lds_dwordx4 v[228:229], off
	s_barrier
	s_waitcnt lgkmcnt(0)
	s_setprio 1
	s_waitcnt lgkmcnt(0)
	v_mfma_f32_16x16x32_bf16 v[60:63], v[128:131], v[158:161], v[60:63]
	v_mfma_f32_16x16x32_bf16 v[56:59], v[136:139], v[158:161], v[56:59]
	v_mfma_f32_16x16x32_bf16 v[44:47], v[128:131], v[184:187], v[44:47]
	v_mfma_f32_16x16x32_bf16 v[40:43], v[136:139], v[184:187], v[40:43]
	v_mfma_f32_16x16x32_bf16 v[28:31], v[128:131], v[192:195], v[28:31]
	v_mfma_f32_16x16x32_bf16 v[24:27], v[136:139], v[192:195], v[24:27]
	v_mfma_f32_16x16x32_bf16 v[16:19], v[128:131], v[200:203], v[16:19]
	v_mfma_f32_16x16x32_bf16 v[8:11], v[136:139], v[200:203], v[8:11]
	v_mfma_f32_16x16x32_bf16 v[60:63], v[132:135], v[162:165], v[60:63]
	v_mfma_f32_16x16x32_bf16 v[56:59], v[140:143], v[162:165], v[56:59]
	v_mfma_f32_16x16x32_bf16 v[44:47], v[132:135], v[188:191], v[44:47]
	v_mfma_f32_16x16x32_bf16 v[40:43], v[140:143], v[188:191], v[40:43]
	v_mfma_f32_16x16x32_bf16 v[28:31], v[132:135], v[196:199], v[28:31]
	v_mfma_f32_16x16x32_bf16 v[24:27], v[140:143], v[196:199], v[24:27]
	v_mfma_f32_16x16x32_bf16 v[16:19], v[132:135], v[204:207], v[16:19]
	v_mfma_f32_16x16x32_bf16 v[8:11], v[140:143], v[204:207], v[8:11]
	s_setprio 0
	s_barrier
	s_add_u32 s68, s30, 0x40000
	s_addc_u32 s69, s31, 0
	s_add_i32 s67, s57, s40
	v_lshl_add_u64 v[128:129], s[68:69], 0, v[146:147]
	s_mov_b32 m0, s67
	s_nop 0
	global_load_lds_dwordx4 v[128:129], off
	v_lshl_add_u64 v[128:129], s[68:69], 0, v[150:151]
	s_add_i32 m0, s67, 0x2000
	s_nop 0
	global_load_lds_dwordx4 v[128:129], off
	s_waitcnt vmcnt(6)
	s_barrier
	s_setprio 1
	v_mfma_f32_16x16x32_bf16 v[52:55], v[208:211], v[158:161], v[52:55]
	v_mfma_f32_16x16x32_bf16 v[48:51], v[216:219], v[158:161], v[48:51]
	v_mfma_f32_16x16x32_bf16 v[36:39], v[208:211], v[184:187], v[36:39]
	v_mfma_f32_16x16x32_bf16 v[32:35], v[216:219], v[184:187], v[32:35]
	v_mfma_f32_16x16x32_bf16 v[20:23], v[208:211], v[192:195], v[20:23]
	v_mfma_f32_16x16x32_bf16 v[12:15], v[216:219], v[192:195], v[12:15]
	v_mfma_f32_16x16x32_bf16 v[4:7], v[208:211], v[200:203], v[4:7]
	v_mfma_f32_16x16x32_bf16 v[0:3], v[216:219], v[200:203], v[0:3]
	v_mfma_f32_16x16x32_bf16 v[52:55], v[212:215], v[162:165], v[52:55]
	v_mfma_f32_16x16x32_bf16 v[48:51], v[220:223], v[162:165], v[48:51]
	v_mfma_f32_16x16x32_bf16 v[36:39], v[212:215], v[188:191], v[36:39]
	v_mfma_f32_16x16x32_bf16 v[32:35], v[220:223], v[188:191], v[32:35]
	v_mfma_f32_16x16x32_bf16 v[20:23], v[212:215], v[196:199], v[20:23]
	v_mfma_f32_16x16x32_bf16 v[12:15], v[220:223], v[196:199], v[12:15]
	v_mfma_f32_16x16x32_bf16 v[4:7], v[212:215], v[204:207], v[4:7]
	v_mfma_f32_16x16x32_bf16 v[0:3], v[220:223], v[204:207], v[0:3]
	s_setprio 0
	s_add_i32 s67, 0, 0x18000
	v_add_u32_e32 v140, s67, v169
	s_barrier
	ds_read_b128 v[128:131], v140
	ds_read_b128 v[132:135], v140 offset:1024
	ds_read_b128 v[136:139], v140 offset:2048
	ds_read_b128 v[140:143], v140 offset:3072
	s_add_u32 s34, s34, 0x40000
	s_addc_u32 s35, s35, 0
	s_mov_b32 m0, s43
	v_lshl_add_u64 v[208:209], s[34:35], 0, v[144:145]
	ds_read_b128 v[158:161], v182 offset:32768
	ds_read_b128 v[162:165], v182 offset:33792
	ds_read_b128 v[184:187], v182 offset:34816
	ds_read_b128 v[188:191], v182 offset:35840
	ds_read_b128 v[192:195], v182 offset:36864
	ds_read_b128 v[196:199], v182 offset:37888
	ds_read_b128 v[200:203], v182 offset:38912
	ds_read_b128 v[204:207], v182 offset:39936
	global_load_lds_dwordx4 v[208:209], off
	v_lshl_add_u64 v[208:209], s[34:35], 0, v[148:149]
	s_mov_b32 m0, s44
	s_nop 0
	global_load_lds_dwordx4 v[208:209], off
	s_waitcnt lgkmcnt(8)
	s_barrier
	s_waitcnt lgkmcnt(0)
	s_setprio 1
	s_waitcnt lgkmcnt(0)
	v_mfma_f32_16x16x32_bf16 v[124:127], v[128:131], v[158:161], v[124:127]
	v_mfma_f32_16x16x32_bf16 v[120:123], v[136:139], v[158:161], v[120:123]
	v_mfma_f32_16x16x32_bf16 v[116:119], v[128:131], v[184:187], v[116:119]
	v_mfma_f32_16x16x32_bf16 v[108:111], v[136:139], v[184:187], v[108:111]
	v_mfma_f32_16x16x32_bf16 v[92:95], v[128:131], v[192:195], v[92:95]
	v_mfma_f32_16x16x32_bf16 v[88:91], v[136:139], v[192:195], v[88:91]
	v_mfma_f32_16x16x32_bf16 v[76:79], v[128:131], v[200:203], v[76:79]
	v_mfma_f32_16x16x32_bf16 v[72:75], v[136:139], v[200:203], v[72:75]
	v_mfma_f32_16x16x32_bf16 v[124:127], v[132:135], v[162:165], v[124:127]
	v_mfma_f32_16x16x32_bf16 v[120:123], v[140:143], v[162:165], v[120:123]
	v_mfma_f32_16x16x32_bf16 v[116:119], v[132:135], v[188:191], v[116:119]
	v_mfma_f32_16x16x32_bf16 v[108:111], v[140:143], v[188:191], v[108:111]
	v_mfma_f32_16x16x32_bf16 v[92:95], v[132:135], v[196:199], v[92:95]
	v_mfma_f32_16x16x32_bf16 v[88:91], v[140:143], v[196:199], v[88:91]
	v_mfma_f32_16x16x32_bf16 v[76:79], v[132:135], v[204:207], v[76:79]
	v_mfma_f32_16x16x32_bf16 v[72:75], v[140:143], v[204:207], v[72:75]
	s_setprio 0
	s_barrier
	s_add_i32 s34, 0, 0x1c000
	s_add_i32 s35, s67, s40
	v_add_u32_e32 v220, s34, v169
	v_lshl_add_u64 v[166:167], v[166:167], 0, s[10:11]
	s_mov_b32 m0, s35
	ds_read_b128 v[208:211], v220
	ds_read_b128 v[212:215], v220 offset:1024
	ds_read_b128 v[216:219], v220 offset:2048
	ds_read_b128 v[220:223], v220 offset:3072
	global_load_lds_dwordx4 v[166:167], off
	v_lshl_add_u64 v[166:167], v[224:225], 0, s[10:11]
	s_add_i32 m0, s35, 0x2000
	s_nop 0
	global_load_lds_dwordx4 v[166:167], off
	s_barrier
	s_waitcnt lgkmcnt(0)
	s_setprio 1
	s_waitcnt lgkmcnt(0)
	v_mfma_f32_16x16x32_bf16 v[112:115], v[208:211], v[158:161], v[112:115]
	v_mfma_f32_16x16x32_bf16 v[104:107], v[216:219], v[158:161], v[104:107]
	v_mfma_f32_16x16x32_bf16 v[100:103], v[208:211], v[184:187], v[100:103]
	v_mfma_f32_16x16x32_bf16 v[96:99], v[216:219], v[184:187], v[96:99]
	v_mfma_f32_16x16x32_bf16 v[84:87], v[208:211], v[192:195], v[84:87]
	v_mfma_f32_16x16x32_bf16 v[80:83], v[216:219], v[192:195], v[80:83]
	v_mfma_f32_16x16x32_bf16 v[68:71], v[208:211], v[200:203], v[68:71]
	v_mfma_f32_16x16x32_bf16 v[64:67], v[216:219], v[200:203], v[64:67]
	v_mfma_f32_16x16x32_bf16 v[112:115], v[212:215], v[162:165], v[112:115]
	v_mfma_f32_16x16x32_bf16 v[104:107], v[220:223], v[162:165], v[104:107]
	v_mfma_f32_16x16x32_bf16 v[100:103], v[212:215], v[188:191], v[100:103]
	v_mfma_f32_16x16x32_bf16 v[96:99], v[220:223], v[188:191], v[96:99]
	v_mfma_f32_16x16x32_bf16 v[84:87], v[212:215], v[196:199], v[84:87]
	v_mfma_f32_16x16x32_bf16 v[80:83], v[220:223], v[196:199], v[80:83]
	v_mfma_f32_16x16x32_bf16 v[68:71], v[212:215], v[204:207], v[68:71]
	v_mfma_f32_16x16x32_bf16 v[64:67], v[220:223], v[204:207], v[64:67]
	s_setprio 0
	s_mov_b32 m0, s50
	v_lshl_add_u64 v[166:167], v[226:227], 0, s[10:11]
	s_barrier
	ds_read_b128 v[158:161], v182 offset:49152
	ds_read_b128 v[162:165], v182 offset:50176
	ds_read_b128 v[184:187], v182 offset:51200
	ds_read_b128 v[188:191], v182 offset:52224
	ds_read_b128 v[192:195], v182 offset:53248
	ds_read_b128 v[196:199], v182 offset:54272
	ds_read_b128 v[200:203], v182 offset:55296
	ds_read_b128 v[204:207], v182 offset:56320
	global_load_lds_dwordx4 v[166:167], off
	v_lshl_add_u64 v[166:167], v[228:229], 0, s[10:11]
	s_mov_b32 m0, s51
	s_nop 0
	global_load_lds_dwordx4 v[166:167], off
	s_barrier
	s_waitcnt lgkmcnt(0)
	s_setprio 1
	s_waitcnt lgkmcnt(0)
	v_mfma_f32_16x16x32_bf16 v[60:63], v[128:131], v[158:161], v[60:63]
	v_mfma_f32_16x16x32_bf16 v[56:59], v[136:139], v[158:161], v[56:59]
	v_mfma_f32_16x16x32_bf16 v[44:47], v[128:131], v[184:187], v[44:47]
	v_mfma_f32_16x16x32_bf16 v[40:43], v[136:139], v[184:187], v[40:43]
	v_mfma_f32_16x16x32_bf16 v[28:31], v[128:131], v[192:195], v[28:31]
	v_mfma_f32_16x16x32_bf16 v[24:27], v[136:139], v[192:195], v[24:27]
	v_mfma_f32_16x16x32_bf16 v[16:19], v[128:131], v[200:203], v[16:19]
	v_mfma_f32_16x16x32_bf16 v[8:11], v[136:139], v[200:203], v[8:11]
	v_mfma_f32_16x16x32_bf16 v[60:63], v[132:135], v[162:165], v[60:63]
	v_mfma_f32_16x16x32_bf16 v[56:59], v[140:143], v[162:165], v[56:59]
	v_mfma_f32_16x16x32_bf16 v[44:47], v[132:135], v[188:191], v[44:47]
	v_mfma_f32_16x16x32_bf16 v[40:43], v[140:143], v[188:191], v[40:43]
	v_mfma_f32_16x16x32_bf16 v[28:31], v[132:135], v[196:199], v[28:31]
	v_mfma_f32_16x16x32_bf16 v[24:27], v[140:143], v[196:199], v[24:27]
	v_mfma_f32_16x16x32_bf16 v[16:19], v[132:135], v[204:207], v[16:19]
	v_mfma_f32_16x16x32_bf16 v[8:11], v[140:143], v[204:207], v[8:11]
	s_setprio 0
	s_barrier
	s_add_u32 s30, s30, 0x40080
	s_addc_u32 s31, s31, 0
	s_add_i32 s34, s34, s40
	v_lshl_add_u64 v[128:129], s[30:31], 0, v[146:147]
	s_mov_b32 m0, s34
	s_nop 0
	global_load_lds_dwordx4 v[128:129], off
	v_lshl_add_u64 v[128:129], s[30:31], 0, v[150:151]
	s_add_i32 m0, s34, 0x2000
	s_nop 0
	global_load_lds_dwordx4 v[128:129], off
	s_waitcnt vmcnt(6)
	s_barrier
	s_setprio 1
	v_mfma_f32_16x16x32_bf16 v[52:55], v[208:211], v[158:161], v[52:55]
	v_mfma_f32_16x16x32_bf16 v[48:51], v[216:219], v[158:161], v[48:51]
	v_mfma_f32_16x16x32_bf16 v[36:39], v[208:211], v[184:187], v[36:39]
	v_mfma_f32_16x16x32_bf16 v[32:35], v[216:219], v[184:187], v[32:35]
	v_mfma_f32_16x16x32_bf16 v[20:23], v[208:211], v[192:195], v[20:23]
	v_mfma_f32_16x16x32_bf16 v[12:15], v[216:219], v[192:195], v[12:15]
	v_mfma_f32_16x16x32_bf16 v[4:7], v[208:211], v[200:203], v[4:7]
	v_mfma_f32_16x16x32_bf16 v[0:3], v[216:219], v[200:203], v[0:3]
	v_mfma_f32_16x16x32_bf16 v[52:55], v[212:215], v[162:165], v[52:55]
	v_mfma_f32_16x16x32_bf16 v[48:51], v[220:223], v[162:165], v[48:51]
	v_mfma_f32_16x16x32_bf16 v[36:39], v[212:215], v[188:191], v[36:39]
	v_mfma_f32_16x16x32_bf16 v[32:35], v[220:223], v[188:191], v[32:35]
	v_mfma_f32_16x16x32_bf16 v[20:23], v[212:215], v[196:199], v[20:23]
	v_mfma_f32_16x16x32_bf16 v[12:15], v[220:223], v[196:199], v[12:15]
	v_mfma_f32_16x16x32_bf16 v[4:7], v[212:215], v[204:207], v[4:7]
	v_mfma_f32_16x16x32_bf16 v[0:3], v[220:223], v[204:207], v[0:3]
	s_setprio 0
	s_add_i32 s66, s66, 2
	s_add_u32 s28, s28, 0x100
	s_addc_u32 s29, s29, 0
	s_add_u32 s64, s64, 0x100
	s_addc_u32 s65, s65, 0
	s_cmp_gt_u32 s66, 13
	s_barrier
	s_cbranch_scc0 .LBB0_404
	v_add_u32_e32 v158, s33, v168
	v_ashrrev_i32_e32 v159, 31, v158
	v_readlane_b32 s28, v254, 56
	v_add_u32_e32 v128, s49, v170
	v_lshlrev_b64 v[130:131], 11, v[158:159]
	v_readlane_b32 s29, v254, 57
	v_ashrrev_i32_e32 v129, 31, v128
	s_nop 0
	v_lshl_add_u64 v[130:131], s[28:29], 0, v[130:131]
	v_lshl_add_u64 v[160:161], v[128:129], 1, v[130:131]
	v_add_co_u32_e32 v192, vcc, s53, v160
	global_load_dwordx4 v[132:135], v[160:161], off
	global_load_dwordx4 v[140:143], v[160:161], off offset:256
	v_addc_co_u32_e32 v193, vcc, 0, v161, vcc
	global_load_dwordx4 v[184:187], v[192:193], off
	v_lshl_add_u64 v[164:165], v[160:161], 0, s[12:13]
	global_load_dwordx4 v[188:191], v[164:165], off offset:256
	v_add_co_u32_e32 v166, vcc, s46, v160
	v_lshl_add_u64 v[162:163], v[160:161], 0, s[14:15]
	s_nop 0
	v_addc_co_u32_e32 v167, vcc, 0, v161, vcc
	global_load_dwordx4 v[136:139], v[166:167], off
	global_load_dwordx4 v[128:131], v[162:163], off offset:256
	s_mov_b32 s98, s52
	s_mov_b32 s99, 0
	v_lshl_add_u64 v[250:251], v[160:161], 0, s[98:99]
	global_load_dwordx4 v[202:205], v[250:251], off
	v_lshl_add_u64 v[250:251], v[160:161], 0, s[16:17]
	global_load_dwordx4 v[206:209], v[250:251], off offset:256
	s_mov_b32 s98, s58
	s_mov_b32 s99, 0
	v_lshl_add_u64 v[250:251], v[160:161], 0, s[98:99]
	global_load_dwordx4 v[210:213], v[250:251], off
	v_lshl_add_u64 v[250:251], v[160:161], 0, s[8:9]
	global_load_dwordx4 v[214:217], v[250:251], off offset:256
	s_mov_b32 s98, s59
	s_mov_b32 s99, 0
	v_lshl_add_u64 v[250:251], v[160:161], 0, s[98:99]
	global_load_dwordx4 v[218:221], v[250:251], off
	v_lshl_add_u64 v[250:251], v[160:161], 0, s[18:19]
	global_load_dwordx4 v[222:225], v[250:251], off offset:256
	s_mov_b32 s98, s60
	s_mov_b32 s99, 0
	v_lshl_add_u64 v[250:251], v[160:161], 0, s[98:99]
	global_load_dwordx4 v[226:229], v[250:251], off
	v_lshl_add_u64 v[250:251], v[160:161], 0, s[20:21]
	global_load_dwordx4 v[230:233], v[250:251], off offset:256
	s_mov_b32 s98, s61
	s_mov_b32 s99, 0
	v_lshl_add_u64 v[250:251], v[160:161], 0, s[98:99]
	global_load_dwordx4 v[234:237], v[250:251], off
	v_lshl_add_u64 v[250:251], v[160:161], 0, s[22:23]
	global_load_dwordx4 v[238:241], v[250:251], off offset:256
	s_waitcnt vmcnt(10)
	v_lshlrev_b32_e32 v194, 16, v132
	v_and_b32_e32 v195, 0xffff0000, v132
	v_lshlrev_b32_e32 v196, 16, v134
	v_and_b32_e32 v197, 0xffff0000, v134
	v_pk_add_f32 v[124:125], v[124:125], v[194:195]
	v_lshlrev_b32_e32 v194, 16, v184
	v_and_b32_e32 v195, 0xffff0000, v184
	v_pk_add_f32 v[120:121], v[120:121], v[196:197]
	v_lshlrev_b32_e32 v184, 16, v185
	v_and_b32_e32 v185, 0xffff0000, v185
	v_lshlrev_b32_e32 v196, 16, v186
	v_and_b32_e32 v197, 0xffff0000, v186
	v_lshlrev_b32_e32 v186, 16, v187
	v_and_b32_e32 v187, 0xffff0000, v187
	v_pk_add_f32 v[116:117], v[116:117], v[194:195]
	v_pk_add_f32 v[118:119], v[118:119], v[184:185]
	v_pk_add_f32 v[184:185], v[110:111], v[186:187]
	v_mul_f32_e32 v111, v117, v117
	v_fmac_f32_e32 v111, v116, v116
	v_lshlrev_b32_e32 v132, 16, v133
	v_and_b32_e32 v133, 0xffff0000, v133
	v_lshlrev_b32_e32 v198, 16, v140
	v_and_b32_e32 v199, 0xffff0000, v140
	v_lshlrev_b32_e32 v140, 16, v141
	v_and_b32_e32 v141, 0xffff0000, v141
	v_lshlrev_b32_e32 v200, 16, v142
	v_and_b32_e32 v201, 0xffff0000, v142
	v_lshlrev_b32_e32 v142, 16, v143
	v_and_b32_e32 v143, 0xffff0000, v143
	v_fmac_f32_e32 v111, v118, v118
	v_lshlrev_b32_e32 v134, 16, v135
	v_and_b32_e32 v135, 0xffff0000, v135
	v_pk_add_f32 v[126:127], v[126:127], v[132:133]
	v_pk_add_f32 v[132:133], v[114:115], v[140:141]
	v_pk_add_f32 v[140:141], v[106:107], v[142:143]
	v_cvt_pk_bf16_f32 v106, v120, v121
	v_pk_add_f32 v[108:109], v[108:109], v[196:197]
	v_fmac_f32_e32 v111, v119, v119
	v_pk_add_f32 v[122:123], v[122:123], v[134:135]
	v_pk_add_f32 v[134:135], v[112:113], v[198:199]
	v_pk_add_f32 v[142:143], v[104:105], v[200:201]
	v_cvt_pk_bf16_f32 v104, v124, v125
	v_cvt_pk_bf16_f32 v105, v126, v127
	v_cvt_pk_bf16_f32 v107, v122, v123
	v_cvt_pk_bf16_f32 v112, v134, v135
	v_cvt_pk_bf16_f32 v113, v132, v133
	s_nop 0
	v_cvt_pk_bf16_f32 v114, v142, v143
	v_cvt_pk_bf16_f32 v115, v140, v141
	global_store_dwordx4 v[160:161], v[104:107], off
	v_fmac_f32_e32 v111, v108, v108
	global_store_dwordx4 v[160:161], v[112:115], off offset:256
	v_cvt_pk_bf16_f32 v106, v108, v109
	v_add_co_u32_e32 v108, vcc, s52, v160
	v_cvt_pk_bf16_f32 v104, v116, v117
	v_cvt_pk_bf16_f32 v105, v118, v119
	v_cvt_pk_bf16_f32 v107, v184, v185
	v_fmac_f32_e32 v111, v109, v109
	v_lshlrev_b32_e32 v112, 16, v188
	v_and_b32_e32 v113, 0xffff0000, v188
	v_lshlrev_b32_e32 v114, 16, v189
	v_and_b32_e32 v115, 0xffff0000, v189
	v_lshlrev_b32_e32 v116, 16, v190
	v_addc_co_u32_e32 v109, vcc, 0, v161, vcc
	v_and_b32_e32 v117, 0xffff0000, v190
	global_store_dwordx4 v[192:193], v[104:107], off
	v_lshlrev_b32_e32 v118, 16, v191
	v_and_b32_e32 v119, 0xffff0000, v191
	v_pk_add_f32 v[102:103], v[102:103], v[114:115]
	v_pk_add_f32 v[100:101], v[100:101], v[112:113]
	v_pk_add_f32 v[114:115], v[96:97], v[116:117]
	v_cvt_pk_bf16_f32 v96, v100, v101
	v_pk_add_f32 v[112:113], v[98:99], v[118:119]
	v_cvt_pk_bf16_f32 v97, v102, v103
	v_cvt_pk_bf16_f32 v98, v114, v115
	v_fmac_f32_e32 v111, v184, v184
	v_cvt_pk_bf16_f32 v99, v112, v113
	global_store_dwordx4 v[164:165], v[96:99], off offset:256
	v_fmac_f32_e32 v111, v185, v185
	v_lshlrev_b32_e32 v116, 16, v138
	v_mul_f32_e32 v96, v101, v101
	v_fmac_f32_e32 v96, v100, v100
	v_fmac_f32_e32 v96, v102, v102
	v_fmac_f32_e32 v96, v103, v103
	v_fmac_f32_e32 v96, v114, v114
	v_fmac_f32_e32 v96, v115, v115
	v_fmac_f32_e32 v96, v112, v112
	v_fmac_f32_e32 v96, v113, v113
	v_lshl_add_u64 v[100:101], v[160:161], 0, s[16:17]
	v_add_f32_e32 v102, v111, v96
	v_lshlrev_b32_e32 v112, 16, v136
	v_and_b32_e32 v113, 0xffff0000, v136
	v_lshlrev_b32_e32 v114, 16, v137
	v_and_b32_e32 v115, 0xffff0000, v137
	v_and_b32_e32 v117, 0xffff0000, v138
	v_lshlrev_b32_e32 v118, 16, v139
	v_and_b32_e32 v119, 0xffff0000, v139
	v_pk_add_f32 v[94:95], v[94:95], v[114:115]
	v_pk_add_f32 v[92:93], v[92:93], v[112:113]
	v_pk_add_f32 v[114:115], v[88:89], v[116:117]
	v_cvt_pk_bf16_f32 v88, v92, v93
	v_pk_add_f32 v[112:113], v[90:91], v[118:119]
	v_cvt_pk_bf16_f32 v89, v94, v95
	v_cvt_pk_bf16_f32 v90, v114, v115
	v_mul_f32_e32 v103, v93, v93
	v_cvt_pk_bf16_f32 v91, v112, v113
	global_store_dwordx4 v[166:167], v[88:91], off
	v_fmac_f32_e32 v103, v92, v92
	v_fmac_f32_e32 v103, v94, v94
	v_add_co_u32_e32 v88, vcc, s58, v160
	v_fmac_f32_e32 v103, v95, v95
	s_nop 0
	v_addc_co_u32_e32 v89, vcc, 0, v161, vcc
	v_fmac_f32_e32 v103, v114, v114
	v_fmac_f32_e32 v103, v115, v115
	v_fmac_f32_e32 v103, v112, v112
	v_fmac_f32_e32 v103, v113, v113
	v_lshlrev_b32_e32 v94, 16, v128
	v_and_b32_e32 v95, 0xffff0000, v128
	v_lshlrev_b32_e32 v112, 16, v129
	v_and_b32_e32 v113, 0xffff0000, v129
	v_lshlrev_b32_e32 v114, 16, v130
	v_and_b32_e32 v115, 0xffff0000, v130
	v_lshlrev_b32_e32 v116, 16, v131
	v_and_b32_e32 v117, 0xffff0000, v131
	v_pk_add_f32 v[86:87], v[86:87], v[112:113]
	v_pk_add_f32 v[84:85], v[84:85], v[94:95]
	v_pk_add_f32 v[112:113], v[80:81], v[114:115]
	v_cvt_pk_bf16_f32 v80, v84, v85
	v_pk_add_f32 v[94:95], v[82:83], v[116:117]
	v_cvt_pk_bf16_f32 v81, v86, v87
	v_cvt_pk_bf16_f32 v82, v112, v113
	v_mul_f32_e32 v125, v125, v125
	v_cvt_pk_bf16_f32 v83, v94, v95
	global_store_dwordx4 v[162:163], v[80:83], off offset:256
	v_mul_f32_e32 v135, v135, v135
	v_fmac_f32_e32 v125, v124, v124
	v_mul_f32_e32 v80, v85, v85
	v_fmac_f32_e32 v80, v84, v84
	v_fmac_f32_e32 v80, v86, v86
	v_fmac_f32_e32 v80, v87, v87
	v_fmac_f32_e32 v80, v112, v112
	v_fmac_f32_e32 v80, v113, v113
	v_fmac_f32_e32 v80, v94, v94
	v_fmac_f32_e32 v80, v95, v95
	v_lshl_add_u64 v[84:85], v[160:161], 0, s[8:9]
	v_add_f32_e32 v86, v103, v80
	s_waitcnt vmcnt(12)
	s_nop 1
	v_mov_b32_e32 v104, v202
	v_mov_b32_e32 v105, v203
	v_mov_b32_e32 v106, v204
	v_mov_b32_e32 v107, v205
	v_mov_b32_e32 v96, v206
	v_mov_b32_e32 v97, v207
	v_mov_b32_e32 v98, v208
	v_mov_b32_e32 v99, v209
	v_mov_b32_e32 v90, v210
	v_mov_b32_e32 v91, v211
	v_mov_b32_e32 v92, v212
	v_mov_b32_e32 v93, v213
	v_mov_b32_e32 v80, v214
	v_mov_b32_e32 v81, v215
	v_mov_b32_e32 v82, v216
	v_mov_b32_e32 v83, v217
	v_lshlrev_b32_e32 v94, 16, v104
	v_and_b32_e32 v95, 0xffff0000, v104
	v_pk_add_f32 v[76:77], v[76:77], v[94:95]
	v_lshlrev_b32_e32 v104, 16, v105
	v_and_b32_e32 v105, 0xffff0000, v105
	v_mul_f32_e32 v87, v77, v77
	v_pk_add_f32 v[78:79], v[78:79], v[104:105]
	v_fmac_f32_e32 v87, v76, v76
	v_lshlrev_b32_e32 v112, 16, v106
	v_and_b32_e32 v113, 0xffff0000, v106
	v_fmac_f32_e32 v87, v78, v78
	v_pk_add_f32 v[104:105], v[72:73], v[112:113]
	v_fmac_f32_e32 v87, v79, v79
	v_lshlrev_b32_e32 v106, 16, v107
	v_and_b32_e32 v107, 0xffff0000, v107
	v_fmac_f32_e32 v87, v104, v104
	v_pk_add_f32 v[94:95], v[74:75], v[106:107]
	v_fmac_f32_e32 v87, v105, v105
	v_fmac_f32_e32 v87, v94, v94
	v_cvt_pk_bf16_f32 v73, v78, v79
	v_cvt_pk_bf16_f32 v75, v94, v95
	v_fmac_f32_e32 v87, v95, v95
	v_lshlrev_b32_e32 v78, 16, v96
	v_and_b32_e32 v79, 0xffff0000, v96
	v_lshlrev_b32_e32 v94, 16, v97
	v_and_b32_e32 v95, 0xffff0000, v97
	v_lshlrev_b32_e32 v96, 16, v98
	v_and_b32_e32 v97, 0xffff0000, v98
	v_cvt_pk_bf16_f32 v72, v76, v77
	v_add_co_u32_e32 v76, vcc, s59, v160
	v_lshlrev_b32_e32 v98, 16, v99
	v_and_b32_e32 v99, 0xffff0000, v99
	v_pk_add_f32 v[70:71], v[70:71], v[94:95]
	v_pk_add_f32 v[68:69], v[68:69], v[78:79]
	v_pk_add_f32 v[94:95], v[64:65], v[96:97]
	v_cvt_pk_bf16_f32 v64, v68, v69
	v_cvt_pk_bf16_f32 v74, v104, v105
	v_addc_co_u32_e32 v77, vcc, 0, v161, vcc
	v_pk_add_f32 v[78:79], v[66:67], v[98:99]
	v_cvt_pk_bf16_f32 v65, v70, v71
	v_cvt_pk_bf16_f32 v66, v94, v95
	global_store_dwordx4 v[108:109], v[72:75], off
	v_cvt_pk_bf16_f32 v67, v78, v79
	global_store_dwordx4 v[100:101], v[64:67], off offset:256
	v_fmac_f32_e32 v135, v134, v134
	v_mul_f32_e32 v64, v69, v69
	v_fmac_f32_e32 v64, v68, v68
	v_fmac_f32_e32 v64, v70, v70
	v_fmac_f32_e32 v64, v71, v71
	v_fmac_f32_e32 v64, v94, v94
	v_fmac_f32_e32 v64, v95, v95
	v_fmac_f32_e32 v64, v78, v78
	v_fmac_f32_e32 v64, v79, v79
	v_add_f32_e32 v68, v87, v64
	v_lshlrev_b32_e32 v64, 16, v91
	v_and_b32_e32 v65, 0xffff0000, v91
	v_lshl_add_u64 v[66:67], v[160:161], 0, s[18:19]
	v_lshlrev_b32_e32 v70, 16, v90
	v_and_b32_e32 v71, 0xffff0000, v90
	v_lshlrev_b32_e32 v78, 16, v92
	v_and_b32_e32 v79, 0xffff0000, v92
	v_lshlrev_b32_e32 v90, 16, v93
	v_and_b32_e32 v91, 0xffff0000, v93
	v_pk_add_f32 v[92:93], v[62:63], v[64:65]
	v_pk_add_f32 v[60:61], v[60:61], v[70:71]
	v_pk_add_f32 v[78:79], v[56:57], v[78:79]
	v_mul_f32_e32 v69, v61, v61
	v_fmac_f32_e32 v69, v60, v60
	v_fmac_f32_e32 v69, v92, v92
	v_fmac_f32_e32 v69, v93, v93
	v_fmac_f32_e32 v69, v78, v78
	v_pk_add_f32 v[70:71], v[58:59], v[90:91]
	v_fmac_f32_e32 v69, v79, v79
	v_fmac_f32_e32 v69, v70, v70
	v_cvt_pk_bf16_f32 v58, v78, v79
	v_cvt_pk_bf16_f32 v59, v70, v71
	v_fmac_f32_e32 v69, v71, v71
	v_lshlrev_b32_e32 v70, 16, v80
	v_and_b32_e32 v71, 0xffff0000, v80
	v_lshlrev_b32_e32 v78, 16, v81
	v_and_b32_e32 v79, 0xffff0000, v81
	v_lshlrev_b32_e32 v80, 16, v82
	v_and_b32_e32 v81, 0xffff0000, v82
	v_lshlrev_b32_e32 v82, 16, v83
	v_and_b32_e32 v83, 0xffff0000, v83
	v_pk_add_f32 v[54:55], v[54:55], v[78:79]
	v_pk_add_f32 v[52:53], v[52:53], v[70:71]
	v_pk_add_f32 v[78:79], v[48:49], v[80:81]
	v_cvt_pk_bf16_f32 v48, v52, v53
	v_pk_add_f32 v[70:71], v[50:51], v[82:83]
	v_cvt_pk_bf16_f32 v49, v54, v55
	v_cvt_pk_bf16_f32 v50, v78, v79
	v_cvt_pk_bf16_f32 v56, v60, v61
	v_add_co_u32_e32 v60, vcc, s60, v160
	v_cvt_pk_bf16_f32 v51, v70, v71
	global_store_dwordx4 v[84:85], v[48:51], off offset:256
	v_cvt_pk_bf16_f32 v57, v92, v93
	s_nop 0
	v_addc_co_u32_e32 v61, vcc, 0, v161, vcc
	v_mul_f32_e32 v48, v53, v53
	v_fmac_f32_e32 v48, v52, v52
	v_fmac_f32_e32 v48, v54, v54
	v_fmac_f32_e32 v48, v55, v55
	v_fmac_f32_e32 v48, v78, v78
	global_store_dwordx4 v[88:89], v[56:59], off
	v_fmac_f32_e32 v48, v79, v79
	v_fmac_f32_e32 v48, v70, v70
	v_fmac_f32_e32 v48, v71, v71
	v_add_f32_e32 v69, v69, v48
	v_lshl_add_u64 v[48:49], v[160:161], 0, s[20:21]
	v_fmac_f32_e32 v125, v126, v126
	v_fmac_f32_e32 v135, v132, v132
	v_fmac_f32_e32 v125, v127, v127
	v_fmac_f32_e32 v135, v133, v133
	v_fmac_f32_e32 v125, v120, v120
	v_fmac_f32_e32 v135, v142, v142
	v_fmac_f32_e32 v125, v121, v121
	v_fmac_f32_e32 v135, v143, v143
	v_fmac_f32_e32 v125, v122, v122
	s_waitcnt vmcnt(12)
	s_nop 1
	v_mov_b32_e32 v72, v218
	v_mov_b32_e32 v73, v219
	v_mov_b32_e32 v74, v220
	v_mov_b32_e32 v75, v221
	v_mov_b32_e32 v62, v222
	v_mov_b32_e32 v63, v223
	v_mov_b32_e32 v64, v224
	v_mov_b32_e32 v65, v225
	v_mov_b32_e32 v56, v226
	v_mov_b32_e32 v57, v227
	v_mov_b32_e32 v58, v228
	v_mov_b32_e32 v59, v229
	v_mov_b32_e32 v50, v230
	v_mov_b32_e32 v51, v231
	v_mov_b32_e32 v52, v232
	v_mov_b32_e32 v53, v233
	v_lshlrev_b32_e32 v54, 16, v72
	v_and_b32_e32 v55, 0xffff0000, v72
	v_lshlrev_b32_e32 v70, 16, v73
	v_and_b32_e32 v71, 0xffff0000, v73
	v_lshlrev_b32_e32 v72, 16, v74
	v_and_b32_e32 v73, 0xffff0000, v74
	v_pk_add_f32 v[44:45], v[44:45], v[54:55]
	v_pk_add_f32 v[46:47], v[46:47], v[70:71]
	v_pk_add_f32 v[70:71], v[40:41], v[72:73]
	v_mul_f32_e32 v72, v45, v45
	v_fmac_f32_e32 v72, v44, v44
	v_fmac_f32_e32 v72, v46, v46
	v_fmac_f32_e32 v72, v47, v47
	v_lshlrev_b32_e32 v74, 16, v75
	v_and_b32_e32 v75, 0xffff0000, v75
	v_cvt_pk_bf16_f32 v40, v44, v45
	v_fmac_f32_e32 v72, v70, v70
	v_add_co_u32_e32 v44, vcc, s61, v160
	v_pk_add_f32 v[54:55], v[42:43], v[74:75]
	v_cvt_pk_bf16_f32 v41, v46, v47
	v_cvt_pk_bf16_f32 v42, v70, v71
	v_fmac_f32_e32 v72, v71, v71
	v_cvt_pk_bf16_f32 v43, v54, v55
	v_addc_co_u32_e32 v45, vcc, 0, v161, vcc
	global_store_dwordx4 v[76:77], v[40:43], off
	v_fmac_f32_e32 v72, v54, v54
	v_lshlrev_b32_e32 v46, 16, v62
	v_and_b32_e32 v47, 0xffff0000, v62
	v_fmac_f32_e32 v72, v55, v55
	v_lshlrev_b32_e32 v54, 16, v63
	v_and_b32_e32 v55, 0xffff0000, v63
	v_lshlrev_b32_e32 v62, 16, v64
	v_and_b32_e32 v63, 0xffff0000, v64
	v_pk_add_f32 v[36:37], v[36:37], v[46:47]
	v_lshlrev_b32_e32 v64, 16, v65
	v_and_b32_e32 v65, 0xffff0000, v65
	v_pk_add_f32 v[38:39], v[38:39], v[54:55]
	v_pk_add_f32 v[54:55], v[32:33], v[62:63]
	v_mul_f32_e32 v62, v37, v37
	v_pk_add_f32 v[46:47], v[34:35], v[64:65]
	v_cvt_pk_bf16_f32 v32, v36, v37
	v_cvt_pk_bf16_f32 v33, v38, v39
	v_cvt_pk_bf16_f32 v34, v54, v55
	v_fmac_f32_e32 v62, v36, v36
	v_cvt_pk_bf16_f32 v35, v46, v47
	v_lshl_add_u64 v[36:37], v[160:161], 0, s[22:23]
	global_store_dwordx4 v[66:67], v[32:35], off offset:256
	v_fmac_f32_e32 v62, v38, v38
	v_fmac_f32_e32 v62, v39, v39
	v_fmac_f32_e32 v62, v54, v54
	v_fmac_f32_e32 v62, v55, v55
	v_fmac_f32_e32 v62, v46, v46
	v_fmac_f32_e32 v62, v47, v47
	v_fmac_f32_e32 v135, v140, v140
	v_fmac_f32_e32 v125, v123, v123
	v_fmac_f32_e32 v135, v141, v141
	v_add_f32_e32 v110, v125, v135
	v_add_f32_e32 v62, v72, v62
	v_lshlrev_b32_e32 v38, 16, v56
	v_and_b32_e32 v39, 0xffff0000, v56
	v_lshlrev_b32_e32 v46, 16, v57
	v_and_b32_e32 v47, 0xffff0000, v57
	v_lshlrev_b32_e32 v54, 16, v58
	v_and_b32_e32 v55, 0xffff0000, v58
	v_pk_add_f32 v[28:29], v[28:29], v[38:39]
	v_lshlrev_b32_e32 v56, 16, v59
	v_and_b32_e32 v57, 0xffff0000, v59
	v_pk_add_f32 v[30:31], v[30:31], v[46:47]
	v_pk_add_f32 v[46:47], v[24:25], v[54:55]
	v_mul_f32_e32 v54, v29, v29
	v_pk_add_f32 v[38:39], v[26:27], v[56:57]
	v_cvt_pk_bf16_f32 v24, v28, v29
	v_cvt_pk_bf16_f32 v25, v30, v31
	v_cvt_pk_bf16_f32 v26, v46, v47
	v_fmac_f32_e32 v54, v28, v28
	v_cvt_pk_bf16_f32 v27, v38, v39
	global_store_dwordx4 v[60:61], v[24:27], off
	v_fmac_f32_e32 v54, v30, v30
	v_lshlrev_b32_e32 v28, 16, v52
	v_lshlrev_b32_e32 v24, 16, v50
	v_and_b32_e32 v25, 0xffff0000, v50
	v_lshlrev_b32_e32 v26, 16, v51
	v_and_b32_e32 v27, 0xffff0000, v51
	v_and_b32_e32 v29, 0xffff0000, v52
	v_fmac_f32_e32 v54, v31, v31
	v_lshlrev_b32_e32 v30, 16, v53
	v_and_b32_e32 v31, 0xffff0000, v53
	v_pk_add_f32 v[22:23], v[22:23], v[26:27]
	v_pk_add_f32 v[20:21], v[20:21], v[24:25]
	v_pk_add_f32 v[26:27], v[12:13], v[28:29]
	v_cvt_pk_bf16_f32 v12, v20, v21
	v_pk_add_f32 v[24:25], v[14:15], v[30:31]
	v_cvt_pk_bf16_f32 v13, v22, v23
	v_cvt_pk_bf16_f32 v14, v26, v27
	v_fmac_f32_e32 v54, v46, v46
	v_cvt_pk_bf16_f32 v15, v24, v25
	global_store_dwordx4 v[48:49], v[12:15], off offset:256
	v_fmac_f32_e32 v54, v47, v47
	v_fmac_f32_e32 v54, v38, v38
	v_mul_f32_e32 v12, v21, v21
	v_fmac_f32_e32 v12, v20, v20
	v_fmac_f32_e32 v12, v22, v22
	v_fmac_f32_e32 v12, v23, v23
	v_fmac_f32_e32 v12, v26, v26
	v_fmac_f32_e32 v12, v27, v27
	v_fmac_f32_e32 v12, v24, v24
	v_fmac_f32_e32 v54, v39, v39
	v_fmac_f32_e32 v12, v25, v25
	v_add_f32_e32 v24, v54, v12
	s_waitcnt vmcnt(14)
	s_nop 1
	v_mov_b32_e32 v40, v234
	v_mov_b32_e32 v41, v235
	v_mov_b32_e32 v42, v236
	v_mov_b32_e32 v43, v237
	v_mov_b32_e32 v32, v238
	v_mov_b32_e32 v33, v239
	v_mov_b32_e32 v34, v240
	v_mov_b32_e32 v35, v241
	v_lshlrev_b32_e32 v12, 16, v40
	v_and_b32_e32 v13, 0xffff0000, v40
	v_pk_add_f32 v[12:13], v[16:17], v[12:13]
	v_lshlrev_b32_e32 v14, 16, v41
	v_and_b32_e32 v15, 0xffff0000, v41
	v_lshlrev_b32_e32 v20, 16, v42
	v_and_b32_e32 v21, 0xffff0000, v42
	v_mul_f32_e32 v25, v13, v13
	v_lshlrev_b32_e32 v22, 16, v43
	v_and_b32_e32 v23, 0xffff0000, v43
	v_pk_add_f32 v[14:15], v[18:19], v[14:15]
	v_pk_add_f32 v[18:19], v[8:9], v[20:21]
	v_cvt_pk_bf16_f32 v8, v12, v13
	v_cvt_pk_bf16_f32 v9, v14, v15
	v_fmac_f32_e32 v25, v12, v12
	v_pk_add_f32 v[16:17], v[10:11], v[22:23]
	v_cvt_pk_bf16_f32 v10, v18, v19
	v_fmac_f32_e32 v25, v14, v14
	v_cvt_pk_bf16_f32 v11, v16, v17
	global_store_dwordx4 v[44:45], v[8:11], off
	v_fmac_f32_e32 v25, v15, v15
	v_lshlrev_b32_e32 v12, 16, v34
	v_lshlrev_b32_e32 v8, 16, v32
	v_and_b32_e32 v9, 0xffff0000, v32
	v_and_b32_e32 v13, 0xffff0000, v34
	v_pk_add_f32 v[4:5], v[4:5], v[8:9]
	v_fmac_f32_e32 v25, v18, v18
	v_lshlrev_b32_e32 v10, 16, v33
	v_and_b32_e32 v11, 0xffff0000, v33
	v_pk_add_f32 v[22:23], v[0:1], v[12:13]
	v_mul_f32_e32 v0, v5, v5
	v_fmac_f32_e32 v25, v19, v19
	v_pk_add_f32 v[18:19], v[6:7], v[10:11]
	v_fmac_f32_e32 v0, v4, v4
	v_fmac_f32_e32 v0, v18, v18
	v_fmac_f32_e32 v0, v19, v19
	v_lshlrev_b32_e32 v14, 16, v35
	v_and_b32_e32 v15, 0xffff0000, v35
	v_fmac_f32_e32 v0, v22, v22
	v_pk_add_f32 v[20:21], v[2:3], v[14:15]
	v_fmac_f32_e32 v0, v23, v23
	v_fmac_f32_e32 v25, v16, v16
	v_fmac_f32_e32 v0, v20, v20
	v_fmac_f32_e32 v25, v17, v17
	v_fmac_f32_e32 v0, v21, v21
	v_add_f32_e32 v14, v25, v0
	v_cvt_pk_bf16_f32 v16, v4, v5
	ds_bpermute_b32 v1, v171, v110
	ds_bpermute_b32 v2, v171, v102
	ds_bpermute_b32 v4, v171, v86
	ds_bpermute_b32 v6, v171, v68
	ds_bpermute_b32 v8, v171, v69
	ds_bpermute_b32 v10, v171, v62
	ds_bpermute_b32 v12, v171, v24
	ds_bpermute_b32 v15, v171, v14
	s_waitcnt lgkmcnt(0)
	v_add_f32_e32 v0, v110, v1
	v_add_f32_e32 v2, v102, v2
	v_add_f32_e32 v4, v86, v4
	v_add_f32_e32 v6, v68, v6
	v_add_f32_e32 v8, v69, v8
	v_add_f32_e32 v10, v62, v10
	v_add_f32_e32 v12, v24, v12
	v_add_f32_e32 v14, v14, v15
	ds_bpermute_b32 v1, v172, v0
	ds_bpermute_b32 v3, v172, v2
	ds_bpermute_b32 v5, v172, v4
	ds_bpermute_b32 v7, v172, v6
	ds_bpermute_b32 v9, v172, v8
	ds_bpermute_b32 v11, v172, v10
	ds_bpermute_b32 v13, v172, v12
	ds_bpermute_b32 v15, v172, v14
	v_cvt_pk_bf16_f32 v17, v18, v19
	v_cvt_pk_bf16_f32 v18, v22, v23
	v_cvt_pk_bf16_f32 v19, v20, v21
	global_store_dwordx4 v[36:37], v[16:19], off offset:256
	s_and_saveexec_b64 s[28:29], s[0:1]
	s_cbranch_execz .LBB0_407
	s_waitcnt lgkmcnt(6)
	v_add_f32_e32 v2, v2, v3
	v_add_f32_e32 v0, v0, v1
	v_add_u32_e32 v1, s54, v173
	s_waitcnt lgkmcnt(2)
	v_add_f32_e32 v10, v10, v11
	v_add_f32_e32 v8, v8, v9
	v_add_f32_e32 v6, v6, v7
	v_add_f32_e32 v4, v4, v5
	ds_write2st64_b32 v1, v0, v2 offset1:1
	ds_write2st64_b32 v1, v4, v6 offset0:2 offset1:3
	v_add_u32_e32 v0, s54, v177
	s_waitcnt lgkmcnt(2)
	v_add_f32_e32 v14, v14, v15
	v_add_f32_e32 v12, v12, v13
	ds_write2st64_b32 v0, v8, v10 offset1:1
	ds_write2st64_b32 v0, v12, v14 offset0:2 offset1:3

.LBB0_470:
	s_add_u32 s22, s48, 0xfff00080
	s_addc_u32 s23, s49, -1
	s_add_i32 s86, 0, 0x10000
	v_add_u32_e32 v172, s86, v149
	ds_read_b128 v[144:147], v172
	ds_read_b128 v[164:167], v172 offset:1024
	ds_read_b128 v[168:171], v172 offset:2048
	ds_read_b128 v[172:175], v172 offset:3072
	s_cmp_eq_u32 s60, 60
	s_cselect_b32 s53, s45, s23
	s_cselect_b32 s52, s44, s22
	s_cselect_b32 s51, s47, s19
	s_cselect_b32 s50, s46, s18
	v_lshl_add_u64 v[212:213], s[48:49], 0, v[140:141]
	s_add_i32 m0, s75, 0xc000
	ds_read_b128 v[176:179], v163
	ds_read_b128 v[180:183], v163 offset:1024
	ds_read_b128 v[184:187], v163 offset:2048
	ds_read_b128 v[188:191], v163 offset:3072
	ds_read_b128 v[192:195], v163 offset:4096
	ds_read_b128 v[200:203], v163 offset:5120
	ds_read_b128 v[204:207], v163 offset:6144
	ds_read_b128 v[208:211], v163 offset:7168
	global_load_lds_dwordx4 v[212:213], off
	v_lshl_add_u64 v[212:213], s[48:49], 0, v[142:143]
	s_add_i32 m0, s75, 0xe000
	s_nop 0
	global_load_lds_dwordx4 v[212:213], off
	s_waitcnt lgkmcnt(8)
	s_barrier
	s_waitcnt lgkmcnt(0)
	s_setprio 1
	s_waitcnt lgkmcnt(0)
	v_mfma_f32_16x16x32_bf16 v[124:127], v[144:147], v[176:179], v[124:127]
	v_mfma_f32_16x16x32_bf16 v[120:123], v[168:171], v[176:179], v[120:123]
	v_mfma_f32_16x16x32_bf16 v[108:111], v[144:147], v[184:187], v[108:111]
	v_mfma_f32_16x16x32_bf16 v[104:107], v[168:171], v[184:187], v[104:107]
	v_mfma_f32_16x16x32_bf16 v[92:95], v[144:147], v[192:195], v[92:95]
	v_mfma_f32_16x16x32_bf16 v[88:91], v[168:171], v[192:195], v[88:91]
	v_mfma_f32_16x16x32_bf16 v[76:79], v[144:147], v[204:207], v[76:79]
	v_mfma_f32_16x16x32_bf16 v[72:75], v[168:171], v[204:207], v[72:75]
	v_mfma_f32_16x16x32_bf16 v[124:127], v[164:167], v[180:183], v[124:127]
	v_mfma_f32_16x16x32_bf16 v[120:123], v[172:175], v[180:183], v[120:123]
	v_mfma_f32_16x16x32_bf16 v[108:111], v[164:167], v[188:191], v[108:111]
	v_mfma_f32_16x16x32_bf16 v[104:107], v[172:175], v[188:191], v[104:107]
	v_mfma_f32_16x16x32_bf16 v[92:95], v[164:167], v[200:203], v[92:95]
	v_mfma_f32_16x16x32_bf16 v[88:91], v[172:175], v[200:203], v[88:91]
	v_mfma_f32_16x16x32_bf16 v[76:79], v[164:167], v[208:211], v[76:79]
	v_mfma_f32_16x16x32_bf16 v[72:75], v[172:175], v[208:211], v[72:75]
	s_setprio 0
	s_barrier
	s_add_i32 s87, 0, 0x14000
	s_add_i32 s22, s86, s74
	v_add_u32_e32 v224, s87, v149
	v_lshl_add_u64 v[228:229], s[50:51], 0, v[138:139]
	s_mov_b32 m0, s22
	ds_read_b128 v[212:215], v224
	ds_read_b128 v[216:219], v224 offset:1024
	ds_read_b128 v[220:223], v224 offset:2048
	ds_read_b128 v[224:227], v224 offset:3072
	global_load_lds_dwordx4 v[228:229], off
	v_lshl_add_u64 v[230:231], s[50:51], 0, v[134:135]
	s_add_i32 m0, s22, 0x2000
	s_nop 0
	global_load_lds_dwordx4 v[230:231], off
	s_barrier
	s_waitcnt lgkmcnt(0)
	s_setprio 1
	s_waitcnt lgkmcnt(0)
	v_mfma_f32_16x16x32_bf16 v[116:119], v[212:215], v[176:179], v[116:119]
	v_mfma_f32_16x16x32_bf16 v[112:115], v[220:223], v[176:179], v[112:115]
	v_mfma_f32_16x16x32_bf16 v[100:103], v[212:215], v[184:187], v[100:103]
	v_mfma_f32_16x16x32_bf16 v[96:99], v[220:223], v[184:187], v[96:99]
	v_mfma_f32_16x16x32_bf16 v[84:87], v[212:215], v[192:195], v[84:87]
	v_mfma_f32_16x16x32_bf16 v[80:83], v[220:223], v[192:195], v[80:83]
	v_mfma_f32_16x16x32_bf16 v[68:71], v[212:215], v[204:207], v[68:71]
	v_mfma_f32_16x16x32_bf16 v[64:67], v[220:223], v[204:207], v[64:67]
	v_mfma_f32_16x16x32_bf16 v[116:119], v[216:219], v[180:183], v[116:119]
	v_mfma_f32_16x16x32_bf16 v[112:115], v[224:227], v[180:183], v[112:115]
	v_mfma_f32_16x16x32_bf16 v[100:103], v[216:219], v[188:191], v[100:103]
	v_mfma_f32_16x16x32_bf16 v[96:99], v[224:227], v[188:191], v[96:99]
	v_mfma_f32_16x16x32_bf16 v[84:87], v[216:219], v[200:203], v[84:87]
	v_mfma_f32_16x16x32_bf16 v[80:83], v[224:227], v[200:203], v[80:83]
	v_mfma_f32_16x16x32_bf16 v[68:71], v[216:219], v[208:211], v[68:71]
	v_mfma_f32_16x16x32_bf16 v[64:67], v[224:227], v[208:211], v[64:67]
	s_setprio 0
	s_mov_b32 m0, s75
	v_lshl_add_u64 v[232:233], s[52:53], 0, v[128:129]
	s_barrier
	ds_read_b128 v[176:179], v163 offset:16384
	ds_read_b128 v[180:183], v163 offset:17408
	ds_read_b128 v[184:187], v163 offset:18432
	ds_read_b128 v[188:191], v163 offset:19456
	ds_read_b128 v[192:195], v163 offset:20480
	ds_read_b128 v[200:203], v163 offset:21504
	ds_read_b128 v[204:207], v163 offset:22528
	ds_read_b128 v[208:211], v163 offset:23552
	global_load_lds_dwordx4 v[232:233], off
	v_lshl_add_u64 v[234:235], s[52:53], 0, v[136:137]
	s_mov_b32 m0, s76
	s_nop 0
	global_load_lds_dwordx4 v[234:235], off
	s_barrier
	s_waitcnt lgkmcnt(0)
	s_setprio 1
	s_waitcnt lgkmcnt(0)
	v_mfma_f32_16x16x32_bf16 v[60:63], v[144:147], v[176:179], v[60:63]
	v_mfma_f32_16x16x32_bf16 v[56:59], v[168:171], v[176:179], v[56:59]
	v_mfma_f32_16x16x32_bf16 v[44:47], v[144:147], v[184:187], v[44:47]
	v_mfma_f32_16x16x32_bf16 v[40:43], v[168:171], v[184:187], v[40:43]
	v_mfma_f32_16x16x32_bf16 v[28:31], v[144:147], v[192:195], v[28:31]
	v_mfma_f32_16x16x32_bf16 v[24:27], v[168:171], v[192:195], v[24:27]
	v_mfma_f32_16x16x32_bf16 v[12:15], v[144:147], v[204:207], v[12:15]
	v_mfma_f32_16x16x32_bf16 v[8:11], v[168:171], v[204:207], v[8:11]
	v_mfma_f32_16x16x32_bf16 v[60:63], v[164:167], v[180:183], v[60:63]
	v_mfma_f32_16x16x32_bf16 v[56:59], v[172:175], v[180:183], v[56:59]
	v_mfma_f32_16x16x32_bf16 v[44:47], v[164:167], v[188:191], v[44:47]
	v_mfma_f32_16x16x32_bf16 v[40:43], v[172:175], v[188:191], v[40:43]
	v_mfma_f32_16x16x32_bf16 v[28:31], v[164:167], v[200:203], v[28:31]
	v_mfma_f32_16x16x32_bf16 v[24:27], v[172:175], v[200:203], v[24:27]
	v_mfma_f32_16x16x32_bf16 v[12:15], v[164:167], v[208:211], v[12:15]
	v_mfma_f32_16x16x32_bf16 v[8:11], v[172:175], v[208:211], v[8:11]
	s_setprio 0
	s_barrier
	s_add_u32 s22, s50, 0x100000
	s_addc_u32 s23, s51, 0
	s_add_i32 s86, s87, s74
	v_lshl_add_u64 v[144:145], s[22:23], 0, v[138:139]
	s_mov_b32 m0, s86
	s_nop 0
	global_load_lds_dwordx4 v[144:145], off
	v_lshl_add_u64 v[144:145], s[22:23], 0, v[134:135]
	s_add_i32 m0, s86, 0x2000
	s_nop 0
	global_load_lds_dwordx4 v[144:145], off
	s_waitcnt vmcnt(6)
	s_barrier
	s_setprio 1
	v_mfma_f32_16x16x32_bf16 v[52:55], v[212:215], v[176:179], v[52:55]
	v_mfma_f32_16x16x32_bf16 v[48:51], v[220:223], v[176:179], v[48:51]
	v_mfma_f32_16x16x32_bf16 v[36:39], v[212:215], v[184:187], v[36:39]
	v_mfma_f32_16x16x32_bf16 v[32:35], v[220:223], v[184:187], v[32:35]
	v_mfma_f32_16x16x32_bf16 v[20:23], v[212:215], v[192:195], v[20:23]
	v_mfma_f32_16x16x32_bf16 v[16:19], v[220:223], v[192:195], v[16:19]
	v_mfma_f32_16x16x32_bf16 v[4:7], v[212:215], v[204:207], v[4:7]
	v_mfma_f32_16x16x32_bf16 v[0:3], v[220:223], v[204:207], v[0:3]
	v_mfma_f32_16x16x32_bf16 v[52:55], v[216:219], v[180:183], v[52:55]
	v_mfma_f32_16x16x32_bf16 v[48:51], v[224:227], v[180:183], v[48:51]
	v_mfma_f32_16x16x32_bf16 v[36:39], v[216:219], v[188:191], v[36:39]
	v_mfma_f32_16x16x32_bf16 v[32:35], v[224:227], v[188:191], v[32:35]
	v_mfma_f32_16x16x32_bf16 v[20:23], v[216:219], v[200:203], v[20:23]
	v_mfma_f32_16x16x32_bf16 v[16:19], v[224:227], v[200:203], v[16:19]
	v_mfma_f32_16x16x32_bf16 v[4:7], v[216:219], v[208:211], v[4:7]
	v_mfma_f32_16x16x32_bf16 v[0:3], v[224:227], v[208:211], v[0:3]
	s_setprio 0
	s_add_i32 s86, 0, 0x18000
	v_add_u32_e32 v172, s86, v149
	s_barrier
	ds_read_b128 v[144:147], v172
	ds_read_b128 v[164:167], v172 offset:1024
	ds_read_b128 v[168:171], v172 offset:2048
	ds_read_b128 v[172:175], v172 offset:3072
	s_add_u32 s22, s52, 0x100000
	s_addc_u32 s23, s53, 0
	s_mov_b32 m0, s77
	v_lshl_add_u64 v[212:213], s[22:23], 0, v[128:129]
	ds_read_b128 v[176:179], v163 offset:32768
	ds_read_b128 v[180:183], v163 offset:33792
	ds_read_b128 v[184:187], v163 offset:34816
	ds_read_b128 v[188:191], v163 offset:35840
	ds_read_b128 v[192:195], v163 offset:36864
	ds_read_b128 v[200:203], v163 offset:37888
	ds_read_b128 v[204:207], v163 offset:38912
	ds_read_b128 v[208:211], v163 offset:39936
	global_load_lds_dwordx4 v[212:213], off
	v_lshl_add_u64 v[212:213], s[22:23], 0, v[136:137]
	s_mov_b32 m0, s78
	s_nop 0
	global_load_lds_dwordx4 v[212:213], off
	s_waitcnt lgkmcnt(8)
	s_barrier
	s_waitcnt lgkmcnt(0)
	s_setprio 1
	s_waitcnt lgkmcnt(0)
	v_mfma_f32_16x16x32_bf16 v[124:127], v[144:147], v[176:179], v[124:127]
	v_mfma_f32_16x16x32_bf16 v[120:123], v[168:171], v[176:179], v[120:123]
	v_mfma_f32_16x16x32_bf16 v[108:111], v[144:147], v[184:187], v[108:111]
	v_mfma_f32_16x16x32_bf16 v[104:107], v[168:171], v[184:187], v[104:107]
	v_mfma_f32_16x16x32_bf16 v[92:95], v[144:147], v[192:195], v[92:95]
	v_mfma_f32_16x16x32_bf16 v[88:91], v[168:171], v[192:195], v[88:91]
	v_mfma_f32_16x16x32_bf16 v[76:79], v[144:147], v[204:207], v[76:79]
	v_mfma_f32_16x16x32_bf16 v[72:75], v[168:171], v[204:207], v[72:75]
	v_mfma_f32_16x16x32_bf16 v[124:127], v[164:167], v[180:183], v[124:127]
	v_mfma_f32_16x16x32_bf16 v[120:123], v[172:175], v[180:183], v[120:123]
	v_mfma_f32_16x16x32_bf16 v[108:111], v[164:167], v[188:191], v[108:111]
	v_mfma_f32_16x16x32_bf16 v[104:107], v[172:175], v[188:191], v[104:107]
	v_mfma_f32_16x16x32_bf16 v[92:95], v[164:167], v[200:203], v[92:95]
	v_mfma_f32_16x16x32_bf16 v[88:91], v[172:175], v[200:203], v[88:91]
	v_mfma_f32_16x16x32_bf16 v[76:79], v[164:167], v[208:211], v[76:79]
	v_mfma_f32_16x16x32_bf16 v[72:75], v[172:175], v[208:211], v[72:75]
	s_setprio 0
	s_barrier
	s_add_i32 s52, 0, 0x1c000
	s_add_i32 s22, s86, s74
	v_add_u32_e32 v224, s52, v149
	v_lshl_add_u64 v[228:229], v[228:229], 0, s[40:41]
	s_mov_b32 m0, s22
	ds_read_b128 v[212:215], v224
	ds_read_b128 v[216:219], v224 offset:1024
	ds_read_b128 v[220:223], v224 offset:2048
	ds_read_b128 v[224:227], v224 offset:3072
	global_load_lds_dwordx4 v[228:229], off
	v_lshl_add_u64 v[228:229], v[230:231], 0, s[40:41]
	s_add_i32 m0, s22, 0x2000
	s_nop 0
	global_load_lds_dwordx4 v[228:229], off
	s_barrier
	s_waitcnt lgkmcnt(0)
	s_setprio 1
	s_waitcnt lgkmcnt(0)
	v_mfma_f32_16x16x32_bf16 v[116:119], v[212:215], v[176:179], v[116:119]
	v_mfma_f32_16x16x32_bf16 v[112:115], v[220:223], v[176:179], v[112:115]
	v_mfma_f32_16x16x32_bf16 v[100:103], v[212:215], v[184:187], v[100:103]
	v_mfma_f32_16x16x32_bf16 v[96:99], v[220:223], v[184:187], v[96:99]
	v_mfma_f32_16x16x32_bf16 v[84:87], v[212:215], v[192:195], v[84:87]
	v_mfma_f32_16x16x32_bf16 v[80:83], v[220:223], v[192:195], v[80:83]
	v_mfma_f32_16x16x32_bf16 v[68:71], v[212:215], v[204:207], v[68:71]
	v_mfma_f32_16x16x32_bf16 v[64:67], v[220:223], v[204:207], v[64:67]
	v_mfma_f32_16x16x32_bf16 v[116:119], v[216:219], v[180:183], v[116:119]
	v_mfma_f32_16x16x32_bf16 v[112:115], v[224:227], v[180:183], v[112:115]
	v_mfma_f32_16x16x32_bf16 v[100:103], v[216:219], v[188:191], v[100:103]
	v_mfma_f32_16x16x32_bf16 v[96:99], v[224:227], v[188:191], v[96:99]
	v_mfma_f32_16x16x32_bf16 v[84:87], v[216:219], v[200:203], v[84:87]
	v_mfma_f32_16x16x32_bf16 v[80:83], v[224:227], v[200:203], v[80:83]
	v_mfma_f32_16x16x32_bf16 v[68:71], v[216:219], v[208:211], v[68:71]
	v_mfma_f32_16x16x32_bf16 v[64:67], v[224:227], v[208:211], v[64:67]
	s_setprio 0
	s_mov_b32 m0, s79
	v_lshl_add_u64 v[228:229], v[232:233], 0, s[40:41]
	s_barrier
	ds_read_b128 v[176:179], v163 offset:49152
	ds_read_b128 v[180:183], v163 offset:50176
	ds_read_b128 v[184:187], v163 offset:51200
	ds_read_b128 v[188:191], v163 offset:52224
	ds_read_b128 v[192:195], v163 offset:53248
	ds_read_b128 v[200:203], v163 offset:54272
	ds_read_b128 v[204:207], v163 offset:55296
	ds_read_b128 v[208:211], v163 offset:56320
	global_load_lds_dwordx4 v[228:229], off
	v_lshl_add_u64 v[228:229], v[234:235], 0, s[40:41]
	s_mov_b32 m0, s80
	s_nop 0
	global_load_lds_dwordx4 v[228:229], off
	s_barrier
	s_waitcnt lgkmcnt(0)
	s_setprio 1
	s_waitcnt lgkmcnt(0)
	v_mfma_f32_16x16x32_bf16 v[60:63], v[144:147], v[176:179], v[60:63]
	v_mfma_f32_16x16x32_bf16 v[56:59], v[168:171], v[176:179], v[56:59]
	v_mfma_f32_16x16x32_bf16 v[44:47], v[144:147], v[184:187], v[44:47]
	v_mfma_f32_16x16x32_bf16 v[40:43], v[168:171], v[184:187], v[40:43]
	v_mfma_f32_16x16x32_bf16 v[28:31], v[144:147], v[192:195], v[28:31]
	v_mfma_f32_16x16x32_bf16 v[24:27], v[168:171], v[192:195], v[24:27]
	v_mfma_f32_16x16x32_bf16 v[12:15], v[144:147], v[204:207], v[12:15]
	v_mfma_f32_16x16x32_bf16 v[8:11], v[168:171], v[204:207], v[8:11]
	v_mfma_f32_16x16x32_bf16 v[60:63], v[164:167], v[180:183], v[60:63]
	v_mfma_f32_16x16x32_bf16 v[56:59], v[172:175], v[180:183], v[56:59]
	v_mfma_f32_16x16x32_bf16 v[44:47], v[164:167], v[188:191], v[44:47]
	v_mfma_f32_16x16x32_bf16 v[40:43], v[172:175], v[188:191], v[40:43]
	v_mfma_f32_16x16x32_bf16 v[28:31], v[164:167], v[200:203], v[28:31]
	v_mfma_f32_16x16x32_bf16 v[24:27], v[172:175], v[200:203], v[24:27]
	v_mfma_f32_16x16x32_bf16 v[12:15], v[164:167], v[208:211], v[12:15]
	v_mfma_f32_16x16x32_bf16 v[8:11], v[172:175], v[208:211], v[8:11]
	s_setprio 0
	s_barrier
	s_add_u32 s22, s50, 0x100080
	s_addc_u32 s23, s51, 0
	s_add_i32 s50, s52, s74
	v_lshl_add_u64 v[144:145], s[22:23], 0, v[138:139]
	s_mov_b32 m0, s50
	s_nop 0
	global_load_lds_dwordx4 v[144:145], off
	v_lshl_add_u64 v[144:145], s[22:23], 0, v[134:135]
	s_add_i32 m0, s50, 0x2000
	s_nop 0
	global_load_lds_dwordx4 v[144:145], off
	s_waitcnt vmcnt(6)
	s_barrier
	s_setprio 1
	v_mfma_f32_16x16x32_bf16 v[52:55], v[212:215], v[176:179], v[52:55]
	v_mfma_f32_16x16x32_bf16 v[48:51], v[220:223], v[176:179], v[48:51]
	v_mfma_f32_16x16x32_bf16 v[36:39], v[212:215], v[184:187], v[36:39]
	v_mfma_f32_16x16x32_bf16 v[32:35], v[220:223], v[184:187], v[32:35]
	v_mfma_f32_16x16x32_bf16 v[20:23], v[212:215], v[192:195], v[20:23]
	v_mfma_f32_16x16x32_bf16 v[16:19], v[220:223], v[192:195], v[16:19]
	v_mfma_f32_16x16x32_bf16 v[4:7], v[212:215], v[204:207], v[4:7]
	v_mfma_f32_16x16x32_bf16 v[0:3], v[220:223], v[204:207], v[0:3]
	v_mfma_f32_16x16x32_bf16 v[52:55], v[216:219], v[180:183], v[52:55]
	v_mfma_f32_16x16x32_bf16 v[48:51], v[224:227], v[180:183], v[48:51]
	v_mfma_f32_16x16x32_bf16 v[36:39], v[216:219], v[188:191], v[36:39]
	v_mfma_f32_16x16x32_bf16 v[32:35], v[224:227], v[188:191], v[32:35]
	v_mfma_f32_16x16x32_bf16 v[20:23], v[216:219], v[200:203], v[20:23]
	v_mfma_f32_16x16x32_bf16 v[16:19], v[224:227], v[200:203], v[16:19]
	v_mfma_f32_16x16x32_bf16 v[4:7], v[216:219], v[208:211], v[4:7]
	v_mfma_f32_16x16x32_bf16 v[0:3], v[224:227], v[208:211], v[0:3]
	s_setprio 0
	s_add_i32 s60, s60, 2
	s_add_u32 s48, s48, 0x100
	s_addc_u32 s49, s49, 0
	s_add_u32 s18, s18, 0x100
	s_addc_u32 s19, s19, 0
	s_cmp_gt_u32 s60, 61
	s_barrier
	s_cbranch_scc0 .LBB0_470
	v_add_u32_e32 v144, s33, v148
	v_ashrrev_i32_e32 v145, 31, v144
	v_readlane_b32 s18, v254, 56
	v_add_u32_e32 v146, s83, v150
	v_lshlrev_b64 v[164:165], 11, v[144:145]
	v_readlane_b32 s19, v254, 57
	v_ashrrev_i32_e32 v147, 31, v146
	s_nop 0
	v_lshl_add_u64 v[164:165], s[18:19], 0, v[164:165]
	v_lshl_add_u64 v[146:147], v[146:147], 1, v[164:165]
	global_load_dwordx4 v[164:167], v[146:147], off
	global_load_dwordx4 v[172:175], v[146:147], off offset:256
	s_mov_b32 s98, 0x8000
	s_mov_b32 s99, 0
	v_lshl_add_u64 v[236:237], v[146:147], 0, s[98:99]
	global_load_dwordx4 v[176:179], v[236:237], off
	s_mov_b64 s[98:99], 0x8000
	v_lshl_add_u64 v[236:237], v[146:147], 0, s[98:99]
	global_load_dwordx4 v[180:183], v[236:237], off offset:256
	s_mov_b32 s98, 0x10000
	s_mov_b32 s99, 0
	v_lshl_add_u64 v[236:237], v[146:147], 0, s[98:99]
	global_load_dwordx4 v[184:187], v[236:237], off
	s_mov_b64 s[98:99], 0x10000
	v_lshl_add_u64 v[236:237], v[146:147], 0, s[98:99]
	global_load_dwordx4 v[188:191], v[236:237], off offset:256
	s_mov_b32 s98, 0x18000
	s_mov_b32 s99, 0
	v_lshl_add_u64 v[236:237], v[146:147], 0, s[98:99]
	global_load_dwordx4 v[192:195], v[236:237], off
	s_mov_b64 s[98:99], 0x18000
	v_lshl_add_u64 v[236:237], v[146:147], 0, s[98:99]
	global_load_dwordx4 v[200:203], v[236:237], off offset:256
	s_mov_b32 s98, 0x40000
	s_mov_b32 s99, 0
	v_lshl_add_u64 v[236:237], v[146:147], 0, s[98:99]
	global_load_dwordx4 v[204:207], v[236:237], off
	s_mov_b64 s[98:99], 0x40000
	v_lshl_add_u64 v[236:237], v[146:147], 0, s[98:99]
	global_load_dwordx4 v[208:211], v[236:237], off offset:256
	s_mov_b32 s98, 0x48000
	s_mov_b32 s99, 0
	v_lshl_add_u64 v[236:237], v[146:147], 0, s[98:99]
	global_load_dwordx4 v[212:215], v[236:237], off
	s_mov_b64 s[98:99], 0x48000
	v_lshl_add_u64 v[236:237], v[146:147], 0, s[98:99]
	global_load_dwordx4 v[216:219], v[236:237], off offset:256
	s_mov_b32 s98, 0x50000
	s_mov_b32 s99, 0
	v_lshl_add_u64 v[236:237], v[146:147], 0, s[98:99]
	global_load_dwordx4 v[220:223], v[236:237], off
	s_mov_b64 s[98:99], 0x50000
	v_lshl_add_u64 v[236:237], v[146:147], 0, s[98:99]
	global_load_dwordx4 v[224:227], v[236:237], off offset:256
	s_mov_b32 s98, 0x58000
	s_mov_b32 s99, 0
	v_lshl_add_u64 v[236:237], v[146:147], 0, s[98:99]
	global_load_dwordx4 v[228:231], v[236:237], off
	s_mov_b64 s[98:99], 0x58000
	v_lshl_add_u64 v[236:237], v[146:147], 0, s[98:99]
	global_load_dwordx4 v[232:235], v[236:237], off offset:256
	s_mov_b64 s[18:19], 0x8000
	s_waitcnt vmcnt(15)
	v_lshlrev_b32_e32 v168, 16, v164
	v_and_b32_e32 v169, 0xffff0000, v164
	v_lshlrev_b32_e32 v164, 16, v165
	v_and_b32_e32 v165, 0xffff0000, v165
	v_lshlrev_b32_e32 v170, 16, v166
	v_and_b32_e32 v171, 0xffff0000, v166
	v_lshlrev_b32_e32 v166, 16, v167
	v_and_b32_e32 v167, 0xffff0000, v167
	v_pk_add_f32 v[126:127], v[126:127], v[164:165]
	v_pk_add_f32 v[124:125], v[124:125], v[168:169]
	v_pk_add_f32 v[164:165], v[122:123], v[166:167]
	v_pk_add_f32 v[166:167], v[120:121], v[170:171]
	v_cvt_pk_bf16_f32 v120, v124, v125
	v_cvt_pk_bf16_f32 v121, v126, v127
	v_cvt_pk_bf16_f32 v123, v164, v165
	v_mul_f32_e32 v168, v125, v125
	v_cvt_pk_bf16_f32 v122, v166, v167
	global_store_dwordx4 v[146:147], v[120:123], off
	v_fmac_f32_e32 v168, v124, v124
	v_fmac_f32_e32 v168, v126, v126
	v_fmac_f32_e32 v168, v127, v127
	v_fmac_f32_e32 v168, v166, v166
	v_fmac_f32_e32 v168, v167, v167
	v_fmac_f32_e32 v168, v164, v164
	v_fmac_f32_e32 v168, v165, v165
	s_waitcnt vmcnt(15)
	s_nop 1
	v_mov_b32_e32 v120, v172
	v_mov_b32_e32 v121, v173
	v_mov_b32_e32 v122, v174
	v_mov_b32_e32 v123, v175
	v_lshlrev_b32_e32 v124, 16, v120
	v_and_b32_e32 v125, 0xffff0000, v120
	v_lshlrev_b32_e32 v120, 16, v121
	v_and_b32_e32 v121, 0xffff0000, v121
	v_lshlrev_b32_e32 v126, 16, v122
	v_and_b32_e32 v127, 0xffff0000, v122
	v_lshlrev_b32_e32 v122, 16, v123
	v_and_b32_e32 v123, 0xffff0000, v123
	v_pk_add_f32 v[118:119], v[118:119], v[120:121]
	v_pk_add_f32 v[116:117], v[116:117], v[124:125]
	v_pk_add_f32 v[120:121], v[114:115], v[122:123]
	v_pk_add_f32 v[122:123], v[112:113], v[126:127]
	v_cvt_pk_bf16_f32 v112, v116, v117
	v_cvt_pk_bf16_f32 v113, v118, v119
	v_cvt_pk_bf16_f32 v115, v120, v121
	s_nop 0
	v_cvt_pk_bf16_f32 v114, v122, v123
	global_store_dwordx4 v[146:147], v[112:115], off offset:256
	s_nop 1
	v_mul_f32_e32 v112, v117, v117
	v_fmac_f32_e32 v112, v116, v116
	v_fmac_f32_e32 v112, v118, v118
	v_fmac_f32_e32 v112, v119, v119
	v_fmac_f32_e32 v112, v122, v122
	v_fmac_f32_e32 v112, v123, v123
	v_lshl_add_u64 v[118:119], v[146:147], 0, s[18:19]
	s_mov_b32 s18, 0x8000
	v_fmac_f32_e32 v112, v120, v120
	v_add_co_u32_e32 v120, vcc, s18, v146
	v_fmac_f32_e32 v112, v121, v121
	s_nop 0
	v_addc_co_u32_e32 v121, vcc, 0, v147, vcc
	s_mov_b64 s[18:19], 0x10000
	v_add_f32_e32 v112, v168, v112
	s_waitcnt vmcnt(15)
	s_nop 1
	v_mov_b32_e32 v114, v176
	v_mov_b32_e32 v115, v177
	v_mov_b32_e32 v116, v178
	v_mov_b32_e32 v117, v179
	v_lshlrev_b32_e32 v122, 16, v114
	v_and_b32_e32 v123, 0xffff0000, v114
	v_lshlrev_b32_e32 v114, 16, v115
	v_and_b32_e32 v115, 0xffff0000, v115
	v_lshlrev_b32_e32 v124, 16, v116
	v_and_b32_e32 v125, 0xffff0000, v116
	v_lshlrev_b32_e32 v116, 16, v117
	v_and_b32_e32 v117, 0xffff0000, v117
	v_pk_add_f32 v[110:111], v[110:111], v[114:115]
	v_pk_add_f32 v[108:109], v[108:109], v[122:123]
	v_pk_add_f32 v[114:115], v[106:107], v[116:117]
	v_pk_add_f32 v[116:117], v[104:105], v[124:125]
	v_cvt_pk_bf16_f32 v104, v108, v109
	v_cvt_pk_bf16_f32 v105, v110, v111
	v_cvt_pk_bf16_f32 v107, v114, v115
	v_mul_f32_e32 v113, v109, v109
	v_cvt_pk_bf16_f32 v106, v116, v117
	global_store_dwordx4 v[120:121], v[104:107], off
	v_fmac_f32_e32 v113, v108, v108
	v_fmac_f32_e32 v113, v110, v110
	v_fmac_f32_e32 v113, v111, v111
	v_fmac_f32_e32 v113, v116, v116
	v_fmac_f32_e32 v113, v117, v117
	v_fmac_f32_e32 v113, v114, v114
	v_fmac_f32_e32 v113, v115, v115
	s_waitcnt vmcnt(15)
	s_nop 1
	v_mov_b32_e32 v104, v180
	v_mov_b32_e32 v105, v181
	v_mov_b32_e32 v106, v182
	v_mov_b32_e32 v107, v183
	v_lshlrev_b32_e32 v108, 16, v104
	v_and_b32_e32 v109, 0xffff0000, v104
	v_lshlrev_b32_e32 v104, 16, v105
	v_and_b32_e32 v105, 0xffff0000, v105
	v_lshlrev_b32_e32 v110, 16, v106
	v_and_b32_e32 v111, 0xffff0000, v106
	v_lshlrev_b32_e32 v106, 16, v107
	v_and_b32_e32 v107, 0xffff0000, v107
	v_pk_add_f32 v[102:103], v[102:103], v[104:105]
	v_pk_add_f32 v[100:101], v[100:101], v[108:109]
	v_pk_add_f32 v[104:105], v[98:99], v[106:107]
	v_pk_add_f32 v[106:107], v[96:97], v[110:111]
	v_cvt_pk_bf16_f32 v96, v100, v101
	v_cvt_pk_bf16_f32 v97, v102, v103
	v_cvt_pk_bf16_f32 v99, v104, v105
	s_nop 0
	v_cvt_pk_bf16_f32 v98, v106, v107
	global_store_dwordx4 v[118:119], v[96:99], off offset:256
	s_nop 1
	v_mul_f32_e32 v96, v101, v101
	v_fmac_f32_e32 v96, v100, v100
	v_fmac_f32_e32 v96, v102, v102
	v_fmac_f32_e32 v96, v103, v103
	v_fmac_f32_e32 v96, v106, v106
	v_fmac_f32_e32 v96, v107, v107
	v_fmac_f32_e32 v96, v104, v104
	v_fmac_f32_e32 v96, v105, v105
	v_add_f32_e32 v98, v113, v96
	v_lshl_add_u64 v[96:97], v[146:147], 0, s[18:19]
	s_mov_b32 s18, 0x10000
	v_add_co_u32_e32 v104, vcc, s18, v146
	s_mov_b64 s[18:19], 0x18000
	s_nop 0
	v_addc_co_u32_e32 v105, vcc, 0, v147, vcc
	s_waitcnt vmcnt(15)
	s_nop 1
	v_mov_b32_e32 v100, v184
	v_mov_b32_e32 v101, v185
	v_mov_b32_e32 v102, v186
	v_mov_b32_e32 v103, v187
	v_lshlrev_b32_e32 v106, 16, v100
	v_and_b32_e32 v107, 0xffff0000, v100
	v_lshlrev_b32_e32 v100, 16, v101
	v_and_b32_e32 v101, 0xffff0000, v101
	v_lshlrev_b32_e32 v108, 16, v102
	v_and_b32_e32 v109, 0xffff0000, v102
	v_lshlrev_b32_e32 v102, 16, v103
	v_and_b32_e32 v103, 0xffff0000, v103
	v_pk_add_f32 v[94:95], v[94:95], v[100:101]
	v_pk_add_f32 v[92:93], v[92:93], v[106:107]
	v_pk_add_f32 v[100:101], v[90:91], v[102:103]
	v_pk_add_f32 v[102:103], v[88:89], v[108:109]
	v_cvt_pk_bf16_f32 v88, v92, v93
	v_cvt_pk_bf16_f32 v89, v94, v95
	v_cvt_pk_bf16_f32 v91, v100, v101
	v_mul_f32_e32 v99, v93, v93
	v_cvt_pk_bf16_f32 v90, v102, v103
	global_store_dwordx4 v[104:105], v[88:91], off
	v_fmac_f32_e32 v99, v92, v92
	v_fmac_f32_e32 v99, v94, v94
	v_fmac_f32_e32 v99, v95, v95
	v_fmac_f32_e32 v99, v102, v102
	v_fmac_f32_e32 v99, v103, v103
	v_fmac_f32_e32 v99, v100, v100
	v_fmac_f32_e32 v99, v101, v101
	s_waitcnt vmcnt(15)
	s_nop 1
	v_mov_b32_e32 v88, v188
	v_mov_b32_e32 v89, v189
	v_mov_b32_e32 v90, v190
	v_mov_b32_e32 v91, v191
	v_lshlrev_b32_e32 v92, 16, v88
	v_and_b32_e32 v93, 0xffff0000, v88
	v_lshlrev_b32_e32 v88, 16, v89
	v_and_b32_e32 v89, 0xffff0000, v89
	v_lshlrev_b32_e32 v94, 16, v90
	v_and_b32_e32 v95, 0xffff0000, v90
	v_lshlrev_b32_e32 v90, 16, v91
	v_and_b32_e32 v91, 0xffff0000, v91
	v_pk_add_f32 v[86:87], v[86:87], v[88:89]
	v_pk_add_f32 v[84:85], v[84:85], v[92:93]
	v_pk_add_f32 v[88:89], v[82:83], v[90:91]
	v_pk_add_f32 v[90:91], v[80:81], v[94:95]
	v_cvt_pk_bf16_f32 v80, v84, v85
	v_cvt_pk_bf16_f32 v81, v86, v87
	v_cvt_pk_bf16_f32 v83, v88, v89
	s_nop 0
	v_cvt_pk_bf16_f32 v82, v90, v91
	global_store_dwordx4 v[96:97], v[80:83], off offset:256
	s_nop 1
	v_mul_f32_e32 v80, v85, v85
	v_fmac_f32_e32 v80, v84, v84
	v_fmac_f32_e32 v80, v86, v86
	v_fmac_f32_e32 v80, v87, v87
	v_fmac_f32_e32 v80, v90, v90
	v_fmac_f32_e32 v80, v91, v91
	v_fmac_f32_e32 v80, v88, v88
	v_fmac_f32_e32 v80, v89, v89
	v_add_f32_e32 v82, v99, v80
	v_lshl_add_u64 v[80:81], v[146:147], 0, s[18:19]
	s_mov_b32 s18, 0x18000
	v_add_co_u32_e32 v88, vcc, s18, v146
	s_mov_b64 s[18:19], 0x40000
	s_nop 0
	v_addc_co_u32_e32 v89, vcc, 0, v147, vcc
	s_waitcnt vmcnt(15)
	s_nop 1
	v_mov_b32_e32 v84, v192
	v_mov_b32_e32 v85, v193
	v_mov_b32_e32 v86, v194
	v_mov_b32_e32 v87, v195
	v_lshlrev_b32_e32 v90, 16, v84
	v_and_b32_e32 v91, 0xffff0000, v84
	v_lshlrev_b32_e32 v84, 16, v85
	v_and_b32_e32 v85, 0xffff0000, v85
	v_lshlrev_b32_e32 v92, 16, v86
	v_and_b32_e32 v93, 0xffff0000, v86
	v_lshlrev_b32_e32 v86, 16, v87
	v_and_b32_e32 v87, 0xffff0000, v87
	v_pk_add_f32 v[78:79], v[78:79], v[84:85]
	v_pk_add_f32 v[76:77], v[76:77], v[90:91]
	v_pk_add_f32 v[84:85], v[74:75], v[86:87]
	v_pk_add_f32 v[86:87], v[72:73], v[92:93]
	v_cvt_pk_bf16_f32 v72, v76, v77
	v_cvt_pk_bf16_f32 v73, v78, v79
	v_cvt_pk_bf16_f32 v75, v84, v85
	v_mul_f32_e32 v83, v77, v77
	v_cvt_pk_bf16_f32 v74, v86, v87
	global_store_dwordx4 v[88:89], v[72:75], off
	v_fmac_f32_e32 v83, v76, v76
	v_fmac_f32_e32 v83, v78, v78
	v_fmac_f32_e32 v83, v79, v79
	v_fmac_f32_e32 v83, v86, v86
	v_fmac_f32_e32 v83, v87, v87
	v_fmac_f32_e32 v83, v84, v84
	v_fmac_f32_e32 v83, v85, v85
	s_waitcnt vmcnt(15)
	s_nop 1
	v_mov_b32_e32 v72, v200
	v_mov_b32_e32 v73, v201
	v_mov_b32_e32 v74, v202
	v_mov_b32_e32 v75, v203
	v_lshlrev_b32_e32 v76, 16, v72
	v_and_b32_e32 v77, 0xffff0000, v72
	v_lshlrev_b32_e32 v72, 16, v73
	v_and_b32_e32 v73, 0xffff0000, v73
	v_lshlrev_b32_e32 v78, 16, v74
	v_and_b32_e32 v79, 0xffff0000, v74
	v_lshlrev_b32_e32 v74, 16, v75
	v_and_b32_e32 v75, 0xffff0000, v75
	v_pk_add_f32 v[70:71], v[70:71], v[72:73]
	v_pk_add_f32 v[68:69], v[68:69], v[76:77]
	v_pk_add_f32 v[72:73], v[66:67], v[74:75]
	v_pk_add_f32 v[74:75], v[64:65], v[78:79]
	v_cvt_pk_bf16_f32 v64, v68, v69
	v_cvt_pk_bf16_f32 v65, v70, v71
	v_cvt_pk_bf16_f32 v67, v72, v73
	s_nop 0
	v_cvt_pk_bf16_f32 v66, v74, v75
	global_store_dwordx4 v[80:81], v[64:67], off offset:256
	s_nop 1
	v_mul_f32_e32 v64, v69, v69
	v_fmac_f32_e32 v64, v68, v68
	v_fmac_f32_e32 v64, v70, v70
	v_fmac_f32_e32 v64, v71, v71
	v_fmac_f32_e32 v64, v74, v74
	v_fmac_f32_e32 v64, v75, v75
	v_fmac_f32_e32 v64, v72, v72
	v_fmac_f32_e32 v64, v73, v73
	v_add_f32_e32 v66, v83, v64
	v_lshl_add_u64 v[64:65], v[146:147], 0, s[18:19]
	s_mov_b32 s18, 0x40000
	v_add_co_u32_e32 v72, vcc, s18, v146
	s_mov_b64 s[18:19], 0x48000
	s_nop 0
	v_addc_co_u32_e32 v73, vcc, 0, v147, vcc
	s_waitcnt vmcnt(15)
	s_nop 1
	v_mov_b32_e32 v68, v204
	v_mov_b32_e32 v69, v205
	v_mov_b32_e32 v70, v206
	v_mov_b32_e32 v71, v207
	v_lshlrev_b32_e32 v74, 16, v68
	v_and_b32_e32 v75, 0xffff0000, v68
	v_lshlrev_b32_e32 v68, 16, v69
	v_and_b32_e32 v69, 0xffff0000, v69
	v_lshlrev_b32_e32 v76, 16, v70
	v_and_b32_e32 v77, 0xffff0000, v70
	v_lshlrev_b32_e32 v70, 16, v71
	v_and_b32_e32 v71, 0xffff0000, v71
	v_pk_add_f32 v[62:63], v[62:63], v[68:69]
	v_pk_add_f32 v[60:61], v[60:61], v[74:75]
	v_pk_add_f32 v[68:69], v[58:59], v[70:71]
	v_pk_add_f32 v[70:71], v[56:57], v[76:77]
	v_cvt_pk_bf16_f32 v56, v60, v61
	v_cvt_pk_bf16_f32 v57, v62, v63
	v_cvt_pk_bf16_f32 v59, v68, v69
	v_mul_f32_e32 v67, v61, v61
	v_cvt_pk_bf16_f32 v58, v70, v71
	global_store_dwordx4 v[72:73], v[56:59], off
	v_fmac_f32_e32 v67, v60, v60
	v_fmac_f32_e32 v67, v62, v62
	v_fmac_f32_e32 v67, v63, v63
	v_fmac_f32_e32 v67, v70, v70
	v_fmac_f32_e32 v67, v71, v71
	v_fmac_f32_e32 v67, v68, v68
	v_fmac_f32_e32 v67, v69, v69
	s_waitcnt vmcnt(15)
	s_nop 1
	v_mov_b32_e32 v56, v208
	v_mov_b32_e32 v57, v209
	v_mov_b32_e32 v58, v210
	v_mov_b32_e32 v59, v211
	v_lshlrev_b32_e32 v60, 16, v56
	v_and_b32_e32 v61, 0xffff0000, v56
	v_lshlrev_b32_e32 v56, 16, v57
	v_and_b32_e32 v57, 0xffff0000, v57
	v_lshlrev_b32_e32 v62, 16, v58
	v_and_b32_e32 v63, 0xffff0000, v58
	v_lshlrev_b32_e32 v58, 16, v59
	v_and_b32_e32 v59, 0xffff0000, v59
	v_pk_add_f32 v[54:55], v[54:55], v[56:57]
	v_pk_add_f32 v[52:53], v[52:53], v[60:61]
	v_pk_add_f32 v[56:57], v[50:51], v[58:59]
	v_pk_add_f32 v[58:59], v[48:49], v[62:63]
	v_cvt_pk_bf16_f32 v48, v52, v53
	v_cvt_pk_bf16_f32 v49, v54, v55
	v_cvt_pk_bf16_f32 v51, v56, v57
	s_nop 0
	v_cvt_pk_bf16_f32 v50, v58, v59
	global_store_dwordx4 v[64:65], v[48:51], off offset:256
	s_nop 1
	v_mul_f32_e32 v48, v53, v53
	v_fmac_f32_e32 v48, v52, v52
	v_fmac_f32_e32 v48, v54, v54
	v_fmac_f32_e32 v48, v55, v55
	v_fmac_f32_e32 v48, v58, v58
	v_fmac_f32_e32 v48, v59, v59
	v_fmac_f32_e32 v48, v56, v56
	v_fmac_f32_e32 v48, v57, v57
	v_add_f32_e32 v50, v67, v48
	v_lshl_add_u64 v[48:49], v[146:147], 0, s[18:19]
	s_mov_b32 s18, 0x48000
	v_add_co_u32_e32 v56, vcc, s18, v146
	s_mov_b64 s[18:19], 0x50000
	s_nop 0
	v_addc_co_u32_e32 v57, vcc, 0, v147, vcc
	s_waitcnt vmcnt(15)
	s_nop 1
	v_mov_b32_e32 v52, v212
	v_mov_b32_e32 v53, v213
	v_mov_b32_e32 v54, v214
	v_mov_b32_e32 v55, v215
	v_lshlrev_b32_e32 v58, 16, v52
	v_and_b32_e32 v59, 0xffff0000, v52
	v_lshlrev_b32_e32 v52, 16, v53
	v_and_b32_e32 v53, 0xffff0000, v53
	v_lshlrev_b32_e32 v60, 16, v54
	v_and_b32_e32 v61, 0xffff0000, v54
	v_lshlrev_b32_e32 v54, 16, v55
	v_and_b32_e32 v55, 0xffff0000, v55
	v_pk_add_f32 v[46:47], v[46:47], v[52:53]
	v_pk_add_f32 v[44:45], v[44:45], v[58:59]
	v_pk_add_f32 v[52:53], v[42:43], v[54:55]
	v_pk_add_f32 v[54:55], v[40:41], v[60:61]
	v_cvt_pk_bf16_f32 v40, v44, v45
	v_cvt_pk_bf16_f32 v41, v46, v47
	v_cvt_pk_bf16_f32 v43, v52, v53
	v_mul_f32_e32 v51, v45, v45
	v_cvt_pk_bf16_f32 v42, v54, v55
	global_store_dwordx4 v[56:57], v[40:43], off
	v_fmac_f32_e32 v51, v44, v44
	v_fmac_f32_e32 v51, v46, v46
	v_fmac_f32_e32 v51, v47, v47
	v_fmac_f32_e32 v51, v54, v54
	v_fmac_f32_e32 v51, v55, v55
	v_fmac_f32_e32 v51, v52, v52
	v_fmac_f32_e32 v51, v53, v53
	s_waitcnt vmcnt(15)
	s_nop 1
	v_mov_b32_e32 v40, v216
	v_mov_b32_e32 v41, v217
	v_mov_b32_e32 v42, v218
	v_mov_b32_e32 v43, v219
	v_lshlrev_b32_e32 v44, 16, v40
	v_and_b32_e32 v45, 0xffff0000, v40
	v_lshlrev_b32_e32 v40, 16, v41
	v_and_b32_e32 v41, 0xffff0000, v41
	v_lshlrev_b32_e32 v46, 16, v42
	v_and_b32_e32 v47, 0xffff0000, v42
	v_lshlrev_b32_e32 v42, 16, v43
	v_and_b32_e32 v43, 0xffff0000, v43
	v_pk_add_f32 v[38:39], v[38:39], v[40:41]
	v_pk_add_f32 v[36:37], v[36:37], v[44:45]
	v_pk_add_f32 v[40:41], v[34:35], v[42:43]
	v_pk_add_f32 v[42:43], v[32:33], v[46:47]
	v_cvt_pk_bf16_f32 v32, v36, v37
	v_cvt_pk_bf16_f32 v33, v38, v39
	v_cvt_pk_bf16_f32 v35, v40, v41
	s_nop 0
	v_cvt_pk_bf16_f32 v34, v42, v43
	global_store_dwordx4 v[48:49], v[32:35], off offset:256
	s_nop 1
	v_mul_f32_e32 v32, v37, v37
	v_fmac_f32_e32 v32, v36, v36
	v_fmac_f32_e32 v32, v38, v38
	v_fmac_f32_e32 v32, v39, v39
	v_fmac_f32_e32 v32, v42, v42
	v_fmac_f32_e32 v32, v43, v43
	v_fmac_f32_e32 v32, v40, v40
	v_fmac_f32_e32 v32, v41, v41
	v_add_f32_e32 v34, v51, v32
	v_lshl_add_u64 v[32:33], v[146:147], 0, s[18:19]
	s_mov_b32 s18, 0x50000
	v_add_co_u32_e32 v40, vcc, s18, v146
	s_mov_b64 s[18:19], 0x58000
	s_nop 0
	v_addc_co_u32_e32 v41, vcc, 0, v147, vcc
	s_waitcnt vmcnt(15)
	s_nop 1
	v_mov_b32_e32 v36, v220
	v_mov_b32_e32 v37, v221
	v_mov_b32_e32 v38, v222
	v_mov_b32_e32 v39, v223
	v_lshlrev_b32_e32 v42, 16, v36
	v_and_b32_e32 v43, 0xffff0000, v36
	v_lshlrev_b32_e32 v36, 16, v37
	v_and_b32_e32 v37, 0xffff0000, v37
	v_lshlrev_b32_e32 v44, 16, v38
	v_and_b32_e32 v45, 0xffff0000, v38
	v_lshlrev_b32_e32 v38, 16, v39
	v_and_b32_e32 v39, 0xffff0000, v39
	v_pk_add_f32 v[30:31], v[30:31], v[36:37]
	v_pk_add_f32 v[28:29], v[28:29], v[42:43]
	v_pk_add_f32 v[36:37], v[26:27], v[38:39]
	v_pk_add_f32 v[38:39], v[24:25], v[44:45]
	v_cvt_pk_bf16_f32 v24, v28, v29
	v_cvt_pk_bf16_f32 v25, v30, v31
	v_cvt_pk_bf16_f32 v27, v36, v37
	v_mul_f32_e32 v35, v29, v29
	v_cvt_pk_bf16_f32 v26, v38, v39
	global_store_dwordx4 v[40:41], v[24:27], off
	v_fmac_f32_e32 v35, v28, v28
	v_fmac_f32_e32 v35, v30, v30
	v_fmac_f32_e32 v35, v31, v31
	v_fmac_f32_e32 v35, v38, v38
	v_fmac_f32_e32 v35, v39, v39
	v_fmac_f32_e32 v35, v36, v36
	v_fmac_f32_e32 v35, v37, v37
	s_waitcnt vmcnt(15)
	s_nop 1
	v_mov_b32_e32 v24, v224
	v_mov_b32_e32 v25, v225
	v_mov_b32_e32 v26, v226
	v_mov_b32_e32 v27, v227
	v_lshlrev_b32_e32 v28, 16, v24
	v_and_b32_e32 v29, 0xffff0000, v24
	v_lshlrev_b32_e32 v24, 16, v25
	v_and_b32_e32 v25, 0xffff0000, v25
	v_lshlrev_b32_e32 v30, 16, v26
	v_and_b32_e32 v31, 0xffff0000, v26
	v_lshlrev_b32_e32 v26, 16, v27
	v_and_b32_e32 v27, 0xffff0000, v27
	v_pk_add_f32 v[22:23], v[22:23], v[24:25]
	v_pk_add_f32 v[20:21], v[20:21], v[28:29]
	v_pk_add_f32 v[24:25], v[18:19], v[26:27]
	v_pk_add_f32 v[26:27], v[16:17], v[30:31]
	v_cvt_pk_bf16_f32 v16, v20, v21
	v_cvt_pk_bf16_f32 v17, v22, v23
	v_cvt_pk_bf16_f32 v19, v24, v25
	s_nop 0
	v_cvt_pk_bf16_f32 v18, v26, v27
	global_store_dwordx4 v[32:33], v[16:19], off offset:256
	s_nop 1
	v_mul_f32_e32 v16, v21, v21
	v_fmac_f32_e32 v16, v20, v20
	v_fmac_f32_e32 v16, v22, v22
	v_fmac_f32_e32 v16, v23, v23
	v_fmac_f32_e32 v16, v26, v26
	v_fmac_f32_e32 v16, v27, v27
	v_fmac_f32_e32 v16, v24, v24
	v_fmac_f32_e32 v16, v25, v25
	v_add_f32_e32 v18, v35, v16
	v_lshl_add_u64 v[16:17], v[146:147], 0, s[18:19]
	s_mov_b32 s18, 0x58000
	v_add_co_u32_e32 v24, vcc, s18, v146
	s_nop 1
	v_addc_co_u32_e32 v25, vcc, 0, v147, vcc
	s_waitcnt vmcnt(15)
	s_nop 1
	v_mov_b32_e32 v20, v228
	v_mov_b32_e32 v21, v229
	v_mov_b32_e32 v22, v230
	v_mov_b32_e32 v23, v231
	v_lshlrev_b32_e32 v26, 16, v20
	v_and_b32_e32 v27, 0xffff0000, v20
	v_lshlrev_b32_e32 v20, 16, v21
	v_and_b32_e32 v21, 0xffff0000, v21
	v_lshlrev_b32_e32 v28, 16, v22
	v_and_b32_e32 v29, 0xffff0000, v22
	v_lshlrev_b32_e32 v22, 16, v23
	v_and_b32_e32 v23, 0xffff0000, v23
	v_pk_add_f32 v[14:15], v[14:15], v[20:21]
	v_pk_add_f32 v[20:21], v[12:13], v[26:27]
	v_pk_add_f32 v[22:23], v[10:11], v[22:23]
	v_pk_add_f32 v[26:27], v[8:9], v[28:29]
	v_cvt_pk_bf16_f32 v8, v20, v21
	v_cvt_pk_bf16_f32 v9, v14, v15
	v_cvt_pk_bf16_f32 v11, v22, v23
	v_mul_f32_e32 v12, v21, v21
	v_cvt_pk_bf16_f32 v10, v26, v27
	global_store_dwordx4 v[24:25], v[8:11], off
	v_fmac_f32_e32 v12, v20, v20
	v_fmac_f32_e32 v12, v14, v14
	v_fmac_f32_e32 v12, v15, v15
	v_fmac_f32_e32 v12, v26, v26
	v_fmac_f32_e32 v12, v27, v27
	v_fmac_f32_e32 v12, v22, v22
	v_fmac_f32_e32 v12, v23, v23
	s_waitcnt vmcnt(15)
	s_nop 1
	v_mov_b32_e32 v8, v232
	v_mov_b32_e32 v9, v233
	v_mov_b32_e32 v10, v234
	v_mov_b32_e32 v11, v235
	v_lshlrev_b32_e32 v14, 16, v8
	v_and_b32_e32 v15, 0xffff0000, v8
	v_lshlrev_b32_e32 v8, 16, v9
	v_and_b32_e32 v9, 0xffff0000, v9
	v_lshlrev_b32_e32 v20, 16, v10
	v_and_b32_e32 v21, 0xffff0000, v10
	v_lshlrev_b32_e32 v10, 16, v11
	v_and_b32_e32 v11, 0xffff0000, v11
	v_pk_add_f32 v[6:7], v[6:7], v[8:9]
	v_pk_add_f32 v[4:5], v[4:5], v[14:15]
	v_pk_add_f32 v[8:9], v[2:3], v[10:11]
	v_pk_add_f32 v[10:11], v[0:1], v[20:21]
	v_cvt_pk_bf16_f32 v0, v4, v5
	v_cvt_pk_bf16_f32 v1, v6, v7
	v_cvt_pk_bf16_f32 v3, v8, v9
	s_nop 0
	v_cvt_pk_bf16_f32 v2, v10, v11
	global_store_dwordx4 v[16:17], v[0:3], off offset:256
	ds_bpermute_b32 v2, v151, v98
	s_nop 0
	v_mul_f32_e32 v0, v5, v5
	v_fmac_f32_e32 v0, v4, v4
	v_fmac_f32_e32 v0, v6, v6
	v_fmac_f32_e32 v0, v7, v7
	v_fmac_f32_e32 v0, v10, v10
	v_fmac_f32_e32 v0, v11, v11
	v_fmac_f32_e32 v0, v8, v8
	v_fmac_f32_e32 v0, v9, v9
	v_add_f32_e32 v14, v12, v0
	ds_bpermute_b32 v0, v151, v112
	ds_bpermute_b32 v4, v151, v82
	ds_bpermute_b32 v6, v151, v66
	ds_bpermute_b32 v8, v151, v50
	ds_bpermute_b32 v10, v151, v34
	ds_bpermute_b32 v12, v151, v18
	ds_bpermute_b32 v15, v151, v14
	s_waitcnt lgkmcnt(0)
	v_add_f32_e32 v0, v112, v0
	v_add_f32_e32 v2, v98, v2
	v_add_f32_e32 v4, v82, v4
	v_add_f32_e32 v6, v66, v6
	v_add_f32_e32 v8, v50, v8
	v_add_f32_e32 v10, v34, v10
	v_add_f32_e32 v12, v18, v12
	v_add_f32_e32 v14, v14, v15
	ds_bpermute_b32 v1, v152, v0
	ds_bpermute_b32 v3, v152, v2
	ds_bpermute_b32 v5, v152, v4
	ds_bpermute_b32 v7, v152, v6
	ds_bpermute_b32 v9, v152, v8
	ds_bpermute_b32 v11, v152, v10
	ds_bpermute_b32 v13, v152, v12
	ds_bpermute_b32 v15, v152, v14
	s_and_saveexec_b64 s[48:49], s[2:3]
	s_cbranch_execz .LBB0_473
	s_waitcnt lgkmcnt(6)
	v_add_f32_e32 v2, v2, v3
	v_add_f32_e32 v0, v0, v1
	v_add_u32_e32 v1, s82, v153
	s_waitcnt lgkmcnt(2)
	v_add_f32_e32 v10, v10, v11
	v_add_f32_e32 v8, v8, v9
	v_add_f32_e32 v6, v6, v7
	v_add_f32_e32 v4, v4, v5
	ds_write2st64_b32 v1, v0, v2 offset1:1
	ds_write2st64_b32 v1, v4, v6 offset0:2 offset1:3
	v_add_u32_e32 v0, s82, v157
	s_waitcnt lgkmcnt(2)
	v_add_f32_e32 v14, v14, v15
	v_add_f32_e32 v12, v12, v13
	ds_write2st64_b32 v0, v8, v10 offset1:1
	ds_write2st64_b32 v0, v12, v14 offset0:2 offset1:3

.LBB0_817:
	ds_read_b128 v[128:131], v179
	ds_read_b128 v[132:135], v179 offset:1024
	ds_read_b128 v[136:139], v179 offset:2048
	ds_read_b128 v[140:143], v179 offset:3072
	s_add_u32 s44, s42, 0xfffc0080
	s_addc_u32 s45, s43, -1
	s_cmp_eq_u32 s60, 12
	s_cselect_b32 s47, s39, s45
	s_cselect_b32 s46, s38, s44
	s_cselect_b32 s45, s41, s19
	s_cselect_b32 s44, s40, s18
	v_lshl_add_u64 v[194:195], s[42:43], 0, v[152:153]
	s_add_i32 m0, s52, 0xc000
	ds_read_b128 v[158:161], v180
	ds_read_b128 v[162:165], v180 offset:1024
	ds_read_b128 v[182:185], v180 offset:2048
	ds_read_b128 v[186:189], v180 offset:3072
	ds_read_b128 v[190:193], v180 offset:4096
	ds_read_b128 v[200:203], v180 offset:5120
	ds_read_b128 v[204:207], v180 offset:6144
	ds_read_b128 v[208:211], v180 offset:7168
	global_load_lds_dwordx4 v[194:195], off
	v_lshl_add_u64 v[194:195], s[42:43], 0, v[154:155]
	s_add_i32 m0, s52, 0xe000
	s_nop 0
	global_load_lds_dwordx4 v[194:195], off
	s_waitcnt lgkmcnt(8)
	s_barrier
	s_waitcnt lgkmcnt(0)
	s_setprio 1
	s_waitcnt lgkmcnt(0)
	v_mfma_f32_16x16x32_bf16 v[124:127], v[128:131], v[158:161], v[124:127]
	v_mfma_f32_16x16x32_bf16 v[120:123], v[136:139], v[158:161], v[120:123]
	v_mfma_f32_16x16x32_bf16 v[116:119], v[128:131], v[182:185], v[116:119]
	v_mfma_f32_16x16x32_bf16 v[108:111], v[136:139], v[182:185], v[108:111]
	v_mfma_f32_16x16x32_bf16 v[92:95], v[128:131], v[190:193], v[92:95]
	v_mfma_f32_16x16x32_bf16 v[88:91], v[136:139], v[190:193], v[88:91]
	v_mfma_f32_16x16x32_bf16 v[76:79], v[128:131], v[204:207], v[76:79]
	v_mfma_f32_16x16x32_bf16 v[72:75], v[136:139], v[204:207], v[72:75]
	v_mfma_f32_16x16x32_bf16 v[124:127], v[132:135], v[162:165], v[124:127]
	v_mfma_f32_16x16x32_bf16 v[120:123], v[140:143], v[162:165], v[120:123]
	v_mfma_f32_16x16x32_bf16 v[116:119], v[132:135], v[186:189], v[116:119]
	v_mfma_f32_16x16x32_bf16 v[108:111], v[140:143], v[186:189], v[108:111]
	v_mfma_f32_16x16x32_bf16 v[92:95], v[132:135], v[200:203], v[92:95]
	v_mfma_f32_16x16x32_bf16 v[88:91], v[140:143], v[200:203], v[88:91]
	v_mfma_f32_16x16x32_bf16 v[76:79], v[132:135], v[208:211], v[76:79]
	v_mfma_f32_16x16x32_bf16 v[72:75], v[140:143], v[208:211], v[72:75]
	s_setprio 0
	s_barrier
	s_add_i32 s81, s73, s51
	v_lshl_add_u64 v[194:195], s[44:45], 0, v[146:147]
	s_mov_b32 m0, s81
	ds_read_b128 v[212:215], v181
	ds_read_b128 v[216:219], v181 offset:1024
	ds_read_b128 v[220:223], v181 offset:2048
	ds_read_b128 v[224:227], v181 offset:3072
	global_load_lds_dwordx4 v[194:195], off
	v_lshl_add_u64 v[228:229], s[44:45], 0, v[150:151]
	s_add_i32 m0, s81, 0x2000
	s_nop 0
	global_load_lds_dwordx4 v[228:229], off
	s_barrier
	s_waitcnt lgkmcnt(0)
	s_setprio 1
	s_waitcnt lgkmcnt(0)
	v_mfma_f32_16x16x32_bf16 v[112:115], v[212:215], v[158:161], v[112:115]
	v_mfma_f32_16x16x32_bf16 v[104:107], v[220:223], v[158:161], v[104:107]
	v_mfma_f32_16x16x32_bf16 v[100:103], v[212:215], v[182:185], v[100:103]
	v_mfma_f32_16x16x32_bf16 v[96:99], v[220:223], v[182:185], v[96:99]
	v_mfma_f32_16x16x32_bf16 v[84:87], v[212:215], v[190:193], v[84:87]
	v_mfma_f32_16x16x32_bf16 v[80:83], v[220:223], v[190:193], v[80:83]
	v_mfma_f32_16x16x32_bf16 v[68:71], v[212:215], v[204:207], v[68:71]
	v_mfma_f32_16x16x32_bf16 v[64:67], v[220:223], v[204:207], v[64:67]
	v_mfma_f32_16x16x32_bf16 v[112:115], v[216:219], v[162:165], v[112:115]
	v_mfma_f32_16x16x32_bf16 v[104:107], v[224:227], v[162:165], v[104:107]
	v_mfma_f32_16x16x32_bf16 v[100:103], v[216:219], v[186:189], v[100:103]
	v_mfma_f32_16x16x32_bf16 v[96:99], v[224:227], v[186:189], v[96:99]
	v_mfma_f32_16x16x32_bf16 v[84:87], v[216:219], v[200:203], v[84:87]
	v_mfma_f32_16x16x32_bf16 v[80:83], v[224:227], v[200:203], v[80:83]
	v_mfma_f32_16x16x32_bf16 v[68:71], v[216:219], v[208:211], v[68:71]
	v_mfma_f32_16x16x32_bf16 v[64:67], v[224:227], v[208:211], v[64:67]
	s_setprio 0
	s_mov_b32 m0, s52
	v_lshl_add_u64 v[230:231], s[46:47], 0, v[144:145]
	s_barrier
	ds_read_b128 v[158:161], v180 offset:16384
	ds_read_b128 v[162:165], v180 offset:17408
	ds_read_b128 v[182:185], v180 offset:18432
	ds_read_b128 v[186:189], v180 offset:19456
	ds_read_b128 v[190:193], v180 offset:20480
	ds_read_b128 v[200:203], v180 offset:21504
	ds_read_b128 v[204:207], v180 offset:22528
	ds_read_b128 v[208:211], v180 offset:23552
	global_load_lds_dwordx4 v[230:231], off
	v_lshl_add_u64 v[232:233], s[46:47], 0, v[148:149]
	s_mov_b32 m0, s53
	s_nop 0
	global_load_lds_dwordx4 v[232:233], off
	s_barrier
	s_waitcnt lgkmcnt(0)
	s_setprio 1
	s_waitcnt lgkmcnt(0)
	v_mfma_f32_16x16x32_bf16 v[60:63], v[128:131], v[158:161], v[60:63]
	v_mfma_f32_16x16x32_bf16 v[56:59], v[136:139], v[158:161], v[56:59]
	v_mfma_f32_16x16x32_bf16 v[44:47], v[128:131], v[182:185], v[44:47]
	v_mfma_f32_16x16x32_bf16 v[40:43], v[136:139], v[182:185], v[40:43]
	v_mfma_f32_16x16x32_bf16 v[28:31], v[128:131], v[190:193], v[28:31]
	v_mfma_f32_16x16x32_bf16 v[24:27], v[136:139], v[190:193], v[24:27]
	v_mfma_f32_16x16x32_bf16 v[16:19], v[128:131], v[204:207], v[16:19]
	v_mfma_f32_16x16x32_bf16 v[8:11], v[136:139], v[204:207], v[8:11]
	v_mfma_f32_16x16x32_bf16 v[60:63], v[132:135], v[162:165], v[60:63]
	v_mfma_f32_16x16x32_bf16 v[56:59], v[140:143], v[162:165], v[56:59]
	v_mfma_f32_16x16x32_bf16 v[44:47], v[132:135], v[186:189], v[44:47]
	v_mfma_f32_16x16x32_bf16 v[40:43], v[140:143], v[186:189], v[40:43]
	v_mfma_f32_16x16x32_bf16 v[28:31], v[132:135], v[200:203], v[28:31]
	v_mfma_f32_16x16x32_bf16 v[24:27], v[140:143], v[200:203], v[24:27]
	v_mfma_f32_16x16x32_bf16 v[16:19], v[132:135], v[208:211], v[16:19]
	v_mfma_f32_16x16x32_bf16 v[8:11], v[140:143], v[208:211], v[8:11]
	s_setprio 0
	s_barrier
	s_add_u32 s82, s44, 0x40000
	s_addc_u32 s83, s45, 0
	s_add_i32 s81, s74, s51
	v_lshl_add_u64 v[128:129], s[82:83], 0, v[146:147]
	s_mov_b32 m0, s81
	s_nop 0
	global_load_lds_dwordx4 v[128:129], off
	v_lshl_add_u64 v[128:129], s[82:83], 0, v[150:151]
	s_add_i32 m0, s81, 0x2000
	s_nop 0
	global_load_lds_dwordx4 v[128:129], off
	s_waitcnt vmcnt(6)
	s_barrier
	s_setprio 1
	v_mfma_f32_16x16x32_bf16 v[52:55], v[212:215], v[158:161], v[52:55]
	v_mfma_f32_16x16x32_bf16 v[48:51], v[220:223], v[158:161], v[48:51]
	v_mfma_f32_16x16x32_bf16 v[36:39], v[212:215], v[182:185], v[36:39]
	v_mfma_f32_16x16x32_bf16 v[32:35], v[220:223], v[182:185], v[32:35]
	v_mfma_f32_16x16x32_bf16 v[20:23], v[212:215], v[190:193], v[20:23]
	v_mfma_f32_16x16x32_bf16 v[12:15], v[220:223], v[190:193], v[12:15]
	v_mfma_f32_16x16x32_bf16 v[4:7], v[212:215], v[204:207], v[4:7]
	v_mfma_f32_16x16x32_bf16 v[0:3], v[220:223], v[204:207], v[0:3]
	v_mfma_f32_16x16x32_bf16 v[52:55], v[216:219], v[162:165], v[52:55]
	v_mfma_f32_16x16x32_bf16 v[48:51], v[224:227], v[162:165], v[48:51]
	v_mfma_f32_16x16x32_bf16 v[36:39], v[216:219], v[186:189], v[36:39]
	v_mfma_f32_16x16x32_bf16 v[32:35], v[224:227], v[186:189], v[32:35]
	v_mfma_f32_16x16x32_bf16 v[20:23], v[216:219], v[200:203], v[20:23]
	v_mfma_f32_16x16x32_bf16 v[12:15], v[224:227], v[200:203], v[12:15]
	v_mfma_f32_16x16x32_bf16 v[4:7], v[216:219], v[208:211], v[4:7]
	v_mfma_f32_16x16x32_bf16 v[0:3], v[224:227], v[208:211], v[0:3]
	s_setprio 0
	s_add_i32 s81, 0, 0x18000
	v_add_u32_e32 v140, s81, v167
	s_barrier
	ds_read_b128 v[128:131], v140
	ds_read_b128 v[132:135], v140 offset:1024
	ds_read_b128 v[136:139], v140 offset:2048
	ds_read_b128 v[140:143], v140 offset:3072
	s_add_u32 s46, s46, 0x40000
	s_addc_u32 s47, s47, 0
	s_mov_b32 m0, s62
	v_lshl_add_u64 v[212:213], s[46:47], 0, v[144:145]
	ds_read_b128 v[158:161], v180 offset:32768
	ds_read_b128 v[162:165], v180 offset:33792
	ds_read_b128 v[182:185], v180 offset:34816
	ds_read_b128 v[186:189], v180 offset:35840
	ds_read_b128 v[190:193], v180 offset:36864
	ds_read_b128 v[200:203], v180 offset:37888
	ds_read_b128 v[204:207], v180 offset:38912
	ds_read_b128 v[208:211], v180 offset:39936
	global_load_lds_dwordx4 v[212:213], off
	v_lshl_add_u64 v[212:213], s[46:47], 0, v[148:149]
	s_mov_b32 m0, s63
	s_nop 0
	global_load_lds_dwordx4 v[212:213], off
	s_waitcnt lgkmcnt(8)
	s_barrier
	s_waitcnt lgkmcnt(0)
	s_setprio 1
	s_waitcnt lgkmcnt(0)
	v_mfma_f32_16x16x32_bf16 v[124:127], v[128:131], v[158:161], v[124:127]
	v_mfma_f32_16x16x32_bf16 v[120:123], v[136:139], v[158:161], v[120:123]
	v_mfma_f32_16x16x32_bf16 v[116:119], v[128:131], v[182:185], v[116:119]
	v_mfma_f32_16x16x32_bf16 v[108:111], v[136:139], v[182:185], v[108:111]
	v_mfma_f32_16x16x32_bf16 v[92:95], v[128:131], v[190:193], v[92:95]
	v_mfma_f32_16x16x32_bf16 v[88:91], v[136:139], v[190:193], v[88:91]
	v_mfma_f32_16x16x32_bf16 v[76:79], v[128:131], v[204:207], v[76:79]
	v_mfma_f32_16x16x32_bf16 v[72:75], v[136:139], v[204:207], v[72:75]
	v_mfma_f32_16x16x32_bf16 v[124:127], v[132:135], v[162:165], v[124:127]
	v_mfma_f32_16x16x32_bf16 v[120:123], v[140:143], v[162:165], v[120:123]
	v_mfma_f32_16x16x32_bf16 v[116:119], v[132:135], v[186:189], v[116:119]
	v_mfma_f32_16x16x32_bf16 v[108:111], v[140:143], v[186:189], v[108:111]
	v_mfma_f32_16x16x32_bf16 v[92:95], v[132:135], v[200:203], v[92:95]
	v_mfma_f32_16x16x32_bf16 v[88:91], v[140:143], v[200:203], v[88:91]
	v_mfma_f32_16x16x32_bf16 v[76:79], v[132:135], v[208:211], v[76:79]
	v_mfma_f32_16x16x32_bf16 v[72:75], v[140:143], v[208:211], v[72:75]
	s_setprio 0
	s_barrier
	s_add_i32 s46, 0, 0x1c000
	s_add_i32 s47, s81, s51
	v_add_u32_e32 v224, s46, v167
	v_lshl_add_u64 v[194:195], v[194:195], 0, s[22:23]
	s_mov_b32 m0, s47
	ds_read_b128 v[212:215], v224
	ds_read_b128 v[216:219], v224 offset:1024
	ds_read_b128 v[220:223], v224 offset:2048
	ds_read_b128 v[224:227], v224 offset:3072
	global_load_lds_dwordx4 v[194:195], off
	v_lshl_add_u64 v[194:195], v[228:229], 0, s[22:23]
	s_add_i32 m0, s47, 0x2000
	s_nop 0
	global_load_lds_dwordx4 v[194:195], off
	s_barrier
	s_waitcnt lgkmcnt(0)
	s_setprio 1
	s_waitcnt lgkmcnt(0)
	v_mfma_f32_16x16x32_bf16 v[112:115], v[212:215], v[158:161], v[112:115]
	v_mfma_f32_16x16x32_bf16 v[104:107], v[220:223], v[158:161], v[104:107]
	v_mfma_f32_16x16x32_bf16 v[100:103], v[212:215], v[182:185], v[100:103]
	v_mfma_f32_16x16x32_bf16 v[96:99], v[220:223], v[182:185], v[96:99]
	v_mfma_f32_16x16x32_bf16 v[84:87], v[212:215], v[190:193], v[84:87]
	v_mfma_f32_16x16x32_bf16 v[80:83], v[220:223], v[190:193], v[80:83]
	v_mfma_f32_16x16x32_bf16 v[68:71], v[212:215], v[204:207], v[68:71]
	v_mfma_f32_16x16x32_bf16 v[64:67], v[220:223], v[204:207], v[64:67]
	v_mfma_f32_16x16x32_bf16 v[112:115], v[216:219], v[162:165], v[112:115]
	v_mfma_f32_16x16x32_bf16 v[104:107], v[224:227], v[162:165], v[104:107]
	v_mfma_f32_16x16x32_bf16 v[100:103], v[216:219], v[186:189], v[100:103]
	v_mfma_f32_16x16x32_bf16 v[96:99], v[224:227], v[186:189], v[96:99]
	v_mfma_f32_16x16x32_bf16 v[84:87], v[216:219], v[200:203], v[84:87]
	v_mfma_f32_16x16x32_bf16 v[80:83], v[224:227], v[200:203], v[80:83]
	v_mfma_f32_16x16x32_bf16 v[68:71], v[216:219], v[208:211], v[68:71]
	v_mfma_f32_16x16x32_bf16 v[64:67], v[224:227], v[208:211], v[64:67]
	s_setprio 0
	s_mov_b32 m0, s68
	v_lshl_add_u64 v[194:195], v[230:231], 0, s[22:23]
	s_barrier
	ds_read_b128 v[158:161], v180 offset:49152
	ds_read_b128 v[162:165], v180 offset:50176
	ds_read_b128 v[182:185], v180 offset:51200
	ds_read_b128 v[186:189], v180 offset:52224
	ds_read_b128 v[190:193], v180 offset:53248
	ds_read_b128 v[200:203], v180 offset:54272
	ds_read_b128 v[204:207], v180 offset:55296
	ds_read_b128 v[208:211], v180 offset:56320
	global_load_lds_dwordx4 v[194:195], off
	v_lshl_add_u64 v[194:195], v[232:233], 0, s[22:23]
	s_mov_b32 m0, s69
	s_nop 0
	global_load_lds_dwordx4 v[194:195], off
	s_barrier
	s_waitcnt lgkmcnt(0)
	s_setprio 1
	s_waitcnt lgkmcnt(0)
	v_mfma_f32_16x16x32_bf16 v[60:63], v[128:131], v[158:161], v[60:63]
	v_mfma_f32_16x16x32_bf16 v[56:59], v[136:139], v[158:161], v[56:59]
	v_mfma_f32_16x16x32_bf16 v[44:47], v[128:131], v[182:185], v[44:47]
	v_mfma_f32_16x16x32_bf16 v[40:43], v[136:139], v[182:185], v[40:43]
	v_mfma_f32_16x16x32_bf16 v[28:31], v[128:131], v[190:193], v[28:31]
	v_mfma_f32_16x16x32_bf16 v[24:27], v[136:139], v[190:193], v[24:27]
	v_mfma_f32_16x16x32_bf16 v[16:19], v[128:131], v[204:207], v[16:19]
	v_mfma_f32_16x16x32_bf16 v[8:11], v[136:139], v[204:207], v[8:11]
	v_mfma_f32_16x16x32_bf16 v[60:63], v[132:135], v[162:165], v[60:63]
	v_mfma_f32_16x16x32_bf16 v[56:59], v[140:143], v[162:165], v[56:59]
	v_mfma_f32_16x16x32_bf16 v[44:47], v[132:135], v[186:189], v[44:47]
	v_mfma_f32_16x16x32_bf16 v[40:43], v[140:143], v[186:189], v[40:43]
	v_mfma_f32_16x16x32_bf16 v[28:31], v[132:135], v[200:203], v[28:31]
	v_mfma_f32_16x16x32_bf16 v[24:27], v[140:143], v[200:203], v[24:27]
	v_mfma_f32_16x16x32_bf16 v[16:19], v[132:135], v[208:211], v[16:19]
	v_mfma_f32_16x16x32_bf16 v[8:11], v[140:143], v[208:211], v[8:11]
	s_setprio 0
	s_barrier
	s_add_u32 s44, s44, 0x40080
	s_addc_u32 s45, s45, 0
	s_add_i32 s46, s46, s51
	v_lshl_add_u64 v[128:129], s[44:45], 0, v[146:147]
	s_mov_b32 m0, s46
	s_nop 0
	global_load_lds_dwordx4 v[128:129], off
	v_lshl_add_u64 v[128:129], s[44:45], 0, v[150:151]
	s_add_i32 m0, s46, 0x2000
	s_nop 0
	global_load_lds_dwordx4 v[128:129], off
	s_waitcnt vmcnt(6)
	s_barrier
	s_setprio 1
	v_mfma_f32_16x16x32_bf16 v[52:55], v[212:215], v[158:161], v[52:55]
	v_mfma_f32_16x16x32_bf16 v[48:51], v[220:223], v[158:161], v[48:51]
	v_mfma_f32_16x16x32_bf16 v[36:39], v[212:215], v[182:185], v[36:39]
	v_mfma_f32_16x16x32_bf16 v[32:35], v[220:223], v[182:185], v[32:35]
	v_mfma_f32_16x16x32_bf16 v[20:23], v[212:215], v[190:193], v[20:23]
	v_mfma_f32_16x16x32_bf16 v[12:15], v[220:223], v[190:193], v[12:15]
	v_mfma_f32_16x16x32_bf16 v[4:7], v[212:215], v[204:207], v[4:7]
	v_mfma_f32_16x16x32_bf16 v[0:3], v[220:223], v[204:207], v[0:3]
	v_mfma_f32_16x16x32_bf16 v[52:55], v[216:219], v[162:165], v[52:55]
	v_mfma_f32_16x16x32_bf16 v[48:51], v[224:227], v[162:165], v[48:51]
	v_mfma_f32_16x16x32_bf16 v[36:39], v[216:219], v[186:189], v[36:39]
	v_mfma_f32_16x16x32_bf16 v[32:35], v[224:227], v[186:189], v[32:35]
	v_mfma_f32_16x16x32_bf16 v[20:23], v[216:219], v[200:203], v[20:23]
	v_mfma_f32_16x16x32_bf16 v[12:15], v[224:227], v[200:203], v[12:15]
	v_mfma_f32_16x16x32_bf16 v[4:7], v[216:219], v[208:211], v[4:7]
	v_mfma_f32_16x16x32_bf16 v[0:3], v[224:227], v[208:211], v[0:3]
	s_setprio 0
	s_add_i32 s60, s60, 2
	s_add_u32 s42, s42, 0x100
	s_addc_u32 s43, s43, 0
	s_add_u32 s18, s18, 0x100
	s_addc_u32 s19, s19, 0
	s_cmp_gt_u32 s60, 13
	s_barrier
	s_cbranch_scc0 .LBB0_817
	v_add_u32_e32 v158, s33, v166
	v_ashrrev_i32_e32 v159, 31, v158
	v_readlane_b32 s18, v254, 56
	v_add_u32_e32 v128, s67, v168
	v_lshlrev_b64 v[130:131], 11, v[158:159]
	v_readlane_b32 s19, v254, 57
	v_ashrrev_i32_e32 v129, 31, v128
	s_nop 0
	v_lshl_add_u64 v[130:131], s[18:19], 0, v[130:131]
	v_lshl_add_u64 v[160:161], v[128:129], 1, v[130:131]
	v_add_co_u32_e32 v190, vcc, s71, v160
	global_load_dwordx4 v[132:135], v[160:161], off
	global_load_dwordx4 v[140:143], v[160:161], off offset:256
	v_addc_co_u32_e32 v191, vcc, 0, v161, vcc
	global_load_dwordx4 v[182:185], v[190:191], off
	v_lshl_add_u64 v[192:193], v[160:161], 0, s[24:25]
	global_load_dwordx4 v[186:189], v[192:193], off offset:256
	s_mov_b32 s18, 0x10000
	v_add_co_u32_e32 v164, vcc, s18, v160
	v_lshl_add_u64 v[162:163], v[160:161], 0, s[26:27]
	s_nop 0
	v_addc_co_u32_e32 v165, vcc, 0, v161, vcc
	global_load_dwordx4 v[136:139], v[164:165], off
	global_load_dwordx4 v[128:131], v[162:163], off offset:256
	s_mov_b32 s98, s70
	s_mov_b32 s99, 0
	v_lshl_add_u64 v[246:247], v[160:161], 0, s[98:99]
	global_load_dwordx4 v[206:209], v[246:247], off
	v_lshl_add_u64 v[246:247], v[160:161], 0, s[28:29]
	global_load_dwordx4 v[210:213], v[246:247], off offset:256
	s_mov_b32 s98, s75
	s_mov_b32 s99, 0
	v_lshl_add_u64 v[246:247], v[160:161], 0, s[98:99]
	global_load_dwordx4 v[214:217], v[246:247], off
	v_lshl_add_u64 v[246:247], v[160:161], 0, s[20:21]
	global_load_dwordx4 v[218:221], v[246:247], off offset:256
	s_mov_b32 s98, s76
	s_mov_b32 s99, 0
	v_lshl_add_u64 v[246:247], v[160:161], 0, s[98:99]
	global_load_dwordx4 v[222:225], v[246:247], off
	v_lshl_add_u64 v[246:247], v[160:161], 0, s[30:31]
	global_load_dwordx4 v[226:229], v[246:247], off offset:256
	s_mov_b32 s98, s77
	s_mov_b32 s99, 0
	v_lshl_add_u64 v[246:247], v[160:161], 0, s[98:99]
	global_load_dwordx4 v[230:233], v[246:247], off
	v_lshl_add_u64 v[246:247], v[160:161], 0, s[34:35]
	global_load_dwordx4 v[234:237], v[246:247], off offset:256
	s_mov_b32 s98, s78
	s_mov_b32 s99, 0
	v_lshl_add_u64 v[246:247], v[160:161], 0, s[98:99]
	global_load_dwordx4 v[238:241], v[246:247], off
	v_lshl_add_u64 v[246:247], v[160:161], 0, s[36:37]
	global_load_dwordx4 v[242:245], v[246:247], off offset:256
	s_waitcnt vmcnt(10)
	v_lshlrev_b32_e32 v194, 16, v132
	v_and_b32_e32 v195, 0xffff0000, v132
	v_lshlrev_b32_e32 v200, 16, v134
	v_and_b32_e32 v201, 0xffff0000, v134
	v_pk_add_f32 v[124:125], v[124:125], v[194:195]
	v_lshlrev_b32_e32 v194, 16, v182
	v_and_b32_e32 v195, 0xffff0000, v182
	v_pk_add_f32 v[120:121], v[120:121], v[200:201]
	v_lshlrev_b32_e32 v182, 16, v183
	v_and_b32_e32 v183, 0xffff0000, v183
	v_lshlrev_b32_e32 v200, 16, v184
	v_and_b32_e32 v201, 0xffff0000, v184
	v_lshlrev_b32_e32 v184, 16, v185
	v_and_b32_e32 v185, 0xffff0000, v185
	v_pk_add_f32 v[116:117], v[116:117], v[194:195]
	v_pk_add_f32 v[118:119], v[118:119], v[182:183]
	v_pk_add_f32 v[182:183], v[110:111], v[184:185]
	v_mul_f32_e32 v111, v117, v117
	v_fmac_f32_e32 v111, v116, v116
	v_lshlrev_b32_e32 v132, 16, v133
	v_and_b32_e32 v133, 0xffff0000, v133
	v_lshlrev_b32_e32 v202, 16, v140
	v_and_b32_e32 v203, 0xffff0000, v140
	v_lshlrev_b32_e32 v140, 16, v141
	v_and_b32_e32 v141, 0xffff0000, v141
	v_lshlrev_b32_e32 v204, 16, v142
	v_and_b32_e32 v205, 0xffff0000, v142
	v_lshlrev_b32_e32 v142, 16, v143
	v_and_b32_e32 v143, 0xffff0000, v143
	v_fmac_f32_e32 v111, v118, v118
	v_lshlrev_b32_e32 v134, 16, v135
	v_and_b32_e32 v135, 0xffff0000, v135
	v_pk_add_f32 v[126:127], v[126:127], v[132:133]
	v_pk_add_f32 v[132:133], v[114:115], v[140:141]
	v_pk_add_f32 v[140:141], v[106:107], v[142:143]
	v_cvt_pk_bf16_f32 v106, v120, v121
	v_pk_add_f32 v[108:109], v[108:109], v[200:201]
	v_fmac_f32_e32 v111, v119, v119
	v_pk_add_f32 v[122:123], v[122:123], v[134:135]
	v_pk_add_f32 v[134:135], v[112:113], v[202:203]
	v_pk_add_f32 v[142:143], v[104:105], v[204:205]
	v_cvt_pk_bf16_f32 v104, v124, v125
	v_cvt_pk_bf16_f32 v105, v126, v127
	v_cvt_pk_bf16_f32 v107, v122, v123
	v_cvt_pk_bf16_f32 v112, v134, v135
	v_cvt_pk_bf16_f32 v113, v132, v133
	s_nop 0
	v_cvt_pk_bf16_f32 v114, v142, v143
	v_cvt_pk_bf16_f32 v115, v140, v141
	global_store_dwordx4 v[160:161], v[104:107], off
	v_fmac_f32_e32 v111, v108, v108
	global_store_dwordx4 v[160:161], v[112:115], off offset:256
	v_cvt_pk_bf16_f32 v106, v108, v109
	v_add_co_u32_e32 v108, vcc, s70, v160
	v_cvt_pk_bf16_f32 v104, v116, v117
	v_cvt_pk_bf16_f32 v105, v118, v119
	v_cvt_pk_bf16_f32 v107, v182, v183
	v_fmac_f32_e32 v111, v109, v109
	v_lshlrev_b32_e32 v112, 16, v186
	v_and_b32_e32 v113, 0xffff0000, v186
	v_lshlrev_b32_e32 v114, 16, v187
	v_and_b32_e32 v115, 0xffff0000, v187
	v_lshlrev_b32_e32 v116, 16, v188
	v_addc_co_u32_e32 v109, vcc, 0, v161, vcc
	v_and_b32_e32 v117, 0xffff0000, v188
	global_store_dwordx4 v[190:191], v[104:107], off
	v_lshlrev_b32_e32 v118, 16, v189
	v_and_b32_e32 v119, 0xffff0000, v189
	v_pk_add_f32 v[102:103], v[102:103], v[114:115]
	v_pk_add_f32 v[100:101], v[100:101], v[112:113]
	v_pk_add_f32 v[114:115], v[96:97], v[116:117]
	v_cvt_pk_bf16_f32 v96, v100, v101
	v_pk_add_f32 v[112:113], v[98:99], v[118:119]
	v_cvt_pk_bf16_f32 v97, v102, v103
	v_cvt_pk_bf16_f32 v98, v114, v115
	v_fmac_f32_e32 v111, v182, v182
	v_cvt_pk_bf16_f32 v99, v112, v113
	global_store_dwordx4 v[192:193], v[96:99], off offset:256
	v_fmac_f32_e32 v111, v183, v183
	v_lshlrev_b32_e32 v116, 16, v138
	v_mul_f32_e32 v96, v101, v101
	v_fmac_f32_e32 v96, v100, v100
	v_fmac_f32_e32 v96, v102, v102
	v_fmac_f32_e32 v96, v103, v103
	v_fmac_f32_e32 v96, v114, v114
	v_fmac_f32_e32 v96, v115, v115
	v_fmac_f32_e32 v96, v112, v112
	v_fmac_f32_e32 v96, v113, v113
	v_lshl_add_u64 v[100:101], v[160:161], 0, s[28:29]
	v_add_f32_e32 v102, v111, v96
	v_lshlrev_b32_e32 v112, 16, v136
	v_and_b32_e32 v113, 0xffff0000, v136
	v_lshlrev_b32_e32 v114, 16, v137
	v_and_b32_e32 v115, 0xffff0000, v137
	v_and_b32_e32 v117, 0xffff0000, v138
	v_lshlrev_b32_e32 v118, 16, v139
	v_and_b32_e32 v119, 0xffff0000, v139
	v_pk_add_f32 v[94:95], v[94:95], v[114:115]
	v_pk_add_f32 v[92:93], v[92:93], v[112:113]
	v_pk_add_f32 v[114:115], v[88:89], v[116:117]
	v_cvt_pk_bf16_f32 v88, v92, v93
	v_pk_add_f32 v[112:113], v[90:91], v[118:119]
	v_cvt_pk_bf16_f32 v89, v94, v95
	v_cvt_pk_bf16_f32 v90, v114, v115
	v_mul_f32_e32 v103, v93, v93
	v_cvt_pk_bf16_f32 v91, v112, v113
	global_store_dwordx4 v[164:165], v[88:91], off
	v_fmac_f32_e32 v103, v92, v92
	v_fmac_f32_e32 v103, v94, v94
	v_add_co_u32_e32 v88, vcc, s75, v160
	v_fmac_f32_e32 v103, v95, v95
	s_nop 0
	v_addc_co_u32_e32 v89, vcc, 0, v161, vcc
	v_fmac_f32_e32 v103, v114, v114
	v_fmac_f32_e32 v103, v115, v115
	v_fmac_f32_e32 v103, v112, v112
	v_fmac_f32_e32 v103, v113, v113
	v_lshlrev_b32_e32 v94, 16, v128
	v_and_b32_e32 v95, 0xffff0000, v128
	v_lshlrev_b32_e32 v112, 16, v129
	v_and_b32_e32 v113, 0xffff0000, v129
	v_lshlrev_b32_e32 v114, 16, v130
	v_and_b32_e32 v115, 0xffff0000, v130
	v_lshlrev_b32_e32 v116, 16, v131
	v_and_b32_e32 v117, 0xffff0000, v131
	v_pk_add_f32 v[86:87], v[86:87], v[112:113]
	v_pk_add_f32 v[84:85], v[84:85], v[94:95]
	v_pk_add_f32 v[112:113], v[80:81], v[114:115]
	v_cvt_pk_bf16_f32 v80, v84, v85
	v_pk_add_f32 v[94:95], v[82:83], v[116:117]
	v_cvt_pk_bf16_f32 v81, v86, v87
	v_cvt_pk_bf16_f32 v82, v112, v113
	v_mul_f32_e32 v125, v125, v125
	v_cvt_pk_bf16_f32 v83, v94, v95
	global_store_dwordx4 v[162:163], v[80:83], off offset:256
	v_mul_f32_e32 v135, v135, v135
	v_fmac_f32_e32 v125, v124, v124
	v_mul_f32_e32 v80, v85, v85
	v_fmac_f32_e32 v80, v84, v84
	v_fmac_f32_e32 v80, v86, v86
	v_fmac_f32_e32 v80, v87, v87
	v_fmac_f32_e32 v80, v112, v112
	v_fmac_f32_e32 v80, v113, v113
	v_fmac_f32_e32 v80, v94, v94
	v_fmac_f32_e32 v80, v95, v95
	v_lshl_add_u64 v[84:85], v[160:161], 0, s[20:21]
	v_add_f32_e32 v86, v103, v80
	s_waitcnt vmcnt(12)
	s_nop 1
	v_mov_b32_e32 v104, v206
	v_mov_b32_e32 v105, v207
	v_mov_b32_e32 v106, v208
	v_mov_b32_e32 v107, v209
	v_mov_b32_e32 v96, v210
	v_mov_b32_e32 v97, v211
	v_mov_b32_e32 v98, v212
	v_mov_b32_e32 v99, v213
	v_mov_b32_e32 v90, v214
	v_mov_b32_e32 v91, v215
	v_mov_b32_e32 v92, v216
	v_mov_b32_e32 v93, v217
	v_mov_b32_e32 v80, v218
	v_mov_b32_e32 v81, v219
	v_mov_b32_e32 v82, v220
	v_mov_b32_e32 v83, v221
	v_lshlrev_b32_e32 v94, 16, v104
	v_and_b32_e32 v95, 0xffff0000, v104
	v_pk_add_f32 v[76:77], v[76:77], v[94:95]
	v_lshlrev_b32_e32 v104, 16, v105
	v_and_b32_e32 v105, 0xffff0000, v105
	v_mul_f32_e32 v87, v77, v77
	v_pk_add_f32 v[78:79], v[78:79], v[104:105]
	v_fmac_f32_e32 v87, v76, v76
	v_lshlrev_b32_e32 v112, 16, v106
	v_and_b32_e32 v113, 0xffff0000, v106
	v_fmac_f32_e32 v87, v78, v78
	v_pk_add_f32 v[104:105], v[72:73], v[112:113]
	v_fmac_f32_e32 v87, v79, v79
	v_lshlrev_b32_e32 v106, 16, v107
	v_and_b32_e32 v107, 0xffff0000, v107
	v_fmac_f32_e32 v87, v104, v104
	v_pk_add_f32 v[94:95], v[74:75], v[106:107]
	v_fmac_f32_e32 v87, v105, v105
	v_fmac_f32_e32 v87, v94, v94
	v_cvt_pk_bf16_f32 v73, v78, v79
	v_cvt_pk_bf16_f32 v75, v94, v95
	v_fmac_f32_e32 v87, v95, v95
	v_lshlrev_b32_e32 v78, 16, v96
	v_and_b32_e32 v79, 0xffff0000, v96
	v_lshlrev_b32_e32 v94, 16, v97
	v_and_b32_e32 v95, 0xffff0000, v97
	v_lshlrev_b32_e32 v96, 16, v98
	v_and_b32_e32 v97, 0xffff0000, v98
	v_cvt_pk_bf16_f32 v72, v76, v77
	v_add_co_u32_e32 v76, vcc, s76, v160
	v_lshlrev_b32_e32 v98, 16, v99
	v_and_b32_e32 v99, 0xffff0000, v99
	v_pk_add_f32 v[70:71], v[70:71], v[94:95]
	v_pk_add_f32 v[68:69], v[68:69], v[78:79]
	v_pk_add_f32 v[94:95], v[64:65], v[96:97]
	v_cvt_pk_bf16_f32 v64, v68, v69
	v_cvt_pk_bf16_f32 v74, v104, v105
	v_addc_co_u32_e32 v77, vcc, 0, v161, vcc
	v_pk_add_f32 v[78:79], v[66:67], v[98:99]
	v_cvt_pk_bf16_f32 v65, v70, v71
	v_cvt_pk_bf16_f32 v66, v94, v95
	global_store_dwordx4 v[108:109], v[72:75], off
	v_cvt_pk_bf16_f32 v67, v78, v79
	global_store_dwordx4 v[100:101], v[64:67], off offset:256
	v_fmac_f32_e32 v135, v134, v134
	v_mul_f32_e32 v64, v69, v69
	v_fmac_f32_e32 v64, v68, v68
	v_fmac_f32_e32 v64, v70, v70
	v_fmac_f32_e32 v64, v71, v71
	v_fmac_f32_e32 v64, v94, v94
	v_fmac_f32_e32 v64, v95, v95
	v_fmac_f32_e32 v64, v78, v78
	v_fmac_f32_e32 v64, v79, v79
	v_add_f32_e32 v68, v87, v64
	v_lshlrev_b32_e32 v64, 16, v91
	v_and_b32_e32 v65, 0xffff0000, v91
	v_lshl_add_u64 v[66:67], v[160:161], 0, s[30:31]
	v_lshlrev_b32_e32 v70, 16, v90
	v_and_b32_e32 v71, 0xffff0000, v90
	v_lshlrev_b32_e32 v78, 16, v92
	v_and_b32_e32 v79, 0xffff0000, v92
	v_lshlrev_b32_e32 v90, 16, v93
	v_and_b32_e32 v91, 0xffff0000, v93
	v_pk_add_f32 v[92:93], v[62:63], v[64:65]
	v_pk_add_f32 v[60:61], v[60:61], v[70:71]
	v_pk_add_f32 v[78:79], v[56:57], v[78:79]
	v_mul_f32_e32 v69, v61, v61
	v_fmac_f32_e32 v69, v60, v60
	v_fmac_f32_e32 v69, v92, v92
	v_fmac_f32_e32 v69, v93, v93
	v_fmac_f32_e32 v69, v78, v78
	v_pk_add_f32 v[70:71], v[58:59], v[90:91]
	v_fmac_f32_e32 v69, v79, v79
	v_fmac_f32_e32 v69, v70, v70
	v_cvt_pk_bf16_f32 v58, v78, v79
	v_cvt_pk_bf16_f32 v59, v70, v71
	v_fmac_f32_e32 v69, v71, v71
	v_lshlrev_b32_e32 v70, 16, v80
	v_and_b32_e32 v71, 0xffff0000, v80
	v_lshlrev_b32_e32 v78, 16, v81
	v_and_b32_e32 v79, 0xffff0000, v81
	v_lshlrev_b32_e32 v80, 16, v82
	v_and_b32_e32 v81, 0xffff0000, v82
	v_lshlrev_b32_e32 v82, 16, v83
	v_and_b32_e32 v83, 0xffff0000, v83
	v_pk_add_f32 v[54:55], v[54:55], v[78:79]
	v_pk_add_f32 v[52:53], v[52:53], v[70:71]
	v_pk_add_f32 v[78:79], v[48:49], v[80:81]
	v_cvt_pk_bf16_f32 v48, v52, v53
	v_pk_add_f32 v[70:71], v[50:51], v[82:83]
	v_cvt_pk_bf16_f32 v49, v54, v55
	v_cvt_pk_bf16_f32 v50, v78, v79
	v_cvt_pk_bf16_f32 v56, v60, v61
	v_add_co_u32_e32 v60, vcc, s77, v160
	v_cvt_pk_bf16_f32 v51, v70, v71
	global_store_dwordx4 v[84:85], v[48:51], off offset:256
	v_cvt_pk_bf16_f32 v57, v92, v93
	s_nop 0
	v_addc_co_u32_e32 v61, vcc, 0, v161, vcc
	v_mul_f32_e32 v48, v53, v53
	v_fmac_f32_e32 v48, v52, v52
	v_fmac_f32_e32 v48, v54, v54
	v_fmac_f32_e32 v48, v55, v55
	v_fmac_f32_e32 v48, v78, v78
	global_store_dwordx4 v[88:89], v[56:59], off
	v_fmac_f32_e32 v48, v79, v79
	v_fmac_f32_e32 v48, v70, v70
	v_fmac_f32_e32 v48, v71, v71
	v_add_f32_e32 v69, v69, v48
	v_lshl_add_u64 v[48:49], v[160:161], 0, s[34:35]
	v_fmac_f32_e32 v125, v126, v126
	v_fmac_f32_e32 v135, v132, v132
	v_fmac_f32_e32 v125, v127, v127
	v_fmac_f32_e32 v135, v133, v133
	v_fmac_f32_e32 v125, v120, v120
	v_fmac_f32_e32 v135, v142, v142
	v_fmac_f32_e32 v125, v121, v121
	v_fmac_f32_e32 v135, v143, v143
	v_fmac_f32_e32 v125, v122, v122
	s_waitcnt vmcnt(12)
	s_nop 1
	v_mov_b32_e32 v72, v222
	v_mov_b32_e32 v73, v223
	v_mov_b32_e32 v74, v224
	v_mov_b32_e32 v75, v225
	v_mov_b32_e32 v62, v226
	v_mov_b32_e32 v63, v227
	v_mov_b32_e32 v64, v228
	v_mov_b32_e32 v65, v229
	v_mov_b32_e32 v56, v230
	v_mov_b32_e32 v57, v231
	v_mov_b32_e32 v58, v232
	v_mov_b32_e32 v59, v233
	v_mov_b32_e32 v50, v234
	v_mov_b32_e32 v51, v235
	v_mov_b32_e32 v52, v236
	v_mov_b32_e32 v53, v237
	v_lshlrev_b32_e32 v54, 16, v72
	v_and_b32_e32 v55, 0xffff0000, v72
	v_lshlrev_b32_e32 v70, 16, v73
	v_and_b32_e32 v71, 0xffff0000, v73
	v_lshlrev_b32_e32 v72, 16, v74
	v_and_b32_e32 v73, 0xffff0000, v74
	v_pk_add_f32 v[44:45], v[44:45], v[54:55]
	v_pk_add_f32 v[46:47], v[46:47], v[70:71]
	v_pk_add_f32 v[70:71], v[40:41], v[72:73]
	v_mul_f32_e32 v72, v45, v45
	v_fmac_f32_e32 v72, v44, v44
	v_fmac_f32_e32 v72, v46, v46
	v_fmac_f32_e32 v72, v47, v47
	v_lshlrev_b32_e32 v74, 16, v75
	v_and_b32_e32 v75, 0xffff0000, v75
	v_cvt_pk_bf16_f32 v40, v44, v45
	v_fmac_f32_e32 v72, v70, v70
	v_add_co_u32_e32 v44, vcc, s78, v160
	v_pk_add_f32 v[54:55], v[42:43], v[74:75]
	v_cvt_pk_bf16_f32 v41, v46, v47
	v_cvt_pk_bf16_f32 v42, v70, v71
	v_fmac_f32_e32 v72, v71, v71
	v_cvt_pk_bf16_f32 v43, v54, v55
	v_addc_co_u32_e32 v45, vcc, 0, v161, vcc
	global_store_dwordx4 v[76:77], v[40:43], off
	v_fmac_f32_e32 v72, v54, v54
	v_lshlrev_b32_e32 v46, 16, v62
	v_and_b32_e32 v47, 0xffff0000, v62
	v_fmac_f32_e32 v72, v55, v55
	v_lshlrev_b32_e32 v54, 16, v63
	v_and_b32_e32 v55, 0xffff0000, v63
	v_lshlrev_b32_e32 v62, 16, v64
	v_and_b32_e32 v63, 0xffff0000, v64
	v_pk_add_f32 v[36:37], v[36:37], v[46:47]
	v_lshlrev_b32_e32 v64, 16, v65
	v_and_b32_e32 v65, 0xffff0000, v65
	v_pk_add_f32 v[38:39], v[38:39], v[54:55]
	v_pk_add_f32 v[54:55], v[32:33], v[62:63]
	v_mul_f32_e32 v62, v37, v37
	v_pk_add_f32 v[46:47], v[34:35], v[64:65]
	v_cvt_pk_bf16_f32 v32, v36, v37
	v_cvt_pk_bf16_f32 v33, v38, v39
	v_cvt_pk_bf16_f32 v34, v54, v55
	v_fmac_f32_e32 v62, v36, v36
	v_cvt_pk_bf16_f32 v35, v46, v47
	v_lshl_add_u64 v[36:37], v[160:161], 0, s[36:37]
	global_store_dwordx4 v[66:67], v[32:35], off offset:256
	v_fmac_f32_e32 v62, v38, v38
	v_fmac_f32_e32 v62, v39, v39
	v_fmac_f32_e32 v62, v54, v54
	v_fmac_f32_e32 v62, v55, v55
	v_fmac_f32_e32 v62, v46, v46
	v_fmac_f32_e32 v62, v47, v47
	v_fmac_f32_e32 v135, v140, v140
	v_fmac_f32_e32 v125, v123, v123
	v_fmac_f32_e32 v135, v141, v141
	v_add_f32_e32 v110, v125, v135
	v_add_f32_e32 v62, v72, v62
	v_lshlrev_b32_e32 v38, 16, v56
	v_and_b32_e32 v39, 0xffff0000, v56
	v_lshlrev_b32_e32 v46, 16, v57
	v_and_b32_e32 v47, 0xffff0000, v57
	v_lshlrev_b32_e32 v54, 16, v58
	v_and_b32_e32 v55, 0xffff0000, v58
	v_pk_add_f32 v[28:29], v[28:29], v[38:39]
	v_lshlrev_b32_e32 v56, 16, v59
	v_and_b32_e32 v57, 0xffff0000, v59
	v_pk_add_f32 v[30:31], v[30:31], v[46:47]
	v_pk_add_f32 v[46:47], v[24:25], v[54:55]
	v_mul_f32_e32 v54, v29, v29
	v_pk_add_f32 v[38:39], v[26:27], v[56:57]
	v_cvt_pk_bf16_f32 v24, v28, v29
	v_cvt_pk_bf16_f32 v25, v30, v31
	v_cvt_pk_bf16_f32 v26, v46, v47
	v_fmac_f32_e32 v54, v28, v28
	v_cvt_pk_bf16_f32 v27, v38, v39
	global_store_dwordx4 v[60:61], v[24:27], off
	v_fmac_f32_e32 v54, v30, v30
	v_lshlrev_b32_e32 v28, 16, v52
	v_lshlrev_b32_e32 v24, 16, v50
	v_and_b32_e32 v25, 0xffff0000, v50
	v_lshlrev_b32_e32 v26, 16, v51
	v_and_b32_e32 v27, 0xffff0000, v51
	v_and_b32_e32 v29, 0xffff0000, v52
	v_fmac_f32_e32 v54, v31, v31
	v_lshlrev_b32_e32 v30, 16, v53
	v_and_b32_e32 v31, 0xffff0000, v53
	v_pk_add_f32 v[22:23], v[22:23], v[26:27]
	v_pk_add_f32 v[20:21], v[20:21], v[24:25]
	v_pk_add_f32 v[26:27], v[12:13], v[28:29]
	v_cvt_pk_bf16_f32 v12, v20, v21
	v_pk_add_f32 v[24:25], v[14:15], v[30:31]
	v_cvt_pk_bf16_f32 v13, v22, v23
	v_cvt_pk_bf16_f32 v14, v26, v27
	v_fmac_f32_e32 v54, v46, v46
	v_cvt_pk_bf16_f32 v15, v24, v25
	global_store_dwordx4 v[48:49], v[12:15], off offset:256
	v_fmac_f32_e32 v54, v47, v47
	v_fmac_f32_e32 v54, v38, v38
	v_mul_f32_e32 v12, v21, v21
	v_fmac_f32_e32 v12, v20, v20
	v_fmac_f32_e32 v12, v22, v22
	v_fmac_f32_e32 v12, v23, v23
	v_fmac_f32_e32 v12, v26, v26
	v_fmac_f32_e32 v12, v27, v27
	v_fmac_f32_e32 v12, v24, v24
	v_fmac_f32_e32 v54, v39, v39
	v_fmac_f32_e32 v12, v25, v25
	v_add_f32_e32 v24, v54, v12
	s_waitcnt vmcnt(14)
	s_nop 1
	v_mov_b32_e32 v40, v238
	v_mov_b32_e32 v41, v239
	v_mov_b32_e32 v42, v240
	v_mov_b32_e32 v43, v241
	v_mov_b32_e32 v32, v242
	v_mov_b32_e32 v33, v243
	v_mov_b32_e32 v34, v244
	v_mov_b32_e32 v35, v245
	v_lshlrev_b32_e32 v12, 16, v40
	v_and_b32_e32 v13, 0xffff0000, v40
	v_pk_add_f32 v[12:13], v[16:17], v[12:13]
	v_lshlrev_b32_e32 v14, 16, v41
	v_and_b32_e32 v15, 0xffff0000, v41
	v_lshlrev_b32_e32 v20, 16, v42
	v_and_b32_e32 v21, 0xffff0000, v42
	v_mul_f32_e32 v25, v13, v13
	v_lshlrev_b32_e32 v22, 16, v43
	v_and_b32_e32 v23, 0xffff0000, v43
	v_pk_add_f32 v[14:15], v[18:19], v[14:15]
	v_pk_add_f32 v[18:19], v[8:9], v[20:21]
	v_cvt_pk_bf16_f32 v8, v12, v13
	v_cvt_pk_bf16_f32 v9, v14, v15
	v_fmac_f32_e32 v25, v12, v12
	v_pk_add_f32 v[16:17], v[10:11], v[22:23]
	v_cvt_pk_bf16_f32 v10, v18, v19
	v_fmac_f32_e32 v25, v14, v14
	v_cvt_pk_bf16_f32 v11, v16, v17
	global_store_dwordx4 v[44:45], v[8:11], off
	v_fmac_f32_e32 v25, v15, v15
	v_lshlrev_b32_e32 v12, 16, v34
	v_lshlrev_b32_e32 v8, 16, v32
	v_and_b32_e32 v9, 0xffff0000, v32
	v_and_b32_e32 v13, 0xffff0000, v34
	v_pk_add_f32 v[4:5], v[4:5], v[8:9]
	v_fmac_f32_e32 v25, v18, v18
	v_lshlrev_b32_e32 v10, 16, v33
	v_and_b32_e32 v11, 0xffff0000, v33
	v_pk_add_f32 v[22:23], v[0:1], v[12:13]
	v_mul_f32_e32 v0, v5, v5
	v_fmac_f32_e32 v25, v19, v19
	v_pk_add_f32 v[18:19], v[6:7], v[10:11]
	v_fmac_f32_e32 v0, v4, v4
	v_fmac_f32_e32 v0, v18, v18
	v_fmac_f32_e32 v0, v19, v19
	v_lshlrev_b32_e32 v14, 16, v35
	v_and_b32_e32 v15, 0xffff0000, v35
	v_fmac_f32_e32 v0, v22, v22
	v_pk_add_f32 v[20:21], v[2:3], v[14:15]
	v_fmac_f32_e32 v0, v23, v23
	v_fmac_f32_e32 v25, v16, v16
	v_fmac_f32_e32 v0, v20, v20
	v_fmac_f32_e32 v25, v17, v17
	v_fmac_f32_e32 v0, v21, v21
	v_add_f32_e32 v14, v25, v0
	v_cvt_pk_bf16_f32 v16, v4, v5
	ds_bpermute_b32 v1, v169, v110
	ds_bpermute_b32 v2, v169, v102
	ds_bpermute_b32 v4, v169, v86
	ds_bpermute_b32 v6, v169, v68
	ds_bpermute_b32 v8, v169, v69
	ds_bpermute_b32 v10, v169, v62
	ds_bpermute_b32 v12, v169, v24
	ds_bpermute_b32 v15, v169, v14
	s_waitcnt lgkmcnt(0)
	v_add_f32_e32 v0, v110, v1
	v_add_f32_e32 v2, v102, v2
	v_add_f32_e32 v4, v86, v4
	v_add_f32_e32 v6, v68, v6
	v_add_f32_e32 v8, v69, v8
	v_add_f32_e32 v10, v62, v10
	v_add_f32_e32 v12, v24, v12
	v_add_f32_e32 v14, v14, v15
	ds_bpermute_b32 v1, v170, v0
	ds_bpermute_b32 v3, v170, v2
	ds_bpermute_b32 v5, v170, v4
	ds_bpermute_b32 v7, v170, v6
	ds_bpermute_b32 v9, v170, v8
	ds_bpermute_b32 v11, v170, v10
	ds_bpermute_b32 v13, v170, v12
	ds_bpermute_b32 v15, v170, v14
	v_cvt_pk_bf16_f32 v17, v18, v19
	v_cvt_pk_bf16_f32 v18, v22, v23
	v_cvt_pk_bf16_f32 v19, v20, v21
	global_store_dwordx4 v[36:37], v[16:19], off offset:256
	s_and_saveexec_b64 s[42:43], s[4:5]
	s_cbranch_execz .LBB0_820
	s_waitcnt lgkmcnt(6)
	v_add_f32_e32 v2, v2, v3
	v_add_f32_e32 v0, v0, v1
	v_add_u32_e32 v1, s72, v171
	s_waitcnt lgkmcnt(2)
	v_add_f32_e32 v10, v10, v11
	v_add_f32_e32 v8, v8, v9
	v_add_f32_e32 v6, v6, v7
	v_add_f32_e32 v4, v4, v5
	ds_write2st64_b32 v1, v0, v2 offset1:1
	ds_write2st64_b32 v1, v4, v6 offset0:2 offset1:3
	v_add_u32_e32 v0, s72, v175
	s_waitcnt lgkmcnt(2)
	v_add_f32_e32 v14, v14, v15
	v_add_f32_e32 v12, v12, v13
	ds_write2st64_b32 v0, v8, v10 offset1:1
	ds_write2st64_b32 v0, v12, v14 offset0:2 offset1:3

.LBB0_889:
	ds_read_b128 v[128:131], v181
	ds_read_b128 v[132:135], v181 offset:1024
	ds_read_b128 v[136:139], v181 offset:2048
	ds_read_b128 v[140:143], v181 offset:3072
	s_add_u32 s42, s40, 0xfffc0080
	s_addc_u32 s43, s41, -1
	s_cmp_eq_u32 s80, 12
	s_cselect_b32 s45, s37, s43
	s_cselect_b32 s44, s36, s42
	s_cselect_b32 s43, s39, s79
	s_cselect_b32 s42, s38, s78
	v_lshl_add_u64 v[166:167], s[40:41], 0, v[152:153]
	s_add_i32 m0, s50, 0xc000
	ds_read_b128 v[158:161], v182
	ds_read_b128 v[162:165], v182 offset:1024
	ds_read_b128 v[184:187], v182 offset:2048
	ds_read_b128 v[188:191], v182 offset:3072
	ds_read_b128 v[192:195], v182 offset:4096
	ds_read_b128 v[200:203], v182 offset:5120
	ds_read_b128 v[204:207], v182 offset:6144
	ds_read_b128 v[208:211], v182 offset:7168
	global_load_lds_dwordx4 v[166:167], off
	v_lshl_add_u64 v[166:167], s[40:41], 0, v[154:155]
	s_add_i32 m0, s50, 0xe000
	s_nop 0
	global_load_lds_dwordx4 v[166:167], off
	s_waitcnt lgkmcnt(8)
	s_barrier
	s_waitcnt lgkmcnt(0)
	s_setprio 1
	s_waitcnt lgkmcnt(0)
	v_mfma_f32_16x16x32_bf16 v[124:127], v[128:131], v[158:161], v[124:127]
	v_mfma_f32_16x16x32_bf16 v[120:123], v[136:139], v[158:161], v[120:123]
	v_mfma_f32_16x16x32_bf16 v[116:119], v[128:131], v[184:187], v[116:119]
	v_mfma_f32_16x16x32_bf16 v[108:111], v[136:139], v[184:187], v[108:111]
	v_mfma_f32_16x16x32_bf16 v[92:95], v[128:131], v[192:195], v[92:95]
	v_mfma_f32_16x16x32_bf16 v[88:91], v[136:139], v[192:195], v[88:91]
	v_mfma_f32_16x16x32_bf16 v[76:79], v[128:131], v[204:207], v[76:79]
	v_mfma_f32_16x16x32_bf16 v[72:75], v[136:139], v[204:207], v[72:75]
	v_mfma_f32_16x16x32_bf16 v[124:127], v[132:135], v[162:165], v[124:127]
	v_mfma_f32_16x16x32_bf16 v[120:123], v[140:143], v[162:165], v[120:123]
	v_mfma_f32_16x16x32_bf16 v[116:119], v[132:135], v[188:191], v[116:119]
	v_mfma_f32_16x16x32_bf16 v[108:111], v[140:143], v[188:191], v[108:111]
	v_mfma_f32_16x16x32_bf16 v[92:95], v[132:135], v[200:203], v[92:95]
	v_mfma_f32_16x16x32_bf16 v[88:91], v[140:143], v[200:203], v[88:91]
	v_mfma_f32_16x16x32_bf16 v[76:79], v[132:135], v[208:211], v[76:79]
	v_mfma_f32_16x16x32_bf16 v[72:75], v[140:143], v[208:211], v[72:75]
	s_setprio 0
	s_barrier
	s_add_i32 s81, s70, s49
	v_lshl_add_u64 v[166:167], s[42:43], 0, v[146:147]
	s_mov_b32 m0, s81
	ds_read_b128 v[212:215], v183
	ds_read_b128 v[216:219], v183 offset:1024
	ds_read_b128 v[220:223], v183 offset:2048
	ds_read_b128 v[224:227], v183 offset:3072
	global_load_lds_dwordx4 v[166:167], off
	v_lshl_add_u64 v[228:229], s[42:43], 0, v[150:151]
	s_add_i32 m0, s81, 0x2000
	s_nop 0
	global_load_lds_dwordx4 v[228:229], off
	s_barrier
	s_waitcnt lgkmcnt(0)
	s_setprio 1
	s_waitcnt lgkmcnt(0)
	v_mfma_f32_16x16x32_bf16 v[112:115], v[212:215], v[158:161], v[112:115]
	v_mfma_f32_16x16x32_bf16 v[104:107], v[220:223], v[158:161], v[104:107]
	v_mfma_f32_16x16x32_bf16 v[100:103], v[212:215], v[184:187], v[100:103]
	v_mfma_f32_16x16x32_bf16 v[96:99], v[220:223], v[184:187], v[96:99]
	v_mfma_f32_16x16x32_bf16 v[84:87], v[212:215], v[192:195], v[84:87]
	v_mfma_f32_16x16x32_bf16 v[80:83], v[220:223], v[192:195], v[80:83]
	v_mfma_f32_16x16x32_bf16 v[68:71], v[212:215], v[204:207], v[68:71]
	v_mfma_f32_16x16x32_bf16 v[64:67], v[220:223], v[204:207], v[64:67]
	v_mfma_f32_16x16x32_bf16 v[112:115], v[216:219], v[162:165], v[112:115]
	v_mfma_f32_16x16x32_bf16 v[104:107], v[224:227], v[162:165], v[104:107]
	v_mfma_f32_16x16x32_bf16 v[100:103], v[216:219], v[188:191], v[100:103]
	v_mfma_f32_16x16x32_bf16 v[96:99], v[224:227], v[188:191], v[96:99]
	v_mfma_f32_16x16x32_bf16 v[84:87], v[216:219], v[200:203], v[84:87]
	v_mfma_f32_16x16x32_bf16 v[80:83], v[224:227], v[200:203], v[80:83]
	v_mfma_f32_16x16x32_bf16 v[68:71], v[216:219], v[208:211], v[68:71]
	v_mfma_f32_16x16x32_bf16 v[64:67], v[224:227], v[208:211], v[64:67]
	s_setprio 0
	s_mov_b32 m0, s50
	v_lshl_add_u64 v[230:231], s[44:45], 0, v[144:145]
	s_barrier
	ds_read_b128 v[158:161], v182 offset:16384
	ds_read_b128 v[162:165], v182 offset:17408
	ds_read_b128 v[184:187], v182 offset:18432
	ds_read_b128 v[188:191], v182 offset:19456
	ds_read_b128 v[192:195], v182 offset:20480
	ds_read_b128 v[200:203], v182 offset:21504
	ds_read_b128 v[204:207], v182 offset:22528
	ds_read_b128 v[208:211], v182 offset:23552
	global_load_lds_dwordx4 v[230:231], off
	v_lshl_add_u64 v[232:233], s[44:45], 0, v[148:149]
	s_mov_b32 m0, s51
	s_nop 0
	global_load_lds_dwordx4 v[232:233], off
	s_barrier
	s_waitcnt lgkmcnt(0)
	s_setprio 1
	s_waitcnt lgkmcnt(0)
	v_mfma_f32_16x16x32_bf16 v[60:63], v[128:131], v[158:161], v[60:63]
	v_mfma_f32_16x16x32_bf16 v[56:59], v[136:139], v[158:161], v[56:59]
	v_mfma_f32_16x16x32_bf16 v[44:47], v[128:131], v[184:187], v[44:47]
	v_mfma_f32_16x16x32_bf16 v[40:43], v[136:139], v[184:187], v[40:43]
	v_mfma_f32_16x16x32_bf16 v[28:31], v[128:131], v[192:195], v[28:31]
	v_mfma_f32_16x16x32_bf16 v[24:27], v[136:139], v[192:195], v[24:27]
	v_mfma_f32_16x16x32_bf16 v[16:19], v[128:131], v[204:207], v[16:19]
	v_mfma_f32_16x16x32_bf16 v[8:11], v[136:139], v[204:207], v[8:11]
	v_mfma_f32_16x16x32_bf16 v[60:63], v[132:135], v[162:165], v[60:63]
	v_mfma_f32_16x16x32_bf16 v[56:59], v[140:143], v[162:165], v[56:59]
	v_mfma_f32_16x16x32_bf16 v[44:47], v[132:135], v[188:191], v[44:47]
	v_mfma_f32_16x16x32_bf16 v[40:43], v[140:143], v[188:191], v[40:43]
	v_mfma_f32_16x16x32_bf16 v[28:31], v[132:135], v[200:203], v[28:31]
	v_mfma_f32_16x16x32_bf16 v[24:27], v[140:143], v[200:203], v[24:27]
	v_mfma_f32_16x16x32_bf16 v[16:19], v[132:135], v[208:211], v[16:19]
	v_mfma_f32_16x16x32_bf16 v[8:11], v[140:143], v[208:211], v[8:11]
	s_setprio 0
	s_barrier
	s_add_u32 s82, s42, 0x40000
	s_addc_u32 s83, s43, 0
	s_add_i32 s81, s71, s49
	v_lshl_add_u64 v[128:129], s[82:83], 0, v[146:147]
	s_mov_b32 m0, s81
	s_nop 0
	global_load_lds_dwordx4 v[128:129], off
	v_lshl_add_u64 v[128:129], s[82:83], 0, v[150:151]
	s_add_i32 m0, s81, 0x2000
	s_nop 0
	global_load_lds_dwordx4 v[128:129], off
	s_waitcnt vmcnt(6)
	s_barrier
	s_setprio 1
	v_mfma_f32_16x16x32_bf16 v[52:55], v[212:215], v[158:161], v[52:55]
	v_mfma_f32_16x16x32_bf16 v[48:51], v[220:223], v[158:161], v[48:51]
	v_mfma_f32_16x16x32_bf16 v[36:39], v[212:215], v[184:187], v[36:39]
	v_mfma_f32_16x16x32_bf16 v[32:35], v[220:223], v[184:187], v[32:35]
	v_mfma_f32_16x16x32_bf16 v[20:23], v[212:215], v[192:195], v[20:23]
	v_mfma_f32_16x16x32_bf16 v[12:15], v[220:223], v[192:195], v[12:15]
	v_mfma_f32_16x16x32_bf16 v[4:7], v[212:215], v[204:207], v[4:7]
	v_mfma_f32_16x16x32_bf16 v[0:3], v[220:223], v[204:207], v[0:3]
	v_mfma_f32_16x16x32_bf16 v[52:55], v[216:219], v[162:165], v[52:55]
	v_mfma_f32_16x16x32_bf16 v[48:51], v[224:227], v[162:165], v[48:51]
	v_mfma_f32_16x16x32_bf16 v[36:39], v[216:219], v[188:191], v[36:39]
	v_mfma_f32_16x16x32_bf16 v[32:35], v[224:227], v[188:191], v[32:35]
	v_mfma_f32_16x16x32_bf16 v[20:23], v[216:219], v[200:203], v[20:23]
	v_mfma_f32_16x16x32_bf16 v[12:15], v[224:227], v[200:203], v[12:15]
	v_mfma_f32_16x16x32_bf16 v[4:7], v[216:219], v[208:211], v[4:7]
	v_mfma_f32_16x16x32_bf16 v[0:3], v[224:227], v[208:211], v[0:3]
	s_setprio 0
	s_add_i32 s81, 0, 0x18000
	v_add_u32_e32 v140, s81, v169
	s_barrier
	ds_read_b128 v[128:131], v140
	ds_read_b128 v[132:135], v140 offset:1024
	ds_read_b128 v[136:139], v140 offset:2048
	ds_read_b128 v[140:143], v140 offset:3072
	s_add_u32 s44, s44, 0x40000
	s_addc_u32 s45, s45, 0
	s_mov_b32 m0, s52
	v_lshl_add_u64 v[212:213], s[44:45], 0, v[144:145]
	ds_read_b128 v[158:161], v182 offset:32768
	ds_read_b128 v[162:165], v182 offset:33792
	ds_read_b128 v[184:187], v182 offset:34816
	ds_read_b128 v[188:191], v182 offset:35840
	ds_read_b128 v[192:195], v182 offset:36864
	ds_read_b128 v[200:203], v182 offset:37888
	ds_read_b128 v[204:207], v182 offset:38912
	ds_read_b128 v[208:211], v182 offset:39936
	global_load_lds_dwordx4 v[212:213], off
	v_lshl_add_u64 v[212:213], s[44:45], 0, v[148:149]
	s_mov_b32 m0, s53
	s_nop 0
	global_load_lds_dwordx4 v[212:213], off
	s_waitcnt lgkmcnt(8)
	s_barrier
	s_waitcnt lgkmcnt(0)
	s_setprio 1
	s_waitcnt lgkmcnt(0)
	v_mfma_f32_16x16x32_bf16 v[124:127], v[128:131], v[158:161], v[124:127]
	v_mfma_f32_16x16x32_bf16 v[120:123], v[136:139], v[158:161], v[120:123]
	v_mfma_f32_16x16x32_bf16 v[116:119], v[128:131], v[184:187], v[116:119]
	v_mfma_f32_16x16x32_bf16 v[108:111], v[136:139], v[184:187], v[108:111]
	v_mfma_f32_16x16x32_bf16 v[92:95], v[128:131], v[192:195], v[92:95]
	v_mfma_f32_16x16x32_bf16 v[88:91], v[136:139], v[192:195], v[88:91]
	v_mfma_f32_16x16x32_bf16 v[76:79], v[128:131], v[204:207], v[76:79]
	v_mfma_f32_16x16x32_bf16 v[72:75], v[136:139], v[204:207], v[72:75]
	v_mfma_f32_16x16x32_bf16 v[124:127], v[132:135], v[162:165], v[124:127]
	v_mfma_f32_16x16x32_bf16 v[120:123], v[140:143], v[162:165], v[120:123]
	v_mfma_f32_16x16x32_bf16 v[116:119], v[132:135], v[188:191], v[116:119]
	v_mfma_f32_16x16x32_bf16 v[108:111], v[140:143], v[188:191], v[108:111]
	v_mfma_f32_16x16x32_bf16 v[92:95], v[132:135], v[200:203], v[92:95]
	v_mfma_f32_16x16x32_bf16 v[88:91], v[140:143], v[200:203], v[88:91]
	v_mfma_f32_16x16x32_bf16 v[76:79], v[132:135], v[208:211], v[76:79]
	v_mfma_f32_16x16x32_bf16 v[72:75], v[140:143], v[208:211], v[72:75]
	s_setprio 0
	s_barrier
	s_add_i32 s44, 0, 0x1c000
	s_add_i32 s45, s81, s49
	v_add_u32_e32 v224, s44, v169
	v_lshl_add_u64 v[166:167], v[166:167], 0, s[20:21]
	s_mov_b32 m0, s45
	ds_read_b128 v[212:215], v224
	ds_read_b128 v[216:219], v224 offset:1024
	ds_read_b128 v[220:223], v224 offset:2048
	ds_read_b128 v[224:227], v224 offset:3072
	global_load_lds_dwordx4 v[166:167], off
	v_lshl_add_u64 v[166:167], v[228:229], 0, s[20:21]
	s_add_i32 m0, s45, 0x2000
	s_nop 0
	global_load_lds_dwordx4 v[166:167], off
	s_barrier
	s_waitcnt lgkmcnt(0)
	s_setprio 1
	s_waitcnt lgkmcnt(0)
	v_mfma_f32_16x16x32_bf16 v[112:115], v[212:215], v[158:161], v[112:115]
	v_mfma_f32_16x16x32_bf16 v[104:107], v[220:223], v[158:161], v[104:107]
	v_mfma_f32_16x16x32_bf16 v[100:103], v[212:215], v[184:187], v[100:103]
	v_mfma_f32_16x16x32_bf16 v[96:99], v[220:223], v[184:187], v[96:99]
	v_mfma_f32_16x16x32_bf16 v[84:87], v[212:215], v[192:195], v[84:87]
	v_mfma_f32_16x16x32_bf16 v[80:83], v[220:223], v[192:195], v[80:83]
	v_mfma_f32_16x16x32_bf16 v[68:71], v[212:215], v[204:207], v[68:71]
	v_mfma_f32_16x16x32_bf16 v[64:67], v[220:223], v[204:207], v[64:67]
	v_mfma_f32_16x16x32_bf16 v[112:115], v[216:219], v[162:165], v[112:115]
	v_mfma_f32_16x16x32_bf16 v[104:107], v[224:227], v[162:165], v[104:107]
	v_mfma_f32_16x16x32_bf16 v[100:103], v[216:219], v[188:191], v[100:103]
	v_mfma_f32_16x16x32_bf16 v[96:99], v[224:227], v[188:191], v[96:99]
	v_mfma_f32_16x16x32_bf16 v[84:87], v[216:219], v[200:203], v[84:87]
	v_mfma_f32_16x16x32_bf16 v[80:83], v[224:227], v[200:203], v[80:83]
	v_mfma_f32_16x16x32_bf16 v[68:71], v[216:219], v[208:211], v[68:71]
	v_mfma_f32_16x16x32_bf16 v[64:67], v[224:227], v[208:211], v[64:67]
	s_setprio 0
	s_mov_b32 m0, s65
	v_lshl_add_u64 v[166:167], v[230:231], 0, s[20:21]
	s_barrier
	ds_read_b128 v[158:161], v182 offset:49152
	ds_read_b128 v[162:165], v182 offset:50176
	ds_read_b128 v[184:187], v182 offset:51200
	ds_read_b128 v[188:191], v182 offset:52224
	ds_read_b128 v[192:195], v182 offset:53248
	ds_read_b128 v[200:203], v182 offset:54272
	ds_read_b128 v[204:207], v182 offset:55296
	ds_read_b128 v[208:211], v182 offset:56320
	global_load_lds_dwordx4 v[166:167], off
	v_lshl_add_u64 v[166:167], v[232:233], 0, s[20:21]
	s_mov_b32 m0, s66
	s_nop 0
	global_load_lds_dwordx4 v[166:167], off
	s_barrier
	s_waitcnt lgkmcnt(0)
	s_setprio 1
	s_waitcnt lgkmcnt(0)
	v_mfma_f32_16x16x32_bf16 v[60:63], v[128:131], v[158:161], v[60:63]
	v_mfma_f32_16x16x32_bf16 v[56:59], v[136:139], v[158:161], v[56:59]
	v_mfma_f32_16x16x32_bf16 v[44:47], v[128:131], v[184:187], v[44:47]
	v_mfma_f32_16x16x32_bf16 v[40:43], v[136:139], v[184:187], v[40:43]
	v_mfma_f32_16x16x32_bf16 v[28:31], v[128:131], v[192:195], v[28:31]
	v_mfma_f32_16x16x32_bf16 v[24:27], v[136:139], v[192:195], v[24:27]
	v_mfma_f32_16x16x32_bf16 v[16:19], v[128:131], v[204:207], v[16:19]
	v_mfma_f32_16x16x32_bf16 v[8:11], v[136:139], v[204:207], v[8:11]
	v_mfma_f32_16x16x32_bf16 v[60:63], v[132:135], v[162:165], v[60:63]
	v_mfma_f32_16x16x32_bf16 v[56:59], v[140:143], v[162:165], v[56:59]
	v_mfma_f32_16x16x32_bf16 v[44:47], v[132:135], v[188:191], v[44:47]
	v_mfma_f32_16x16x32_bf16 v[40:43], v[140:143], v[188:191], v[40:43]
	v_mfma_f32_16x16x32_bf16 v[28:31], v[132:135], v[200:203], v[28:31]
	v_mfma_f32_16x16x32_bf16 v[24:27], v[140:143], v[200:203], v[24:27]
	v_mfma_f32_16x16x32_bf16 v[16:19], v[132:135], v[208:211], v[16:19]
	v_mfma_f32_16x16x32_bf16 v[8:11], v[140:143], v[208:211], v[8:11]
	s_setprio 0
	s_barrier
	s_add_u32 s42, s42, 0x40080
	s_addc_u32 s43, s43, 0
	s_add_i32 s44, s44, s49
	v_lshl_add_u64 v[128:129], s[42:43], 0, v[146:147]
	s_mov_b32 m0, s44
	s_nop 0
	global_load_lds_dwordx4 v[128:129], off
	v_lshl_add_u64 v[128:129], s[42:43], 0, v[150:151]
	s_add_i32 m0, s44, 0x2000
	s_nop 0
	global_load_lds_dwordx4 v[128:129], off
	s_waitcnt vmcnt(6)
	s_barrier
	s_setprio 1
	v_mfma_f32_16x16x32_bf16 v[52:55], v[212:215], v[158:161], v[52:55]
	v_mfma_f32_16x16x32_bf16 v[48:51], v[220:223], v[158:161], v[48:51]
	v_mfma_f32_16x16x32_bf16 v[36:39], v[212:215], v[184:187], v[36:39]
	v_mfma_f32_16x16x32_bf16 v[32:35], v[220:223], v[184:187], v[32:35]
	v_mfma_f32_16x16x32_bf16 v[20:23], v[212:215], v[192:195], v[20:23]
	v_mfma_f32_16x16x32_bf16 v[12:15], v[220:223], v[192:195], v[12:15]
	v_mfma_f32_16x16x32_bf16 v[4:7], v[212:215], v[204:207], v[4:7]
	v_mfma_f32_16x16x32_bf16 v[0:3], v[220:223], v[204:207], v[0:3]
	v_mfma_f32_16x16x32_bf16 v[52:55], v[216:219], v[162:165], v[52:55]
	v_mfma_f32_16x16x32_bf16 v[48:51], v[224:227], v[162:165], v[48:51]
	v_mfma_f32_16x16x32_bf16 v[36:39], v[216:219], v[188:191], v[36:39]
	v_mfma_f32_16x16x32_bf16 v[32:35], v[224:227], v[188:191], v[32:35]
	v_mfma_f32_16x16x32_bf16 v[20:23], v[216:219], v[200:203], v[20:23]
	v_mfma_f32_16x16x32_bf16 v[12:15], v[224:227], v[200:203], v[12:15]
	v_mfma_f32_16x16x32_bf16 v[4:7], v[216:219], v[208:211], v[4:7]
	v_mfma_f32_16x16x32_bf16 v[0:3], v[224:227], v[208:211], v[0:3]
	s_setprio 0
	s_add_i32 s80, s80, 2
	s_add_u32 s40, s40, 0x100
	s_addc_u32 s41, s41, 0
	s_add_u32 s78, s78, 0x100
	s_addc_u32 s79, s79, 0
	s_cmp_gt_u32 s80, 13
	s_barrier
	s_cbranch_scc0 .LBB0_889
	v_add_u32_e32 v158, s33, v168
	v_ashrrev_i32_e32 v159, 31, v158
	v_readlane_b32 s40, v254, 56
	v_add_u32_e32 v128, s64, v170
	v_lshlrev_b64 v[130:131], 11, v[158:159]
	v_readlane_b32 s41, v254, 57
	v_ashrrev_i32_e32 v129, 31, v128
	s_nop 0
	v_lshl_add_u64 v[130:131], s[40:41], 0, v[130:131]
	v_lshl_add_u64 v[160:161], v[128:129], 1, v[130:131]
	v_add_co_u32_e32 v192, vcc, s68, v160
	global_load_dwordx4 v[132:135], v[160:161], off
	global_load_dwordx4 v[140:143], v[160:161], off offset:256
	v_addc_co_u32_e32 v193, vcc, 0, v161, vcc
	global_load_dwordx4 v[184:187], v[192:193], off
	v_lshl_add_u64 v[164:165], v[160:161], 0, s[22:23]
	global_load_dwordx4 v[188:191], v[164:165], off offset:256
	v_add_co_u32_e32 v166, vcc, s61, v160
	v_lshl_add_u64 v[162:163], v[160:161], 0, s[24:25]
	s_nop 0
	v_addc_co_u32_e32 v167, vcc, 0, v161, vcc
	global_load_dwordx4 v[136:139], v[166:167], off
	global_load_dwordx4 v[128:131], v[162:163], off offset:256
	s_mov_b32 s98, s67
	s_mov_b32 s99, 0
	v_lshl_add_u64 v[246:247], v[160:161], 0, s[98:99]
	global_load_dwordx4 v[206:209], v[246:247], off
	v_lshl_add_u64 v[246:247], v[160:161], 0, s[26:27]
	global_load_dwordx4 v[210:213], v[246:247], off offset:256
	s_mov_b32 s98, s72
	s_mov_b32 s99, 0
	v_lshl_add_u64 v[246:247], v[160:161], 0, s[98:99]
	global_load_dwordx4 v[214:217], v[246:247], off
	v_lshl_add_u64 v[246:247], v[160:161], 0, s[18:19]
	global_load_dwordx4 v[218:221], v[246:247], off offset:256
	s_mov_b32 s98, s73
	s_mov_b32 s99, 0
	v_lshl_add_u64 v[246:247], v[160:161], 0, s[98:99]
	global_load_dwordx4 v[222:225], v[246:247], off
	v_lshl_add_u64 v[246:247], v[160:161], 0, s[28:29]
	global_load_dwordx4 v[226:229], v[246:247], off offset:256
	s_mov_b32 s98, s74
	s_mov_b32 s99, 0
	v_lshl_add_u64 v[246:247], v[160:161], 0, s[98:99]
	global_load_dwordx4 v[230:233], v[246:247], off
	v_lshl_add_u64 v[246:247], v[160:161], 0, s[30:31]
	global_load_dwordx4 v[234:237], v[246:247], off offset:256
	s_mov_b32 s98, s75
	s_mov_b32 s99, 0
	v_lshl_add_u64 v[246:247], v[160:161], 0, s[98:99]
	global_load_dwordx4 v[238:241], v[246:247], off
	v_lshl_add_u64 v[246:247], v[160:161], 0, s[34:35]
	global_load_dwordx4 v[242:245], v[246:247], off offset:256
	s_waitcnt vmcnt(10)
	v_lshlrev_b32_e32 v194, 16, v132
	v_and_b32_e32 v195, 0xffff0000, v132
	v_lshlrev_b32_e32 v200, 16, v134
	v_and_b32_e32 v201, 0xffff0000, v134
	v_pk_add_f32 v[124:125], v[124:125], v[194:195]
	v_lshlrev_b32_e32 v194, 16, v184
	v_and_b32_e32 v195, 0xffff0000, v184
	v_pk_add_f32 v[120:121], v[120:121], v[200:201]
	v_lshlrev_b32_e32 v184, 16, v185
	v_and_b32_e32 v185, 0xffff0000, v185
	v_lshlrev_b32_e32 v200, 16, v186
	v_and_b32_e32 v201, 0xffff0000, v186
	v_lshlrev_b32_e32 v186, 16, v187
	v_and_b32_e32 v187, 0xffff0000, v187
	v_pk_add_f32 v[116:117], v[116:117], v[194:195]
	v_pk_add_f32 v[118:119], v[118:119], v[184:185]
	v_pk_add_f32 v[184:185], v[110:111], v[186:187]
	v_mul_f32_e32 v111, v117, v117
	v_fmac_f32_e32 v111, v116, v116
	v_lshlrev_b32_e32 v132, 16, v133
	v_and_b32_e32 v133, 0xffff0000, v133
	v_lshlrev_b32_e32 v202, 16, v140
	v_and_b32_e32 v203, 0xffff0000, v140
	v_lshlrev_b32_e32 v140, 16, v141
	v_and_b32_e32 v141, 0xffff0000, v141
	v_lshlrev_b32_e32 v204, 16, v142
	v_and_b32_e32 v205, 0xffff0000, v142
	v_lshlrev_b32_e32 v142, 16, v143
	v_and_b32_e32 v143, 0xffff0000, v143
	v_fmac_f32_e32 v111, v118, v118
	v_lshlrev_b32_e32 v134, 16, v135
	v_and_b32_e32 v135, 0xffff0000, v135
	v_pk_add_f32 v[126:127], v[126:127], v[132:133]
	v_pk_add_f32 v[132:133], v[114:115], v[140:141]
	v_pk_add_f32 v[140:141], v[106:107], v[142:143]
	v_cvt_pk_bf16_f32 v106, v120, v121
	v_pk_add_f32 v[108:109], v[108:109], v[200:201]
	v_fmac_f32_e32 v111, v119, v119
	v_pk_add_f32 v[122:123], v[122:123], v[134:135]
	v_pk_add_f32 v[134:135], v[112:113], v[202:203]
	v_pk_add_f32 v[142:143], v[104:105], v[204:205]
	v_cvt_pk_bf16_f32 v104, v124, v125
	v_cvt_pk_bf16_f32 v105, v126, v127
	v_cvt_pk_bf16_f32 v107, v122, v123
	v_cvt_pk_bf16_f32 v112, v134, v135
	v_cvt_pk_bf16_f32 v113, v132, v133
	s_nop 0
	v_cvt_pk_bf16_f32 v114, v142, v143
	v_cvt_pk_bf16_f32 v115, v140, v141
	global_store_dwordx4 v[160:161], v[104:107], off
	v_fmac_f32_e32 v111, v108, v108
	global_store_dwordx4 v[160:161], v[112:115], off offset:256
	v_cvt_pk_bf16_f32 v106, v108, v109
	v_add_co_u32_e32 v108, vcc, s67, v160
	v_cvt_pk_bf16_f32 v104, v116, v117
	v_cvt_pk_bf16_f32 v105, v118, v119
	v_cvt_pk_bf16_f32 v107, v184, v185
	v_fmac_f32_e32 v111, v109, v109
	v_lshlrev_b32_e32 v112, 16, v188
	v_and_b32_e32 v113, 0xffff0000, v188
	v_lshlrev_b32_e32 v114, 16, v189
	v_and_b32_e32 v115, 0xffff0000, v189
	v_lshlrev_b32_e32 v116, 16, v190
	v_addc_co_u32_e32 v109, vcc, 0, v161, vcc
	v_and_b32_e32 v117, 0xffff0000, v190
	global_store_dwordx4 v[192:193], v[104:107], off
	v_lshlrev_b32_e32 v118, 16, v191
	v_and_b32_e32 v119, 0xffff0000, v191
	v_pk_add_f32 v[102:103], v[102:103], v[114:115]
	v_pk_add_f32 v[100:101], v[100:101], v[112:113]
	v_pk_add_f32 v[114:115], v[96:97], v[116:117]
	v_cvt_pk_bf16_f32 v96, v100, v101
	v_pk_add_f32 v[112:113], v[98:99], v[118:119]
	v_cvt_pk_bf16_f32 v97, v102, v103
	v_cvt_pk_bf16_f32 v98, v114, v115
	v_fmac_f32_e32 v111, v184, v184
	v_cvt_pk_bf16_f32 v99, v112, v113
	global_store_dwordx4 v[164:165], v[96:99], off offset:256
	v_fmac_f32_e32 v111, v185, v185
	v_lshlrev_b32_e32 v116, 16, v138
	v_mul_f32_e32 v96, v101, v101
	v_fmac_f32_e32 v96, v100, v100
	v_fmac_f32_e32 v96, v102, v102
	v_fmac_f32_e32 v96, v103, v103
	v_fmac_f32_e32 v96, v114, v114
	v_fmac_f32_e32 v96, v115, v115
	v_fmac_f32_e32 v96, v112, v112
	v_fmac_f32_e32 v96, v113, v113
	v_lshl_add_u64 v[100:101], v[160:161], 0, s[26:27]
	v_add_f32_e32 v102, v111, v96
	v_lshlrev_b32_e32 v112, 16, v136
	v_and_b32_e32 v113, 0xffff0000, v136
	v_lshlrev_b32_e32 v114, 16, v137
	v_and_b32_e32 v115, 0xffff0000, v137
	v_and_b32_e32 v117, 0xffff0000, v138
	v_lshlrev_b32_e32 v118, 16, v139
	v_and_b32_e32 v119, 0xffff0000, v139
	v_pk_add_f32 v[94:95], v[94:95], v[114:115]
	v_pk_add_f32 v[92:93], v[92:93], v[112:113]
	v_pk_add_f32 v[114:115], v[88:89], v[116:117]
	v_cvt_pk_bf16_f32 v88, v92, v93
	v_pk_add_f32 v[112:113], v[90:91], v[118:119]
	v_cvt_pk_bf16_f32 v89, v94, v95
	v_cvt_pk_bf16_f32 v90, v114, v115
	v_mul_f32_e32 v103, v93, v93
	v_cvt_pk_bf16_f32 v91, v112, v113
	global_store_dwordx4 v[166:167], v[88:91], off
	v_fmac_f32_e32 v103, v92, v92
	v_fmac_f32_e32 v103, v94, v94
	v_add_co_u32_e32 v88, vcc, s72, v160
	v_fmac_f32_e32 v103, v95, v95
	s_nop 0
	v_addc_co_u32_e32 v89, vcc, 0, v161, vcc
	v_fmac_f32_e32 v103, v114, v114
	v_fmac_f32_e32 v103, v115, v115
	v_fmac_f32_e32 v103, v112, v112
	v_fmac_f32_e32 v103, v113, v113
	v_lshlrev_b32_e32 v94, 16, v128
	v_and_b32_e32 v95, 0xffff0000, v128
	v_lshlrev_b32_e32 v112, 16, v129
	v_and_b32_e32 v113, 0xffff0000, v129
	v_lshlrev_b32_e32 v114, 16, v130
	v_and_b32_e32 v115, 0xffff0000, v130
	v_lshlrev_b32_e32 v116, 16, v131
	v_and_b32_e32 v117, 0xffff0000, v131
	v_pk_add_f32 v[86:87], v[86:87], v[112:113]
	v_pk_add_f32 v[84:85], v[84:85], v[94:95]
	v_pk_add_f32 v[112:113], v[80:81], v[114:115]
	v_cvt_pk_bf16_f32 v80, v84, v85
	v_pk_add_f32 v[94:95], v[82:83], v[116:117]
	v_cvt_pk_bf16_f32 v81, v86, v87
	v_cvt_pk_bf16_f32 v82, v112, v113
	v_mul_f32_e32 v125, v125, v125
	v_cvt_pk_bf16_f32 v83, v94, v95
	global_store_dwordx4 v[162:163], v[80:83], off offset:256
	v_mul_f32_e32 v135, v135, v135
	v_fmac_f32_e32 v125, v124, v124
	v_mul_f32_e32 v80, v85, v85
	v_fmac_f32_e32 v80, v84, v84
	v_fmac_f32_e32 v80, v86, v86
	v_fmac_f32_e32 v80, v87, v87
	v_fmac_f32_e32 v80, v112, v112
	v_fmac_f32_e32 v80, v113, v113
	v_fmac_f32_e32 v80, v94, v94
	v_fmac_f32_e32 v80, v95, v95
	v_lshl_add_u64 v[84:85], v[160:161], 0, s[18:19]
	v_add_f32_e32 v86, v103, v80
	s_waitcnt vmcnt(12)
	s_nop 1
	v_mov_b32_e32 v104, v206
	v_mov_b32_e32 v105, v207
	v_mov_b32_e32 v106, v208
	v_mov_b32_e32 v107, v209
	v_mov_b32_e32 v96, v210
	v_mov_b32_e32 v97, v211
	v_mov_b32_e32 v98, v212
	v_mov_b32_e32 v99, v213
	v_mov_b32_e32 v90, v214
	v_mov_b32_e32 v91, v215
	v_mov_b32_e32 v92, v216
	v_mov_b32_e32 v93, v217
	v_mov_b32_e32 v80, v218
	v_mov_b32_e32 v81, v219
	v_mov_b32_e32 v82, v220
	v_mov_b32_e32 v83, v221
	v_lshlrev_b32_e32 v94, 16, v104
	v_and_b32_e32 v95, 0xffff0000, v104
	v_pk_add_f32 v[76:77], v[76:77], v[94:95]
	v_lshlrev_b32_e32 v104, 16, v105
	v_and_b32_e32 v105, 0xffff0000, v105
	v_mul_f32_e32 v87, v77, v77
	v_pk_add_f32 v[78:79], v[78:79], v[104:105]
	v_fmac_f32_e32 v87, v76, v76
	v_lshlrev_b32_e32 v112, 16, v106
	v_and_b32_e32 v113, 0xffff0000, v106
	v_fmac_f32_e32 v87, v78, v78
	v_pk_add_f32 v[104:105], v[72:73], v[112:113]
	v_fmac_f32_e32 v87, v79, v79
	v_lshlrev_b32_e32 v106, 16, v107
	v_and_b32_e32 v107, 0xffff0000, v107
	v_fmac_f32_e32 v87, v104, v104
	v_pk_add_f32 v[94:95], v[74:75], v[106:107]
	v_fmac_f32_e32 v87, v105, v105
	v_fmac_f32_e32 v87, v94, v94
	v_cvt_pk_bf16_f32 v73, v78, v79
	v_cvt_pk_bf16_f32 v75, v94, v95
	v_fmac_f32_e32 v87, v95, v95
	v_lshlrev_b32_e32 v78, 16, v96
	v_and_b32_e32 v79, 0xffff0000, v96
	v_lshlrev_b32_e32 v94, 16, v97
	v_and_b32_e32 v95, 0xffff0000, v97
	v_lshlrev_b32_e32 v96, 16, v98
	v_and_b32_e32 v97, 0xffff0000, v98
	v_cvt_pk_bf16_f32 v72, v76, v77
	v_add_co_u32_e32 v76, vcc, s73, v160
	v_lshlrev_b32_e32 v98, 16, v99
	v_and_b32_e32 v99, 0xffff0000, v99
	v_pk_add_f32 v[70:71], v[70:71], v[94:95]
	v_pk_add_f32 v[68:69], v[68:69], v[78:79]
	v_pk_add_f32 v[94:95], v[64:65], v[96:97]
	v_cvt_pk_bf16_f32 v64, v68, v69
	v_cvt_pk_bf16_f32 v74, v104, v105
	v_addc_co_u32_e32 v77, vcc, 0, v161, vcc
	v_pk_add_f32 v[78:79], v[66:67], v[98:99]
	v_cvt_pk_bf16_f32 v65, v70, v71
	v_cvt_pk_bf16_f32 v66, v94, v95
	global_store_dwordx4 v[108:109], v[72:75], off
	v_cvt_pk_bf16_f32 v67, v78, v79
	global_store_dwordx4 v[100:101], v[64:67], off offset:256
	v_fmac_f32_e32 v135, v134, v134
	v_mul_f32_e32 v64, v69, v69
	v_fmac_f32_e32 v64, v68, v68
	v_fmac_f32_e32 v64, v70, v70
	v_fmac_f32_e32 v64, v71, v71
	v_fmac_f32_e32 v64, v94, v94
	v_fmac_f32_e32 v64, v95, v95
	v_fmac_f32_e32 v64, v78, v78
	v_fmac_f32_e32 v64, v79, v79
	v_add_f32_e32 v68, v87, v64
	v_lshlrev_b32_e32 v64, 16, v91
	v_and_b32_e32 v65, 0xffff0000, v91
	v_lshl_add_u64 v[66:67], v[160:161], 0, s[28:29]
	v_lshlrev_b32_e32 v70, 16, v90
	v_and_b32_e32 v71, 0xffff0000, v90
	v_lshlrev_b32_e32 v78, 16, v92
	v_and_b32_e32 v79, 0xffff0000, v92
	v_lshlrev_b32_e32 v90, 16, v93
	v_and_b32_e32 v91, 0xffff0000, v93
	v_pk_add_f32 v[92:93], v[62:63], v[64:65]
	v_pk_add_f32 v[60:61], v[60:61], v[70:71]
	v_pk_add_f32 v[78:79], v[56:57], v[78:79]
	v_mul_f32_e32 v69, v61, v61
	v_fmac_f32_e32 v69, v60, v60
	v_fmac_f32_e32 v69, v92, v92
	v_fmac_f32_e32 v69, v93, v93
	v_fmac_f32_e32 v69, v78, v78
	v_pk_add_f32 v[70:71], v[58:59], v[90:91]
	v_fmac_f32_e32 v69, v79, v79
	v_fmac_f32_e32 v69, v70, v70
	v_cvt_pk_bf16_f32 v58, v78, v79
	v_cvt_pk_bf16_f32 v59, v70, v71
	v_fmac_f32_e32 v69, v71, v71
	v_lshlrev_b32_e32 v70, 16, v80
	v_and_b32_e32 v71, 0xffff0000, v80
	v_lshlrev_b32_e32 v78, 16, v81
	v_and_b32_e32 v79, 0xffff0000, v81
	v_lshlrev_b32_e32 v80, 16, v82
	v_and_b32_e32 v81, 0xffff0000, v82
	v_lshlrev_b32_e32 v82, 16, v83
	v_and_b32_e32 v83, 0xffff0000, v83
	v_pk_add_f32 v[54:55], v[54:55], v[78:79]
	v_pk_add_f32 v[52:53], v[52:53], v[70:71]
	v_pk_add_f32 v[78:79], v[48:49], v[80:81]
	v_cvt_pk_bf16_f32 v48, v52, v53
	v_pk_add_f32 v[70:71], v[50:51], v[82:83]
	v_cvt_pk_bf16_f32 v49, v54, v55
	v_cvt_pk_bf16_f32 v50, v78, v79
	v_cvt_pk_bf16_f32 v56, v60, v61
	v_add_co_u32_e32 v60, vcc, s74, v160
	v_cvt_pk_bf16_f32 v51, v70, v71
	global_store_dwordx4 v[84:85], v[48:51], off offset:256
	v_cvt_pk_bf16_f32 v57, v92, v93
	s_nop 0
	v_addc_co_u32_e32 v61, vcc, 0, v161, vcc
	v_mul_f32_e32 v48, v53, v53
	v_fmac_f32_e32 v48, v52, v52
	v_fmac_f32_e32 v48, v54, v54
	v_fmac_f32_e32 v48, v55, v55
	v_fmac_f32_e32 v48, v78, v78
	global_store_dwordx4 v[88:89], v[56:59], off
	v_fmac_f32_e32 v48, v79, v79
	v_fmac_f32_e32 v48, v70, v70
	v_fmac_f32_e32 v48, v71, v71
	v_add_f32_e32 v69, v69, v48
	v_lshl_add_u64 v[48:49], v[160:161], 0, s[30:31]
	v_fmac_f32_e32 v125, v126, v126
	v_fmac_f32_e32 v135, v132, v132
	v_fmac_f32_e32 v125, v127, v127
	v_fmac_f32_e32 v135, v133, v133
	v_fmac_f32_e32 v125, v120, v120
	v_fmac_f32_e32 v135, v142, v142
	v_fmac_f32_e32 v125, v121, v121
	v_fmac_f32_e32 v135, v143, v143
	v_fmac_f32_e32 v125, v122, v122
	s_waitcnt vmcnt(12)
	s_nop 1
	v_mov_b32_e32 v72, v222
	v_mov_b32_e32 v73, v223
	v_mov_b32_e32 v74, v224
	v_mov_b32_e32 v75, v225
	v_mov_b32_e32 v62, v226
	v_mov_b32_e32 v63, v227
	v_mov_b32_e32 v64, v228
	v_mov_b32_e32 v65, v229
	v_mov_b32_e32 v56, v230
	v_mov_b32_e32 v57, v231
	v_mov_b32_e32 v58, v232
	v_mov_b32_e32 v59, v233
	v_mov_b32_e32 v50, v234
	v_mov_b32_e32 v51, v235
	v_mov_b32_e32 v52, v236
	v_mov_b32_e32 v53, v237
	v_lshlrev_b32_e32 v54, 16, v72
	v_and_b32_e32 v55, 0xffff0000, v72
	v_lshlrev_b32_e32 v70, 16, v73
	v_and_b32_e32 v71, 0xffff0000, v73
	v_lshlrev_b32_e32 v72, 16, v74
	v_and_b32_e32 v73, 0xffff0000, v74
	v_pk_add_f32 v[44:45], v[44:45], v[54:55]
	v_pk_add_f32 v[46:47], v[46:47], v[70:71]
	v_pk_add_f32 v[70:71], v[40:41], v[72:73]
	v_mul_f32_e32 v72, v45, v45
	v_fmac_f32_e32 v72, v44, v44
	v_fmac_f32_e32 v72, v46, v46
	v_fmac_f32_e32 v72, v47, v47
	v_lshlrev_b32_e32 v74, 16, v75
	v_and_b32_e32 v75, 0xffff0000, v75
	v_cvt_pk_bf16_f32 v40, v44, v45
	v_fmac_f32_e32 v72, v70, v70
	v_add_co_u32_e32 v44, vcc, s75, v160
	v_pk_add_f32 v[54:55], v[42:43], v[74:75]
	v_cvt_pk_bf16_f32 v41, v46, v47
	v_cvt_pk_bf16_f32 v42, v70, v71
	v_fmac_f32_e32 v72, v71, v71
	v_cvt_pk_bf16_f32 v43, v54, v55
	v_addc_co_u32_e32 v45, vcc, 0, v161, vcc
	global_store_dwordx4 v[76:77], v[40:43], off
	v_fmac_f32_e32 v72, v54, v54
	v_lshlrev_b32_e32 v46, 16, v62
	v_and_b32_e32 v47, 0xffff0000, v62
	v_fmac_f32_e32 v72, v55, v55
	v_lshlrev_b32_e32 v54, 16, v63
	v_and_b32_e32 v55, 0xffff0000, v63
	v_lshlrev_b32_e32 v62, 16, v64
	v_and_b32_e32 v63, 0xffff0000, v64
	v_pk_add_f32 v[36:37], v[36:37], v[46:47]
	v_lshlrev_b32_e32 v64, 16, v65
	v_and_b32_e32 v65, 0xffff0000, v65
	v_pk_add_f32 v[38:39], v[38:39], v[54:55]
	v_pk_add_f32 v[54:55], v[32:33], v[62:63]
	v_mul_f32_e32 v62, v37, v37
	v_pk_add_f32 v[46:47], v[34:35], v[64:65]
	v_cvt_pk_bf16_f32 v32, v36, v37
	v_cvt_pk_bf16_f32 v33, v38, v39
	v_cvt_pk_bf16_f32 v34, v54, v55
	v_fmac_f32_e32 v62, v36, v36
	v_cvt_pk_bf16_f32 v35, v46, v47
	v_lshl_add_u64 v[36:37], v[160:161], 0, s[34:35]
	global_store_dwordx4 v[66:67], v[32:35], off offset:256
	v_fmac_f32_e32 v62, v38, v38
	v_fmac_f32_e32 v62, v39, v39
	v_fmac_f32_e32 v62, v54, v54
	v_fmac_f32_e32 v62, v55, v55
	v_fmac_f32_e32 v62, v46, v46
	v_fmac_f32_e32 v62, v47, v47
	v_fmac_f32_e32 v135, v140, v140
	v_fmac_f32_e32 v125, v123, v123
	v_fmac_f32_e32 v135, v141, v141
	v_add_f32_e32 v110, v125, v135
	v_add_f32_e32 v62, v72, v62
	v_lshlrev_b32_e32 v38, 16, v56
	v_and_b32_e32 v39, 0xffff0000, v56
	v_lshlrev_b32_e32 v46, 16, v57
	v_and_b32_e32 v47, 0xffff0000, v57
	v_lshlrev_b32_e32 v54, 16, v58
	v_and_b32_e32 v55, 0xffff0000, v58
	v_pk_add_f32 v[28:29], v[28:29], v[38:39]
	v_lshlrev_b32_e32 v56, 16, v59
	v_and_b32_e32 v57, 0xffff0000, v59
	v_pk_add_f32 v[30:31], v[30:31], v[46:47]
	v_pk_add_f32 v[46:47], v[24:25], v[54:55]
	v_mul_f32_e32 v54, v29, v29
	v_pk_add_f32 v[38:39], v[26:27], v[56:57]
	v_cvt_pk_bf16_f32 v24, v28, v29
	v_cvt_pk_bf16_f32 v25, v30, v31
	v_cvt_pk_bf16_f32 v26, v46, v47
	v_fmac_f32_e32 v54, v28, v28
	v_cvt_pk_bf16_f32 v27, v38, v39
	global_store_dwordx4 v[60:61], v[24:27], off
	v_fmac_f32_e32 v54, v30, v30
	v_lshlrev_b32_e32 v28, 16, v52
	v_lshlrev_b32_e32 v24, 16, v50
	v_and_b32_e32 v25, 0xffff0000, v50
	v_lshlrev_b32_e32 v26, 16, v51
	v_and_b32_e32 v27, 0xffff0000, v51
	v_and_b32_e32 v29, 0xffff0000, v52
	v_fmac_f32_e32 v54, v31, v31
	v_lshlrev_b32_e32 v30, 16, v53
	v_and_b32_e32 v31, 0xffff0000, v53
	v_pk_add_f32 v[22:23], v[22:23], v[26:27]
	v_pk_add_f32 v[20:21], v[20:21], v[24:25]
	v_pk_add_f32 v[26:27], v[12:13], v[28:29]
	v_cvt_pk_bf16_f32 v12, v20, v21
	v_pk_add_f32 v[24:25], v[14:15], v[30:31]
	v_cvt_pk_bf16_f32 v13, v22, v23
	v_cvt_pk_bf16_f32 v14, v26, v27
	v_fmac_f32_e32 v54, v46, v46
	v_cvt_pk_bf16_f32 v15, v24, v25
	global_store_dwordx4 v[48:49], v[12:15], off offset:256
	v_fmac_f32_e32 v54, v47, v47
	v_fmac_f32_e32 v54, v38, v38
	v_mul_f32_e32 v12, v21, v21
	v_fmac_f32_e32 v12, v20, v20
	v_fmac_f32_e32 v12, v22, v22
	v_fmac_f32_e32 v12, v23, v23
	v_fmac_f32_e32 v12, v26, v26
	v_fmac_f32_e32 v12, v27, v27
	v_fmac_f32_e32 v12, v24, v24
	v_fmac_f32_e32 v54, v39, v39
	v_fmac_f32_e32 v12, v25, v25
	v_add_f32_e32 v24, v54, v12
	s_waitcnt vmcnt(14)
	s_nop 1
	v_mov_b32_e32 v40, v238
	v_mov_b32_e32 v41, v239
	v_mov_b32_e32 v42, v240
	v_mov_b32_e32 v43, v241
	v_mov_b32_e32 v32, v242
	v_mov_b32_e32 v33, v243
	v_mov_b32_e32 v34, v244
	v_mov_b32_e32 v35, v245
	v_lshlrev_b32_e32 v12, 16, v40
	v_and_b32_e32 v13, 0xffff0000, v40
	v_pk_add_f32 v[12:13], v[16:17], v[12:13]
	v_lshlrev_b32_e32 v14, 16, v41
	v_and_b32_e32 v15, 0xffff0000, v41
	v_lshlrev_b32_e32 v20, 16, v42
	v_and_b32_e32 v21, 0xffff0000, v42
	v_mul_f32_e32 v25, v13, v13
	v_lshlrev_b32_e32 v22, 16, v43
	v_and_b32_e32 v23, 0xffff0000, v43
	v_pk_add_f32 v[14:15], v[18:19], v[14:15]
	v_pk_add_f32 v[18:19], v[8:9], v[20:21]
	v_cvt_pk_bf16_f32 v8, v12, v13
	v_cvt_pk_bf16_f32 v9, v14, v15
	v_fmac_f32_e32 v25, v12, v12
	v_pk_add_f32 v[16:17], v[10:11], v[22:23]
	v_cvt_pk_bf16_f32 v10, v18, v19
	v_fmac_f32_e32 v25, v14, v14
	v_cvt_pk_bf16_f32 v11, v16, v17
	global_store_dwordx4 v[44:45], v[8:11], off
	v_fmac_f32_e32 v25, v15, v15
	v_lshlrev_b32_e32 v12, 16, v34
	v_lshlrev_b32_e32 v8, 16, v32
	v_and_b32_e32 v9, 0xffff0000, v32
	v_and_b32_e32 v13, 0xffff0000, v34
	v_pk_add_f32 v[4:5], v[4:5], v[8:9]
	v_fmac_f32_e32 v25, v18, v18
	v_lshlrev_b32_e32 v10, 16, v33
	v_and_b32_e32 v11, 0xffff0000, v33
	v_pk_add_f32 v[22:23], v[0:1], v[12:13]
	v_mul_f32_e32 v0, v5, v5
	v_fmac_f32_e32 v25, v19, v19
	v_pk_add_f32 v[18:19], v[6:7], v[10:11]
	v_fmac_f32_e32 v0, v4, v4
	v_fmac_f32_e32 v0, v18, v18
	v_fmac_f32_e32 v0, v19, v19
	v_lshlrev_b32_e32 v14, 16, v35
	v_and_b32_e32 v15, 0xffff0000, v35
	v_fmac_f32_e32 v0, v22, v22
	v_pk_add_f32 v[20:21], v[2:3], v[14:15]
	v_fmac_f32_e32 v0, v23, v23
	v_fmac_f32_e32 v25, v16, v16
	v_fmac_f32_e32 v0, v20, v20
	v_fmac_f32_e32 v25, v17, v17
	v_fmac_f32_e32 v0, v21, v21
	v_add_f32_e32 v14, v25, v0
	v_cvt_pk_bf16_f32 v16, v4, v5
	ds_bpermute_b32 v1, v171, v110
	ds_bpermute_b32 v2, v171, v102
	ds_bpermute_b32 v4, v171, v86
	ds_bpermute_b32 v6, v171, v68
	ds_bpermute_b32 v8, v171, v69
	ds_bpermute_b32 v10, v171, v62
	ds_bpermute_b32 v12, v171, v24
	ds_bpermute_b32 v15, v171, v14
	s_waitcnt lgkmcnt(0)
	v_add_f32_e32 v0, v110, v1
	v_add_f32_e32 v2, v102, v2
	v_add_f32_e32 v4, v86, v4
	v_add_f32_e32 v6, v68, v6
	v_add_f32_e32 v8, v69, v8
	v_add_f32_e32 v10, v62, v10
	v_add_f32_e32 v12, v24, v12
	v_add_f32_e32 v14, v14, v15
	ds_bpermute_b32 v1, v172, v0
	ds_bpermute_b32 v3, v172, v2
	ds_bpermute_b32 v5, v172, v4
	ds_bpermute_b32 v7, v172, v6
	ds_bpermute_b32 v9, v172, v8
	ds_bpermute_b32 v11, v172, v10
	ds_bpermute_b32 v13, v172, v12
	ds_bpermute_b32 v15, v172, v14
	v_cvt_pk_bf16_f32 v17, v18, v19
	v_cvt_pk_bf16_f32 v18, v22, v23
	v_cvt_pk_bf16_f32 v19, v20, v21
	global_store_dwordx4 v[36:37], v[16:19], off offset:256
	s_and_saveexec_b64 s[40:41], s[4:5]
	s_cbranch_execz .LBB0_892
	s_waitcnt lgkmcnt(6)
	v_add_f32_e32 v2, v2, v3
	v_add_f32_e32 v0, v0, v1
	v_add_u32_e32 v1, s69, v173
	s_waitcnt lgkmcnt(2)
	v_add_f32_e32 v10, v10, v11
	v_add_f32_e32 v8, v8, v9
	v_add_f32_e32 v6, v6, v7
	v_add_f32_e32 v4, v4, v5
	ds_write2st64_b32 v1, v0, v2 offset1:1
	ds_write2st64_b32 v1, v4, v6 offset0:2 offset1:3
	v_add_u32_e32 v0, s69, v177
	s_waitcnt lgkmcnt(2)
	v_add_f32_e32 v14, v14, v15
	v_add_f32_e32 v12, v12, v13
	ds_write2st64_b32 v0, v8, v10 offset1:1
	ds_write2st64_b32 v0, v12, v14 offset0:2 offset1:3

.LBB0_955:
	s_add_u32 s42, s40, 0xfff00080
	s_addc_u32 s43, s41, -1
	s_add_i32 s83, 0, 0x10000
	v_add_u32_e32 v140, s83, v179
	ds_read_b128 v[128:131], v140
	ds_read_b128 v[132:135], v140 offset:1024
	ds_read_b128 v[136:139], v140 offset:2048
	ds_read_b128 v[140:143], v140 offset:3072
	s_cmp_eq_u32 s82, 60
	s_cselect_b32 s45, s37, s43
	s_cselect_b32 s44, s36, s42
	s_cselect_b32 s43, s39, s81
	s_cselect_b32 s42, s38, s80
	v_lshl_add_u64 v[212:213], s[40:41], 0, v[160:161]
	s_add_i32 m0, s69, 0xc000
	ds_read_b128 v[144:147], v191
	ds_read_b128 v[164:167], v191 offset:1024
	ds_read_b128 v[168:171], v191 offset:2048
	ds_read_b128 v[172:175], v191 offset:3072
	ds_read_b128 v[192:195], v191 offset:4096
	ds_read_b128 v[200:203], v191 offset:5120
	ds_read_b128 v[204:207], v191 offset:6144
	ds_read_b128 v[208:211], v191 offset:7168
	global_load_lds_dwordx4 v[212:213], off
	v_lshl_add_u64 v[212:213], s[40:41], 0, v[162:163]
	s_add_i32 m0, s69, 0xe000
	s_nop 0
	global_load_lds_dwordx4 v[212:213], off
	s_waitcnt lgkmcnt(8)
	s_barrier
	s_waitcnt lgkmcnt(0)
	s_setprio 1
	s_waitcnt lgkmcnt(0)
	v_mfma_f32_16x16x32_bf16 v[124:127], v[128:131], v[144:147], v[124:127]
	v_mfma_f32_16x16x32_bf16 v[120:123], v[136:139], v[144:147], v[120:123]
	v_mfma_f32_16x16x32_bf16 v[116:119], v[128:131], v[168:171], v[116:119]
	v_mfma_f32_16x16x32_bf16 v[108:111], v[136:139], v[168:171], v[108:111]
	v_mfma_f32_16x16x32_bf16 v[92:95], v[128:131], v[192:195], v[92:95]
	v_mfma_f32_16x16x32_bf16 v[88:91], v[136:139], v[192:195], v[88:91]
	v_mfma_f32_16x16x32_bf16 v[76:79], v[128:131], v[204:207], v[76:79]
	v_mfma_f32_16x16x32_bf16 v[72:75], v[136:139], v[204:207], v[72:75]
	v_mfma_f32_16x16x32_bf16 v[124:127], v[132:135], v[164:167], v[124:127]
	v_mfma_f32_16x16x32_bf16 v[120:123], v[140:143], v[164:167], v[120:123]
	v_mfma_f32_16x16x32_bf16 v[116:119], v[132:135], v[172:175], v[116:119]
	v_mfma_f32_16x16x32_bf16 v[108:111], v[140:143], v[172:175], v[108:111]
	v_mfma_f32_16x16x32_bf16 v[92:95], v[132:135], v[200:203], v[92:95]
	v_mfma_f32_16x16x32_bf16 v[88:91], v[140:143], v[200:203], v[88:91]
	v_mfma_f32_16x16x32_bf16 v[76:79], v[132:135], v[208:211], v[76:79]
	v_mfma_f32_16x16x32_bf16 v[72:75], v[140:143], v[208:211], v[72:75]
	s_setprio 0
	s_barrier
	s_add_i32 s86, 0, 0x14000
	s_add_i32 s83, s83, s68
	v_add_u32_e32 v199, s86, v179
	v_lshl_add_u64 v[228:229], s[42:43], 0, v[158:159]
	s_mov_b32 m0, s83
	ds_read_b128 v[212:215], v199
	ds_read_b128 v[216:219], v199 offset:1024
	ds_read_b128 v[220:223], v199 offset:2048
	ds_read_b128 v[224:227], v199 offset:3072
	global_load_lds_dwordx4 v[228:229], off
	v_lshl_add_u64 v[230:231], s[42:43], 0, v[154:155]
	s_add_i32 m0, s83, 0x2000
	s_nop 0
	global_load_lds_dwordx4 v[230:231], off
	s_barrier
	s_waitcnt lgkmcnt(0)
	s_setprio 1
	s_waitcnt lgkmcnt(0)
	v_mfma_f32_16x16x32_bf16 v[112:115], v[212:215], v[144:147], v[112:115]
	v_mfma_f32_16x16x32_bf16 v[104:107], v[220:223], v[144:147], v[104:107]
	v_mfma_f32_16x16x32_bf16 v[100:103], v[212:215], v[168:171], v[100:103]
	v_mfma_f32_16x16x32_bf16 v[96:99], v[220:223], v[168:171], v[96:99]
	v_mfma_f32_16x16x32_bf16 v[84:87], v[212:215], v[192:195], v[84:87]
	v_mfma_f32_16x16x32_bf16 v[80:83], v[220:223], v[192:195], v[80:83]
	v_mfma_f32_16x16x32_bf16 v[68:71], v[212:215], v[204:207], v[68:71]
	v_mfma_f32_16x16x32_bf16 v[64:67], v[220:223], v[204:207], v[64:67]
	v_mfma_f32_16x16x32_bf16 v[112:115], v[216:219], v[164:167], v[112:115]
	v_mfma_f32_16x16x32_bf16 v[104:107], v[224:227], v[164:167], v[104:107]
	v_mfma_f32_16x16x32_bf16 v[100:103], v[216:219], v[172:175], v[100:103]
	v_mfma_f32_16x16x32_bf16 v[96:99], v[224:227], v[172:175], v[96:99]
	v_mfma_f32_16x16x32_bf16 v[84:87], v[216:219], v[200:203], v[84:87]
	v_mfma_f32_16x16x32_bf16 v[80:83], v[224:227], v[200:203], v[80:83]
	v_mfma_f32_16x16x32_bf16 v[68:71], v[216:219], v[208:211], v[68:71]
	v_mfma_f32_16x16x32_bf16 v[64:67], v[224:227], v[208:211], v[64:67]
	s_setprio 0
	s_mov_b32 m0, s69
	v_lshl_add_u64 v[232:233], s[44:45], 0, v[148:149]
	s_barrier
	ds_read_b128 v[144:147], v191 offset:16384
	ds_read_b128 v[164:167], v191 offset:17408
	ds_read_b128 v[168:171], v191 offset:18432
	ds_read_b128 v[172:175], v191 offset:19456
	ds_read_b128 v[192:195], v191 offset:20480
	ds_read_b128 v[200:203], v191 offset:21504
	ds_read_b128 v[204:207], v191 offset:22528
	ds_read_b128 v[208:211], v191 offset:23552
	global_load_lds_dwordx4 v[232:233], off
	v_lshl_add_u64 v[234:235], s[44:45], 0, v[156:157]
	s_mov_b32 m0, s70
	s_nop 0
	global_load_lds_dwordx4 v[234:235], off
	s_barrier
	s_waitcnt lgkmcnt(0)
	s_setprio 1
	s_waitcnt lgkmcnt(0)
	v_mfma_f32_16x16x32_bf16 v[60:63], v[128:131], v[144:147], v[60:63]
	v_mfma_f32_16x16x32_bf16 v[56:59], v[136:139], v[144:147], v[56:59]
	v_mfma_f32_16x16x32_bf16 v[44:47], v[128:131], v[168:171], v[44:47]
	v_mfma_f32_16x16x32_bf16 v[40:43], v[136:139], v[168:171], v[40:43]
	v_mfma_f32_16x16x32_bf16 v[28:31], v[128:131], v[192:195], v[28:31]
	v_mfma_f32_16x16x32_bf16 v[24:27], v[136:139], v[192:195], v[24:27]
	v_mfma_f32_16x16x32_bf16 v[16:19], v[128:131], v[204:207], v[16:19]
	v_mfma_f32_16x16x32_bf16 v[8:11], v[136:139], v[204:207], v[8:11]
	v_mfma_f32_16x16x32_bf16 v[60:63], v[132:135], v[164:167], v[60:63]
	v_mfma_f32_16x16x32_bf16 v[56:59], v[140:143], v[164:167], v[56:59]
	v_mfma_f32_16x16x32_bf16 v[44:47], v[132:135], v[172:175], v[44:47]
	v_mfma_f32_16x16x32_bf16 v[40:43], v[140:143], v[172:175], v[40:43]
	v_mfma_f32_16x16x32_bf16 v[28:31], v[132:135], v[200:203], v[28:31]
	v_mfma_f32_16x16x32_bf16 v[24:27], v[140:143], v[200:203], v[24:27]
	v_mfma_f32_16x16x32_bf16 v[16:19], v[132:135], v[208:211], v[16:19]
	v_mfma_f32_16x16x32_bf16 v[8:11], v[140:143], v[208:211], v[8:11]
	s_setprio 0
	s_barrier
	s_add_u32 s84, s42, 0x100000
	s_addc_u32 s85, s43, 0
	s_add_i32 s83, s86, s68
	v_lshl_add_u64 v[128:129], s[84:85], 0, v[158:159]
	s_mov_b32 m0, s83
	s_nop 0
	global_load_lds_dwordx4 v[128:129], off
	v_lshl_add_u64 v[128:129], s[84:85], 0, v[154:155]
	s_add_i32 m0, s83, 0x2000
	s_nop 0
	global_load_lds_dwordx4 v[128:129], off
	s_waitcnt vmcnt(6)
	s_barrier
	s_setprio 1
	v_mfma_f32_16x16x32_bf16 v[52:55], v[212:215], v[144:147], v[52:55]
	v_mfma_f32_16x16x32_bf16 v[48:51], v[220:223], v[144:147], v[48:51]
	v_mfma_f32_16x16x32_bf16 v[36:39], v[212:215], v[168:171], v[36:39]
	v_mfma_f32_16x16x32_bf16 v[32:35], v[220:223], v[168:171], v[32:35]
	v_mfma_f32_16x16x32_bf16 v[20:23], v[212:215], v[192:195], v[20:23]
	v_mfma_f32_16x16x32_bf16 v[12:15], v[220:223], v[192:195], v[12:15]
	v_mfma_f32_16x16x32_bf16 v[4:7], v[212:215], v[204:207], v[4:7]
	v_mfma_f32_16x16x32_bf16 v[0:3], v[220:223], v[204:207], v[0:3]
	v_mfma_f32_16x16x32_bf16 v[52:55], v[216:219], v[164:167], v[52:55]
	v_mfma_f32_16x16x32_bf16 v[48:51], v[224:227], v[164:167], v[48:51]
	v_mfma_f32_16x16x32_bf16 v[36:39], v[216:219], v[172:175], v[36:39]
	v_mfma_f32_16x16x32_bf16 v[32:35], v[224:227], v[172:175], v[32:35]
	v_mfma_f32_16x16x32_bf16 v[20:23], v[216:219], v[200:203], v[20:23]
	v_mfma_f32_16x16x32_bf16 v[12:15], v[224:227], v[200:203], v[12:15]
	v_mfma_f32_16x16x32_bf16 v[4:7], v[216:219], v[208:211], v[4:7]
	v_mfma_f32_16x16x32_bf16 v[0:3], v[224:227], v[208:211], v[0:3]
	s_setprio 0
	s_add_i32 s83, 0, 0x18000
	v_add_u32_e32 v140, s83, v179
	s_barrier
	ds_read_b128 v[128:131], v140
	ds_read_b128 v[132:135], v140 offset:1024
	ds_read_b128 v[136:139], v140 offset:2048
	ds_read_b128 v[140:143], v140 offset:3072
	s_add_u32 s44, s44, 0x100000
	s_addc_u32 s45, s45, 0
	s_mov_b32 m0, s71
	v_lshl_add_u64 v[212:213], s[44:45], 0, v[148:149]
	ds_read_b128 v[144:147], v191 offset:32768
	ds_read_b128 v[164:167], v191 offset:33792
	ds_read_b128 v[168:171], v191 offset:34816
	ds_read_b128 v[172:175], v191 offset:35840
	ds_read_b128 v[192:195], v191 offset:36864
	ds_read_b128 v[200:203], v191 offset:37888
	ds_read_b128 v[204:207], v191 offset:38912
	ds_read_b128 v[208:211], v191 offset:39936
	global_load_lds_dwordx4 v[212:213], off
	v_lshl_add_u64 v[212:213], s[44:45], 0, v[156:157]
	s_mov_b32 m0, s72
	s_nop 0
	global_load_lds_dwordx4 v[212:213], off
	s_waitcnt lgkmcnt(8)
	s_barrier
	s_waitcnt lgkmcnt(0)
	s_setprio 1
	s_waitcnt lgkmcnt(0)
	v_mfma_f32_16x16x32_bf16 v[124:127], v[128:131], v[144:147], v[124:127]
	v_mfma_f32_16x16x32_bf16 v[120:123], v[136:139], v[144:147], v[120:123]
	v_mfma_f32_16x16x32_bf16 v[116:119], v[128:131], v[168:171], v[116:119]
	v_mfma_f32_16x16x32_bf16 v[108:111], v[136:139], v[168:171], v[108:111]
	v_mfma_f32_16x16x32_bf16 v[92:95], v[128:131], v[192:195], v[92:95]
	v_mfma_f32_16x16x32_bf16 v[88:91], v[136:139], v[192:195], v[88:91]
	v_mfma_f32_16x16x32_bf16 v[76:79], v[128:131], v[204:207], v[76:79]
	v_mfma_f32_16x16x32_bf16 v[72:75], v[136:139], v[204:207], v[72:75]
	v_mfma_f32_16x16x32_bf16 v[124:127], v[132:135], v[164:167], v[124:127]
	v_mfma_f32_16x16x32_bf16 v[120:123], v[140:143], v[164:167], v[120:123]
	v_mfma_f32_16x16x32_bf16 v[116:119], v[132:135], v[172:175], v[116:119]
	v_mfma_f32_16x16x32_bf16 v[108:111], v[140:143], v[172:175], v[108:111]
	v_mfma_f32_16x16x32_bf16 v[92:95], v[132:135], v[200:203], v[92:95]
	v_mfma_f32_16x16x32_bf16 v[88:91], v[140:143], v[200:203], v[88:91]
	v_mfma_f32_16x16x32_bf16 v[76:79], v[132:135], v[208:211], v[76:79]
	v_mfma_f32_16x16x32_bf16 v[72:75], v[140:143], v[208:211], v[72:75]
	s_setprio 0
	s_barrier
	s_add_i32 s44, 0, 0x1c000
	s_add_i32 s45, s83, s68
	v_add_u32_e32 v199, s44, v179
	v_lshl_add_u64 v[228:229], v[228:229], 0, s[26:27]
	s_mov_b32 m0, s45
	ds_read_b128 v[212:215], v199
	ds_read_b128 v[216:219], v199 offset:1024
	ds_read_b128 v[220:223], v199 offset:2048
	ds_read_b128 v[224:227], v199 offset:3072
	global_load_lds_dwordx4 v[228:229], off
	v_lshl_add_u64 v[228:229], v[230:231], 0, s[26:27]
	s_add_i32 m0, s45, 0x2000
	s_nop 0
	global_load_lds_dwordx4 v[228:229], off
	s_barrier
	s_waitcnt lgkmcnt(0)
	s_setprio 1
	s_waitcnt lgkmcnt(0)
	v_mfma_f32_16x16x32_bf16 v[112:115], v[212:215], v[144:147], v[112:115]
	v_mfma_f32_16x16x32_bf16 v[104:107], v[220:223], v[144:147], v[104:107]
	v_mfma_f32_16x16x32_bf16 v[100:103], v[212:215], v[168:171], v[100:103]
	v_mfma_f32_16x16x32_bf16 v[96:99], v[220:223], v[168:171], v[96:99]
	v_mfma_f32_16x16x32_bf16 v[84:87], v[212:215], v[192:195], v[84:87]
	v_mfma_f32_16x16x32_bf16 v[80:83], v[220:223], v[192:195], v[80:83]
	v_mfma_f32_16x16x32_bf16 v[68:71], v[212:215], v[204:207], v[68:71]
	v_mfma_f32_16x16x32_bf16 v[64:67], v[220:223], v[204:207], v[64:67]
	v_mfma_f32_16x16x32_bf16 v[112:115], v[216:219], v[164:167], v[112:115]
	v_mfma_f32_16x16x32_bf16 v[104:107], v[224:227], v[164:167], v[104:107]
	v_mfma_f32_16x16x32_bf16 v[100:103], v[216:219], v[172:175], v[100:103]
	v_mfma_f32_16x16x32_bf16 v[96:99], v[224:227], v[172:175], v[96:99]
	v_mfma_f32_16x16x32_bf16 v[84:87], v[216:219], v[200:203], v[84:87]
	v_mfma_f32_16x16x32_bf16 v[80:83], v[224:227], v[200:203], v[80:83]
	v_mfma_f32_16x16x32_bf16 v[68:71], v[216:219], v[208:211], v[68:71]
	v_mfma_f32_16x16x32_bf16 v[64:67], v[224:227], v[208:211], v[64:67]
	s_setprio 0
	s_mov_b32 m0, s73
	v_lshl_add_u64 v[228:229], v[232:233], 0, s[26:27]
	s_barrier
	ds_read_b128 v[144:147], v191 offset:49152
	ds_read_b128 v[164:167], v191 offset:50176
	ds_read_b128 v[168:171], v191 offset:51200
	ds_read_b128 v[172:175], v191 offset:52224
	ds_read_b128 v[192:195], v191 offset:53248
	ds_read_b128 v[200:203], v191 offset:54272
	ds_read_b128 v[204:207], v191 offset:55296
	ds_read_b128 v[208:211], v191 offset:56320
	global_load_lds_dwordx4 v[228:229], off
	v_lshl_add_u64 v[228:229], v[234:235], 0, s[26:27]
	s_mov_b32 m0, s74
	s_nop 0
	global_load_lds_dwordx4 v[228:229], off
	s_barrier
	s_waitcnt lgkmcnt(0)
	s_setprio 1
	s_waitcnt lgkmcnt(0)
	v_mfma_f32_16x16x32_bf16 v[60:63], v[128:131], v[144:147], v[60:63]
	v_mfma_f32_16x16x32_bf16 v[56:59], v[136:139], v[144:147], v[56:59]
	v_mfma_f32_16x16x32_bf16 v[44:47], v[128:131], v[168:171], v[44:47]
	v_mfma_f32_16x16x32_bf16 v[40:43], v[136:139], v[168:171], v[40:43]
	v_mfma_f32_16x16x32_bf16 v[28:31], v[128:131], v[192:195], v[28:31]
	v_mfma_f32_16x16x32_bf16 v[24:27], v[136:139], v[192:195], v[24:27]
	v_mfma_f32_16x16x32_bf16 v[16:19], v[128:131], v[204:207], v[16:19]
	v_mfma_f32_16x16x32_bf16 v[8:11], v[136:139], v[204:207], v[8:11]
	v_mfma_f32_16x16x32_bf16 v[60:63], v[132:135], v[164:167], v[60:63]
	v_mfma_f32_16x16x32_bf16 v[56:59], v[140:143], v[164:167], v[56:59]
	v_mfma_f32_16x16x32_bf16 v[44:47], v[132:135], v[172:175], v[44:47]
	v_mfma_f32_16x16x32_bf16 v[40:43], v[140:143], v[172:175], v[40:43]
	v_mfma_f32_16x16x32_bf16 v[28:31], v[132:135], v[200:203], v[28:31]
	v_mfma_f32_16x16x32_bf16 v[24:27], v[140:143], v[200:203], v[24:27]
	v_mfma_f32_16x16x32_bf16 v[16:19], v[132:135], v[208:211], v[16:19]
	v_mfma_f32_16x16x32_bf16 v[8:11], v[140:143], v[208:211], v[8:11]
	s_setprio 0
	s_barrier
	s_add_u32 s42, s42, 0x100080
	s_addc_u32 s43, s43, 0
	s_add_i32 s44, s44, s68
	v_lshl_add_u64 v[128:129], s[42:43], 0, v[158:159]
	s_mov_b32 m0, s44
	s_nop 0
	global_load_lds_dwordx4 v[128:129], off
	v_lshl_add_u64 v[128:129], s[42:43], 0, v[154:155]
	s_add_i32 m0, s44, 0x2000
	s_nop 0
	global_load_lds_dwordx4 v[128:129], off
	s_waitcnt vmcnt(6)
	s_barrier
	s_setprio 1
	v_mfma_f32_16x16x32_bf16 v[52:55], v[212:215], v[144:147], v[52:55]
	v_mfma_f32_16x16x32_bf16 v[48:51], v[220:223], v[144:147], v[48:51]
	v_mfma_f32_16x16x32_bf16 v[36:39], v[212:215], v[168:171], v[36:39]
	v_mfma_f32_16x16x32_bf16 v[32:35], v[220:223], v[168:171], v[32:35]
	v_mfma_f32_16x16x32_bf16 v[20:23], v[212:215], v[192:195], v[20:23]
	v_mfma_f32_16x16x32_bf16 v[12:15], v[220:223], v[192:195], v[12:15]
	v_mfma_f32_16x16x32_bf16 v[4:7], v[212:215], v[204:207], v[4:7]
	v_mfma_f32_16x16x32_bf16 v[0:3], v[220:223], v[204:207], v[0:3]
	v_mfma_f32_16x16x32_bf16 v[52:55], v[216:219], v[164:167], v[52:55]
	v_mfma_f32_16x16x32_bf16 v[48:51], v[224:227], v[164:167], v[48:51]
	v_mfma_f32_16x16x32_bf16 v[36:39], v[216:219], v[172:175], v[36:39]
	v_mfma_f32_16x16x32_bf16 v[32:35], v[224:227], v[172:175], v[32:35]
	v_mfma_f32_16x16x32_bf16 v[20:23], v[216:219], v[200:203], v[20:23]
	v_mfma_f32_16x16x32_bf16 v[12:15], v[224:227], v[200:203], v[12:15]
	v_mfma_f32_16x16x32_bf16 v[4:7], v[216:219], v[208:211], v[4:7]
	v_mfma_f32_16x16x32_bf16 v[0:3], v[224:227], v[208:211], v[0:3]
	s_setprio 0
	s_add_i32 s82, s82, 2
	s_add_u32 s40, s40, 0x100
	s_addc_u32 s41, s41, 0
	s_add_u32 s80, s80, 0x100
	s_addc_u32 s81, s81, 0
	s_cmp_gt_u32 s82, 61
	s_barrier
	s_cbranch_scc0 .LBB0_955
	v_add_u32_e32 v164, s33, v178
	v_ashrrev_i32_e32 v165, 31, v164
	v_readlane_b32 s40, v254, 56
	v_add_u32_e32 v128, s77, v180
	v_lshlrev_b64 v[130:131], 11, v[164:165]
	v_readlane_b32 s41, v254, 57
	v_ashrrev_i32_e32 v129, 31, v128
	s_mov_b32 s33, 0x8000
	v_lshl_add_u64 v[130:131], s[40:41], 0, v[130:131]
	v_lshl_add_u64 v[166:167], v[128:129], 1, v[130:131]
	v_add_co_u32_e32 v174, vcc, s33, v166
	global_load_dwordx4 v[136:139], v[166:167], off
	global_load_dwordx4 v[140:143], v[166:167], off offset:256
	v_addc_co_u32_e32 v175, vcc, 0, v167, vcc
	global_load_dwordx4 v[144:147], v[174:175], off
	s_mov_b64 s[40:41], 0x8000
	v_lshl_add_u64 v[172:173], v[166:167], 0, s[40:41]
	global_load_dwordx4 v[192:195], v[172:173], off offset:256
	s_mov_b32 s33, 0x10000
	v_add_co_u32_e32 v170, vcc, s33, v166
	s_mov_b64 s[42:43], 0x10000
	s_nop 0
	v_addc_co_u32_e32 v171, vcc, 0, v167, vcc
	v_lshl_add_u64 v[168:169], v[166:167], 0, s[42:43]
	global_load_dwordx4 v[128:131], v[170:171], off
	global_load_dwordx4 v[132:135], v[168:169], off offset:256
	s_mov_b32 s98, 0x18000
	s_mov_b32 s99, 0
	v_lshl_add_u64 v[248:249], v[166:167], 0, s[98:99]
	global_load_dwordx4 v[208:211], v[248:249], off
	s_mov_b64 s[98:99], 0x18000
	v_lshl_add_u64 v[248:249], v[166:167], 0, s[98:99]
	global_load_dwordx4 v[212:215], v[248:249], off offset:256
	s_mov_b32 s98, 0x40000
	s_mov_b32 s99, 0
	v_lshl_add_u64 v[248:249], v[166:167], 0, s[98:99]
	global_load_dwordx4 v[216:219], v[248:249], off
	s_mov_b64 s[98:99], 0x40000
	v_lshl_add_u64 v[248:249], v[166:167], 0, s[98:99]
	global_load_dwordx4 v[220:223], v[248:249], off offset:256
	s_mov_b32 s98, 0x48000
	s_mov_b32 s99, 0
	v_lshl_add_u64 v[248:249], v[166:167], 0, s[98:99]
	global_load_dwordx4 v[224:227], v[248:249], off
	s_mov_b64 s[98:99], 0x48000
	v_lshl_add_u64 v[248:249], v[166:167], 0, s[98:99]
	global_load_dwordx4 v[228:231], v[248:249], off offset:256
	s_mov_b32 s98, s61
	s_mov_b32 s99, 0
	v_lshl_add_u64 v[248:249], v[166:167], 0, s[98:99]
	global_load_dwordx4 v[232:235], v[248:249], off
	v_lshl_add_u64 v[248:249], v[166:167], 0, s[28:29]
	global_load_dwordx4 v[236:239], v[248:249], off offset:256
	s_mov_b32 s98, s62
	s_mov_b32 s99, 0
	v_lshl_add_u64 v[248:249], v[166:167], 0, s[98:99]
	global_load_dwordx4 v[240:243], v[248:249], off
	v_lshl_add_u64 v[248:249], v[166:167], 0, s[30:31]
	global_load_dwordx4 v[244:247], v[248:249], off offset:256
	s_mov_b32 s33, 0x18000
	s_mov_b64 s[40:41], 0x18000
	s_waitcnt vmcnt(10)
	v_lshlrev_b32_e32 v200, 16, v136
	v_and_b32_e32 v201, 0xffff0000, v136
	v_pk_add_f32 v[124:125], v[124:125], v[200:201]
	v_lshlrev_b32_e32 v202, 16, v138
	v_lshlrev_b32_e32 v200, 16, v144
	v_and_b32_e32 v201, 0xffff0000, v144
	v_lshlrev_b32_e32 v144, 16, v145
	v_and_b32_e32 v145, 0xffff0000, v145
	v_pk_add_f32 v[116:117], v[116:117], v[200:201]
	v_pk_add_f32 v[144:145], v[118:119], v[144:145]
	v_mul_f32_e32 v119, v117, v117
	v_and_b32_e32 v203, 0xffff0000, v138
	v_fmac_f32_e32 v119, v116, v116
	v_pk_add_f32 v[120:121], v[120:121], v[202:203]
	v_lshlrev_b32_e32 v202, 16, v146
	v_and_b32_e32 v203, 0xffff0000, v146
	v_fmac_f32_e32 v119, v144, v144
	v_pk_add_f32 v[108:109], v[108:109], v[202:203]
	v_fmac_f32_e32 v119, v145, v145
	v_lshlrev_b32_e32 v136, 16, v137
	v_and_b32_e32 v137, 0xffff0000, v137
	v_lshlrev_b32_e32 v204, 16, v140
	v_and_b32_e32 v205, 0xffff0000, v140
	v_lshlrev_b32_e32 v140, 16, v141
	v_and_b32_e32 v141, 0xffff0000, v141
	v_lshlrev_b32_e32 v206, 16, v142
	v_and_b32_e32 v207, 0xffff0000, v142
	v_lshlrev_b32_e32 v142, 16, v143
	v_and_b32_e32 v143, 0xffff0000, v143
	v_lshlrev_b32_e32 v146, 16, v147
	v_and_b32_e32 v147, 0xffff0000, v147
	v_fmac_f32_e32 v119, v108, v108
	v_lshlrev_b32_e32 v138, 16, v139
	v_and_b32_e32 v139, 0xffff0000, v139
	v_pk_add_f32 v[126:127], v[126:127], v[136:137]
	v_pk_add_f32 v[136:137], v[114:115], v[140:141]
	v_pk_add_f32 v[140:141], v[106:107], v[142:143]
	v_cvt_pk_bf16_f32 v106, v120, v121
	v_pk_add_f32 v[110:111], v[110:111], v[146:147]
	v_fmac_f32_e32 v119, v109, v109
	v_pk_add_f32 v[122:123], v[122:123], v[138:139]
	v_pk_add_f32 v[138:139], v[112:113], v[204:205]
	v_pk_add_f32 v[142:143], v[104:105], v[206:207]
	v_cvt_pk_bf16_f32 v104, v124, v125
	v_cvt_pk_bf16_f32 v105, v126, v127
	v_cvt_pk_bf16_f32 v107, v122, v123
	v_cvt_pk_bf16_f32 v112, v138, v139
	v_cvt_pk_bf16_f32 v113, v136, v137
	global_store_dwordx4 v[166:167], v[104:107], off
	v_fmac_f32_e32 v119, v110, v110
	v_cvt_pk_bf16_f32 v114, v142, v143
	v_cvt_pk_bf16_f32 v115, v140, v141
	global_store_dwordx4 v[166:167], v[112:115], off offset:256
	v_cvt_pk_bf16_f32 v106, v108, v109
	v_add_co_u32_e32 v108, vcc, s33, v166
	v_cvt_pk_bf16_f32 v104, v116, v117
	v_cvt_pk_bf16_f32 v105, v144, v145
	v_cvt_pk_bf16_f32 v107, v110, v111
	v_fmac_f32_e32 v119, v111, v111
	v_lshlrev_b32_e32 v110, 16, v192
	v_and_b32_e32 v111, 0xffff0000, v192
	v_lshlrev_b32_e32 v112, 16, v194
	v_and_b32_e32 v113, 0xffff0000, v194
	v_addc_co_u32_e32 v109, vcc, 0, v167, vcc
	global_store_dwordx4 v[174:175], v[104:107], off
	v_lshlrev_b32_e32 v114, 16, v193
	v_and_b32_e32 v115, 0xffff0000, v193
	v_lshlrev_b32_e32 v116, 16, v195
	v_and_b32_e32 v117, 0xffff0000, v195
	v_pk_add_f32 v[100:101], v[100:101], v[110:111]
	v_pk_add_f32 v[112:113], v[96:97], v[112:113]
	v_cvt_pk_bf16_f32 v96, v100, v101
	v_pk_add_f32 v[102:103], v[102:103], v[114:115]
	v_pk_add_f32 v[110:111], v[98:99], v[116:117]
	v_cvt_pk_bf16_f32 v97, v102, v103
	v_cvt_pk_bf16_f32 v98, v112, v113
	v_lshlrev_b32_e32 v114, 16, v130
	v_cvt_pk_bf16_f32 v99, v110, v111
	global_store_dwordx4 v[172:173], v[96:99], off offset:256
	v_and_b32_e32 v115, 0xffff0000, v130
	s_mov_b32 s33, 0x40000
	v_mul_f32_e32 v96, v101, v101
	v_fmac_f32_e32 v96, v100, v100
	v_fmac_f32_e32 v96, v102, v102
	v_fmac_f32_e32 v96, v103, v103
	v_fmac_f32_e32 v96, v112, v112
	v_fmac_f32_e32 v96, v113, v113
	v_fmac_f32_e32 v96, v110, v110
	v_fmac_f32_e32 v96, v111, v111
	v_lshl_add_u64 v[100:101], v[166:167], 0, s[40:41]
	v_add_f32_e32 v102, v119, v96
	v_lshlrev_b32_e32 v110, 16, v128
	v_and_b32_e32 v111, 0xffff0000, v128
	v_pk_add_f32 v[92:93], v[92:93], v[110:111]
	v_lshlrev_b32_e32 v112, 16, v129
	v_and_b32_e32 v113, 0xffff0000, v129
	v_mul_f32_e32 v103, v93, v93
	v_lshlrev_b32_e32 v116, 16, v131
	v_and_b32_e32 v117, 0xffff0000, v131
	v_pk_add_f32 v[94:95], v[94:95], v[112:113]
	v_pk_add_f32 v[112:113], v[88:89], v[114:115]
	v_cvt_pk_bf16_f32 v88, v92, v93
	v_fmac_f32_e32 v103, v92, v92
	v_add_co_u32_e32 v92, vcc, s33, v166
	v_pk_add_f32 v[110:111], v[90:91], v[116:117]
	v_cvt_pk_bf16_f32 v89, v94, v95
	v_cvt_pk_bf16_f32 v90, v112, v113
	s_nop 0
	v_addc_co_u32_e32 v93, vcc, 0, v167, vcc
	v_cvt_pk_bf16_f32 v91, v110, v111
	global_store_dwordx4 v[170:171], v[88:91], off
	v_fmac_f32_e32 v103, v94, v94
	v_fmac_f32_e32 v103, v95, v95
	v_fmac_f32_e32 v103, v112, v112
	v_fmac_f32_e32 v103, v113, v113
	v_fmac_f32_e32 v103, v110, v110
	v_fmac_f32_e32 v103, v111, v111
	v_lshlrev_b32_e32 v94, 16, v132
	v_and_b32_e32 v95, 0xffff0000, v132
	v_lshlrev_b32_e32 v110, 16, v133
	v_and_b32_e32 v111, 0xffff0000, v133
	v_lshlrev_b32_e32 v112, 16, v134
	v_and_b32_e32 v113, 0xffff0000, v134
	v_lshlrev_b32_e32 v114, 16, v135
	v_and_b32_e32 v115, 0xffff0000, v135
	v_pk_add_f32 v[86:87], v[86:87], v[110:111]
	v_pk_add_f32 v[84:85], v[84:85], v[94:95]
	v_pk_add_f32 v[110:111], v[80:81], v[112:113]
	v_cvt_pk_bf16_f32 v80, v84, v85
	v_pk_add_f32 v[94:95], v[82:83], v[114:115]
	v_cvt_pk_bf16_f32 v81, v86, v87
	v_cvt_pk_bf16_f32 v82, v110, v111
	s_mov_b64 s[40:41], 0x40000
	v_cvt_pk_bf16_f32 v83, v94, v95
	global_store_dwordx4 v[168:169], v[80:83], off offset:256
	s_mov_b32 s33, 0x48000
	v_mul_f32_e32 v125, v125, v125
	v_mul_f32_e32 v80, v85, v85
	v_fmac_f32_e32 v80, v84, v84
	v_fmac_f32_e32 v80, v86, v86
	v_fmac_f32_e32 v80, v87, v87
	v_fmac_f32_e32 v80, v110, v110
	v_fmac_f32_e32 v80, v111, v111
	v_fmac_f32_e32 v80, v94, v94
	v_fmac_f32_e32 v80, v95, v95
	v_lshl_add_u64 v[84:85], v[166:167], 0, s[40:41]
	v_add_f32_e32 v86, v103, v80
	s_waitcnt vmcnt(13)
	s_nop 1
	v_mov_b32_e32 v104, v208
	v_mov_b32_e32 v105, v209
	v_mov_b32_e32 v106, v210
	v_mov_b32_e32 v107, v211
	v_mov_b32_e32 v96, v212
	v_mov_b32_e32 v97, v213
	v_mov_b32_e32 v98, v214
	v_mov_b32_e32 v99, v215
	v_mov_b32_e32 v88, v216
	v_mov_b32_e32 v89, v217
	v_mov_b32_e32 v90, v218
	v_mov_b32_e32 v91, v219
	v_lshlrev_b32_e32 v94, 16, v104
	v_and_b32_e32 v95, 0xffff0000, v104
	v_pk_add_f32 v[76:77], v[76:77], v[94:95]
	v_lshlrev_b32_e32 v104, 16, v105
	v_and_b32_e32 v105, 0xffff0000, v105
	v_mul_f32_e32 v87, v77, v77
	v_pk_add_f32 v[78:79], v[78:79], v[104:105]
	v_fmac_f32_e32 v87, v76, v76
	v_lshlrev_b32_e32 v110, 16, v106
	v_and_b32_e32 v111, 0xffff0000, v106
	v_fmac_f32_e32 v87, v78, v78
	v_pk_add_f32 v[104:105], v[72:73], v[110:111]
	v_fmac_f32_e32 v87, v79, v79
	v_lshlrev_b32_e32 v106, 16, v107
	v_and_b32_e32 v107, 0xffff0000, v107
	v_fmac_f32_e32 v87, v104, v104
	v_pk_add_f32 v[94:95], v[74:75], v[106:107]
	v_fmac_f32_e32 v87, v105, v105
	v_fmac_f32_e32 v87, v94, v94
	v_cvt_pk_bf16_f32 v73, v78, v79
	v_cvt_pk_bf16_f32 v75, v94, v95
	v_fmac_f32_e32 v87, v95, v95
	v_lshlrev_b32_e32 v78, 16, v96
	v_and_b32_e32 v79, 0xffff0000, v96
	v_lshlrev_b32_e32 v94, 16, v97
	v_and_b32_e32 v95, 0xffff0000, v97
	v_lshlrev_b32_e32 v96, 16, v98
	v_and_b32_e32 v97, 0xffff0000, v98
	v_cvt_pk_bf16_f32 v72, v76, v77
	v_lshlrev_b32_e32 v98, 16, v99
	v_add_co_u32_e32 v76, vcc, s33, v166
	v_and_b32_e32 v99, 0xffff0000, v99
	v_pk_add_f32 v[70:71], v[70:71], v[94:95]
	v_pk_add_f32 v[68:69], v[68:69], v[78:79]
	v_pk_add_f32 v[94:95], v[64:65], v[96:97]
	v_cvt_pk_bf16_f32 v64, v68, v69
	v_cvt_pk_bf16_f32 v74, v104, v105
	v_addc_co_u32_e32 v77, vcc, 0, v167, vcc
	v_pk_add_f32 v[78:79], v[66:67], v[98:99]
	v_cvt_pk_bf16_f32 v65, v70, v71
	v_cvt_pk_bf16_f32 v66, v94, v95
	global_store_dwordx4 v[108:109], v[72:75], off
	v_cvt_pk_bf16_f32 v67, v78, v79
	global_store_dwordx4 v[100:101], v[64:67], off offset:256
	s_mov_b64 s[40:41], 0x48000
	v_mul_f32_e32 v64, v69, v69
	v_fmac_f32_e32 v64, v68, v68
	v_fmac_f32_e32 v64, v70, v70
	v_fmac_f32_e32 v64, v71, v71
	v_fmac_f32_e32 v64, v94, v94
	v_fmac_f32_e32 v64, v95, v95
	v_fmac_f32_e32 v64, v78, v78
	v_fmac_f32_e32 v64, v79, v79
	v_add_f32_e32 v68, v87, v64
	v_lshlrev_b32_e32 v64, 16, v89
	v_and_b32_e32 v65, 0xffff0000, v89
	v_lshl_add_u64 v[66:67], v[166:167], 0, s[40:41]
	v_lshlrev_b32_e32 v70, 16, v88
	v_and_b32_e32 v71, 0xffff0000, v88
	v_lshlrev_b32_e32 v78, 16, v90
	v_and_b32_e32 v79, 0xffff0000, v90
	v_lshlrev_b32_e32 v88, 16, v91
	v_and_b32_e32 v89, 0xffff0000, v91
	v_pk_add_f32 v[90:91], v[62:63], v[64:65]
	v_pk_add_f32 v[60:61], v[60:61], v[70:71]
	v_pk_add_f32 v[78:79], v[56:57], v[78:79]
	v_mul_f32_e32 v69, v61, v61
	v_fmac_f32_e32 v69, v60, v60
	v_fmac_f32_e32 v69, v90, v90
	v_fmac_f32_e32 v69, v91, v91
	v_fmac_f32_e32 v69, v78, v78
	v_pk_add_f32 v[70:71], v[58:59], v[88:89]
	v_fmac_f32_e32 v69, v79, v79
	v_fmac_f32_e32 v69, v70, v70
	v_cvt_pk_bf16_f32 v58, v78, v79
	v_cvt_pk_bf16_f32 v59, v70, v71
	v_fmac_f32_e32 v69, v71, v71
	s_waitcnt vmcnt(12)
	s_nop 1
	v_mov_b32_e32 v80, v220
	v_mov_b32_e32 v81, v221
	v_mov_b32_e32 v82, v222
	v_mov_b32_e32 v83, v223
	v_mov_b32_e32 v72, v224
	v_mov_b32_e32 v73, v225
	v_mov_b32_e32 v74, v226
	v_mov_b32_e32 v75, v227
	v_mov_b32_e32 v62, v228
	v_mov_b32_e32 v63, v229
	v_mov_b32_e32 v64, v230
	v_mov_b32_e32 v65, v231
	v_lshlrev_b32_e32 v70, 16, v80
	v_and_b32_e32 v71, 0xffff0000, v80
	v_lshlrev_b32_e32 v78, 16, v81
	v_and_b32_e32 v79, 0xffff0000, v81
	v_lshlrev_b32_e32 v80, 16, v82
	v_and_b32_e32 v81, 0xffff0000, v82
	v_lshlrev_b32_e32 v82, 16, v83
	v_and_b32_e32 v83, 0xffff0000, v83
	v_pk_add_f32 v[54:55], v[54:55], v[78:79]
	v_pk_add_f32 v[52:53], v[52:53], v[70:71]
	v_pk_add_f32 v[78:79], v[48:49], v[80:81]
	v_cvt_pk_bf16_f32 v48, v52, v53
	v_pk_add_f32 v[70:71], v[50:51], v[82:83]
	v_cvt_pk_bf16_f32 v49, v54, v55
	v_cvt_pk_bf16_f32 v50, v78, v79
	v_cvt_pk_bf16_f32 v56, v60, v61
	v_add_co_u32_e32 v60, vcc, s61, v166
	v_cvt_pk_bf16_f32 v51, v70, v71
	global_store_dwordx4 v[84:85], v[48:51], off offset:256
	v_cvt_pk_bf16_f32 v57, v90, v91
	s_nop 0
	v_addc_co_u32_e32 v61, vcc, 0, v167, vcc
	v_mul_f32_e32 v48, v53, v53
	v_fmac_f32_e32 v48, v52, v52
	v_fmac_f32_e32 v48, v54, v54
	v_fmac_f32_e32 v48, v55, v55
	global_store_dwordx4 v[92:93], v[56:59], off
	v_fmac_f32_e32 v48, v78, v78
	v_fmac_f32_e32 v48, v79, v79
	v_fmac_f32_e32 v48, v70, v70
	v_fmac_f32_e32 v48, v71, v71
	v_lshl_add_u64 v[52:53], v[166:167], 0, s[28:29]
	v_add_f32_e32 v54, v69, v48
	v_mul_f32_e32 v139, v139, v139
	v_fmac_f32_e32 v125, v124, v124
	v_fmac_f32_e32 v139, v138, v138
	v_fmac_f32_e32 v125, v126, v126
	v_fmac_f32_e32 v139, v136, v136
	v_fmac_f32_e32 v125, v127, v127
	v_fmac_f32_e32 v139, v137, v137
	v_fmac_f32_e32 v125, v120, v120
	v_fmac_f32_e32 v139, v142, v142
	v_lshlrev_b32_e32 v70, 16, v72
	v_and_b32_e32 v71, 0xffff0000, v72
	v_pk_add_f32 v[44:45], v[44:45], v[70:71]
	v_lshlrev_b32_e32 v72, 16, v73
	v_and_b32_e32 v73, 0xffff0000, v73
	v_mul_f32_e32 v55, v45, v45
	v_pk_add_f32 v[46:47], v[46:47], v[72:73]
	v_fmac_f32_e32 v55, v44, v44
	v_lshlrev_b32_e32 v78, 16, v74
	v_and_b32_e32 v79, 0xffff0000, v74
	v_fmac_f32_e32 v55, v46, v46
	v_pk_add_f32 v[72:73], v[40:41], v[78:79]
	v_fmac_f32_e32 v55, v47, v47
	v_lshlrev_b32_e32 v74, 16, v75
	v_and_b32_e32 v75, 0xffff0000, v75
	v_cvt_pk_bf16_f32 v40, v44, v45
	v_fmac_f32_e32 v55, v72, v72
	v_add_co_u32_e32 v44, vcc, s62, v166
	v_pk_add_f32 v[70:71], v[42:43], v[74:75]
	v_cvt_pk_bf16_f32 v41, v46, v47
	v_cvt_pk_bf16_f32 v42, v72, v73
	v_fmac_f32_e32 v55, v73, v73
	v_cvt_pk_bf16_f32 v43, v70, v71
	v_addc_co_u32_e32 v45, vcc, 0, v167, vcc
	global_store_dwordx4 v[76:77], v[40:43], off
	v_fmac_f32_e32 v55, v70, v70
	v_lshlrev_b32_e32 v46, 16, v62
	v_and_b32_e32 v47, 0xffff0000, v62
	v_fmac_f32_e32 v55, v71, v71
	v_lshlrev_b32_e32 v70, 16, v64
	v_and_b32_e32 v71, 0xffff0000, v64
	v_lshlrev_b32_e32 v64, 16, v65
	v_and_b32_e32 v65, 0xffff0000, v65
	v_pk_add_f32 v[36:37], v[36:37], v[46:47]
	v_lshlrev_b32_e32 v62, 16, v63
	v_and_b32_e32 v63, 0xffff0000, v63
	v_pk_add_f32 v[46:47], v[34:35], v[64:65]
	v_mul_f32_e32 v64, v37, v37
	v_pk_add_f32 v[38:39], v[38:39], v[62:63]
	v_pk_add_f32 v[62:63], v[32:33], v[70:71]
	v_cvt_pk_bf16_f32 v32, v36, v37
	v_cvt_pk_bf16_f32 v33, v38, v39
	v_cvt_pk_bf16_f32 v35, v46, v47
	v_fmac_f32_e32 v64, v36, v36
	v_cvt_pk_bf16_f32 v34, v62, v63
	v_lshl_add_u64 v[36:37], v[166:167], 0, s[30:31]
	global_store_dwordx4 v[66:67], v[32:35], off offset:256
	v_fmac_f32_e32 v64, v38, v38
	v_fmac_f32_e32 v64, v39, v39
	v_fmac_f32_e32 v64, v62, v62
	v_fmac_f32_e32 v64, v63, v63
	v_fmac_f32_e32 v64, v46, v46
	v_fmac_f32_e32 v64, v47, v47
	v_fmac_f32_e32 v125, v121, v121
	v_fmac_f32_e32 v139, v143, v143
	v_fmac_f32_e32 v125, v122, v122
	v_fmac_f32_e32 v139, v140, v140
	v_fmac_f32_e32 v125, v123, v123
	v_fmac_f32_e32 v139, v141, v141
	s_waitcnt vmcnt(12)
	s_nop 1
	v_mov_b32_e32 v56, v232
	v_mov_b32_e32 v57, v233
	v_mov_b32_e32 v58, v234
	v_mov_b32_e32 v59, v235
	v_mov_b32_e32 v48, v236
	v_mov_b32_e32 v49, v237
	v_mov_b32_e32 v50, v238
	v_mov_b32_e32 v51, v239
	v_mov_b32_e32 v40, v240
	v_mov_b32_e32 v41, v241
	v_mov_b32_e32 v42, v242
	v_mov_b32_e32 v43, v243
	v_mov_b32_e32 v32, v244
	v_mov_b32_e32 v33, v245
	v_mov_b32_e32 v34, v246
	v_mov_b32_e32 v35, v247
	v_lshlrev_b32_e32 v38, 16, v56
	v_and_b32_e32 v39, 0xffff0000, v56
	v_lshlrev_b32_e32 v46, 16, v57
	v_and_b32_e32 v47, 0xffff0000, v57
	v_lshlrev_b32_e32 v56, 16, v58
	v_and_b32_e32 v57, 0xffff0000, v58
	v_pk_add_f32 v[28:29], v[28:29], v[38:39]
	v_lshlrev_b32_e32 v58, 16, v59
	v_and_b32_e32 v59, 0xffff0000, v59
	v_pk_add_f32 v[30:31], v[30:31], v[46:47]
	v_pk_add_f32 v[46:47], v[24:25], v[56:57]
	v_mul_f32_e32 v56, v29, v29
	v_pk_add_f32 v[38:39], v[26:27], v[58:59]
	v_cvt_pk_bf16_f32 v24, v28, v29
	v_cvt_pk_bf16_f32 v25, v30, v31
	v_cvt_pk_bf16_f32 v26, v46, v47
	v_fmac_f32_e32 v56, v28, v28
	v_cvt_pk_bf16_f32 v27, v38, v39
	global_store_dwordx4 v[60:61], v[24:27], off
	v_fmac_f32_e32 v56, v30, v30
	v_lshlrev_b32_e32 v28, 16, v50
	v_lshlrev_b32_e32 v24, 16, v48
	v_and_b32_e32 v25, 0xffff0000, v48
	v_lshlrev_b32_e32 v26, 16, v49
	v_and_b32_e32 v27, 0xffff0000, v49
	v_and_b32_e32 v29, 0xffff0000, v50
	v_fmac_f32_e32 v56, v31, v31
	v_lshlrev_b32_e32 v30, 16, v51
	v_and_b32_e32 v31, 0xffff0000, v51
	v_pk_add_f32 v[22:23], v[22:23], v[26:27]
	v_pk_add_f32 v[20:21], v[20:21], v[24:25]
	v_pk_add_f32 v[26:27], v[12:13], v[28:29]
	v_cvt_pk_bf16_f32 v12, v20, v21
	v_pk_add_f32 v[24:25], v[14:15], v[30:31]
	v_cvt_pk_bf16_f32 v13, v22, v23
	v_cvt_pk_bf16_f32 v14, v26, v27
	v_fmac_f32_e32 v56, v46, v46
	v_cvt_pk_bf16_f32 v15, v24, v25
	global_store_dwordx4 v[52:53], v[12:15], off offset:256
	v_fmac_f32_e32 v56, v47, v47
	v_fmac_f32_e32 v56, v38, v38
	v_mul_f32_e32 v12, v21, v21
	v_fmac_f32_e32 v12, v20, v20
	v_fmac_f32_e32 v12, v22, v22
	v_fmac_f32_e32 v12, v23, v23
	v_fmac_f32_e32 v12, v26, v26
	v_fmac_f32_e32 v12, v27, v27
	v_fmac_f32_e32 v12, v24, v24
	v_fmac_f32_e32 v56, v39, v39
	v_fmac_f32_e32 v12, v25, v25
	v_add_f32_e32 v24, v56, v12
	v_lshlrev_b32_e32 v12, 16, v40
	v_and_b32_e32 v13, 0xffff0000, v40
	v_pk_add_f32 v[12:13], v[16:17], v[12:13]
	v_lshlrev_b32_e32 v14, 16, v41
	v_and_b32_e32 v15, 0xffff0000, v41
	v_lshlrev_b32_e32 v20, 16, v42
	v_and_b32_e32 v21, 0xffff0000, v42
	v_mul_f32_e32 v25, v13, v13
	v_lshlrev_b32_e32 v22, 16, v43
	v_and_b32_e32 v23, 0xffff0000, v43
	v_pk_add_f32 v[14:15], v[18:19], v[14:15]
	v_pk_add_f32 v[18:19], v[8:9], v[20:21]
	v_cvt_pk_bf16_f32 v8, v12, v13
	v_cvt_pk_bf16_f32 v9, v14, v15
	v_fmac_f32_e32 v25, v12, v12
	v_pk_add_f32 v[16:17], v[10:11], v[22:23]
	v_cvt_pk_bf16_f32 v10, v18, v19
	v_fmac_f32_e32 v25, v14, v14
	v_cvt_pk_bf16_f32 v11, v16, v17
	global_store_dwordx4 v[44:45], v[8:11], off
	v_fmac_f32_e32 v25, v15, v15
	v_lshlrev_b32_e32 v12, 16, v34
	v_lshlrev_b32_e32 v8, 16, v32
	v_and_b32_e32 v9, 0xffff0000, v32
	v_and_b32_e32 v13, 0xffff0000, v34
	v_pk_add_f32 v[4:5], v[4:5], v[8:9]
	v_fmac_f32_e32 v25, v18, v18
	v_lshlrev_b32_e32 v10, 16, v33
	v_and_b32_e32 v11, 0xffff0000, v33
	v_pk_add_f32 v[22:23], v[0:1], v[12:13]
	v_mul_f32_e32 v0, v5, v5
	v_fmac_f32_e32 v25, v19, v19
	v_pk_add_f32 v[18:19], v[6:7], v[10:11]
	v_fmac_f32_e32 v0, v4, v4
	v_fmac_f32_e32 v0, v18, v18
	v_fmac_f32_e32 v0, v19, v19
	v_lshlrev_b32_e32 v14, 16, v35
	v_and_b32_e32 v15, 0xffff0000, v35
	v_fmac_f32_e32 v0, v22, v22
	v_pk_add_f32 v[20:21], v[2:3], v[14:15]
	v_fmac_f32_e32 v0, v23, v23
	v_fmac_f32_e32 v25, v16, v16
	v_fmac_f32_e32 v0, v20, v20
	v_fmac_f32_e32 v25, v17, v17
	v_fmac_f32_e32 v0, v21, v21
	v_add_f32_e32 v118, v125, v139
	v_add_f32_e32 v55, v55, v64
	v_add_f32_e32 v14, v25, v0
	v_cvt_pk_bf16_f32 v16, v4, v5
	ds_bpermute_b32 v1, v181, v118
	ds_bpermute_b32 v2, v181, v102
	ds_bpermute_b32 v4, v181, v86
	ds_bpermute_b32 v6, v181, v68
	ds_bpermute_b32 v8, v181, v54
	ds_bpermute_b32 v10, v181, v55
	ds_bpermute_b32 v12, v181, v24
	ds_bpermute_b32 v15, v181, v14
	s_waitcnt lgkmcnt(0)
	v_add_f32_e32 v0, v118, v1
	v_add_f32_e32 v2, v102, v2
	v_add_f32_e32 v4, v86, v4
	v_add_f32_e32 v6, v68, v6
	v_add_f32_e32 v8, v54, v8
	v_add_f32_e32 v10, v55, v10
	v_add_f32_e32 v12, v24, v12
	v_add_f32_e32 v14, v14, v15
	ds_bpermute_b32 v1, v182, v0
	ds_bpermute_b32 v3, v182, v2
	ds_bpermute_b32 v5, v182, v4
	ds_bpermute_b32 v7, v182, v6
	ds_bpermute_b32 v9, v182, v8
	ds_bpermute_b32 v11, v182, v10
	ds_bpermute_b32 v13, v182, v12
	ds_bpermute_b32 v15, v182, v14
	v_cvt_pk_bf16_f32 v17, v18, v19
	v_cvt_pk_bf16_f32 v18, v22, v23
	v_cvt_pk_bf16_f32 v19, v20, v21
	global_store_dwordx4 v[36:37], v[16:19], off offset:256
	s_and_saveexec_b64 s[40:41], s[4:5]
	s_cbranch_execz .LBB0_958
	s_waitcnt lgkmcnt(6)
	v_add_f32_e32 v2, v2, v3
	v_add_f32_e32 v0, v0, v1
	v_add_u32_e32 v1, s76, v183
	s_waitcnt lgkmcnt(2)
	v_add_f32_e32 v10, v10, v11
	v_add_f32_e32 v8, v8, v9
	v_add_f32_e32 v6, v6, v7
	v_add_f32_e32 v4, v4, v5
	ds_write2st64_b32 v1, v0, v2 offset1:1
	ds_write2st64_b32 v1, v4, v6 offset0:2 offset1:3
	v_add_u32_e32 v0, s76, v187
	s_waitcnt lgkmcnt(2)
	v_add_f32_e32 v14, v14, v15
	v_add_f32_e32 v12, v12, v13
	ds_write2st64_b32 v0, v8, v10 offset1:1
	ds_write2st64_b32 v0, v12, v14 offset0:2 offset1:3
